# GEMM K-loops: m0 write hoisted above the DMA address calc so the hazard s_nop is not needed (40 issue slots removed)
# speedup vs baseline: 1.0035x; 1.0035x over previous
; #define G8_STAGE(bufoff, gbase) do { _Pragma("unroll") for (int _i = 0; _i < 2; ++_i) \
;     __builtin_amdgcn_global_load_lds((const unsigned*)((const char*)(gbase) + voffA[_i]), (LAS unsigned*)(lds + (bufoff) + ldsw + _i * 8192), 16, 0, 0); } while (0)
; #define G8_LDA(dst, b, h) do { _Pragma("unroll") for (int m = 0; m < 4; ++m) _Pragma("unroll") for (int k = 0; k < 2; ++k) dst[m][k] = *(const LAS h16x8*)(lds + G8_SA(b, h) + aoff + m * 2048 + k * 1024); } while (0)
; #define G8_LDB(dst, b, h) do { _Pragma("unroll") for (int n = 0; n < 2; ++n) _Pragma("unroll") for (int k = 0; k < 2; ++k) dst[n][k] = *(const LAS h16x8*)(lds + G8_SB(b, h) + boff + n * 2048 + k * 1024); } while (0)
; #define G8_MMA(ai, bj, At, Bt_) do { __builtin_amdgcn_s_setprio(1); _Pragma("unroll") for (int m = 0; m < 4; ++m) _Pragma("unroll") for (int n = 0; n < 2; ++n) _Pragma("unroll") for (int k = 0; k < 2; ++k) \
;     acc[ai][bj][m][n] = __builtin_amdgcn_mfma_f32_16x16x32_f16(Bt_[n][k], At[m][k], acc[ai][bj][m][n], 0, 0, 0); __builtin_amdgcn_s_setprio(0); } while (0)
; #define G8_WAIT_V(n) asm volatile("s_waitcnt vmcnt(" #n ")" ::: "memory")
; #define G8_WAIT_L(n) asm volatile("s_waitcnt lgkmcnt(" #n ")" ::: "memory")
; #define G8_BAR __builtin_amdgcn_s_barrier()
; template <class Epi>
; __device__ __forceinline__ void gemm_phase(LAS unsigned char* lds, const h16* A, const h16* Bt, int K, const Order& S, const Epi& E) {
;     ...
;     for (int t = 0; t < nt; t += 2) {
;       const bool last = (t == nt - 2);
;       const char* a1 = cA + (size_t)(t + 1) * kstep;
;       const char* a2 = last ? nA : cA + (size_t)(t + 2) * kstep;
;       const char* b2 = last ? nB : cB + (size_t)(t + 2) * kstep;
;       const char* a3 = a2 + kstep;
;       const char* b3 = b2 + kstep;
;       if (Epi::MID_T >= 0 && t == Epi::MID_T) E.mid(acc, ui, wr, fr);
;       G8_LDB(B0, 0, 0); G8_SCHED; G8_LDA(At, 0, 0); G8_STAGE(G8_SA(1, 1), a1 + hstep);
;       G8_WAIT_L(8); G8_BAR; G8_WAIT_L(0); G8_MMA(0, 0, At, B0); G8_BAR; G8_SCHED;
;       G8_LDB(B1, 0, 1); G8_STAGE(G8_SB(0, 0), b2);
;       G8_BAR; G8_WAIT_L(0); G8_MMA(0, 1, At, B1); G8_BAR;
;       G8_LDA(At, 0, 1); G8_STAGE(G8_SA(0, 0), a2);
;       G8_BAR; G8_WAIT_L(0); G8_MMA(1, 0, At, B0); G8_BAR; G8_SCHED;
;       G8_STAGE(G8_SB(0, 1), b2 + hstep);
;       G8_WAIT_V(6); G8_BAR; G8_MMA(1, 1, At, B1); G8_BAR;
.LBB0_195:
	s_add_u32 s12, s10, 0xfffc0080
	s_addc_u32 s13, s11, -1
	s_cmp_eq_u32 s54, 12
	s_cselect_b32 s15, s19, s13
	s_cselect_b32 s14, s25, s12
	s_cselect_b32 s13, s17, s53
	s_cselect_b32 s12, s26, s27
	s_mov_b32 m0, s50
	v_lshl_add_u64 v[140:141], s[10:11], 0, v[136:137]
	ds_read_b128 v[202:205], v159
	ds_read_b128 v[206:209], v159 offset:1024
	ds_read_b128 v[210:213], v159 offset:2048
	ds_read_b128 v[214:217], v159 offset:3072
	ds_read_b128 v[218:221], v159 offset:4096
	ds_read_b128 v[222:225], v159 offset:5120
	ds_read_b128 v[226:229], v159 offset:6144
	ds_read_b128 v[230:233], v159 offset:7168
	global_load_lds_dwordx4 v[140:141], off
	s_mov_b32 m0, s51
	v_lshl_add_u64 v[140:141], s[10:11], 0, v[138:139]
	global_load_lds_dwordx4 v[140:141], off
	s_waitcnt lgkmcnt(8)
	s_barrier
	s_waitcnt lgkmcnt(0)
	v_mfma_f32_16x16x32_f16 v[126:129], v[152:155], v[202:205], v[126:129]
	v_mfma_f32_16x16x32_f16 v[122:125], v[182:185], v[202:205], v[122:125]
	v_mfma_f32_16x16x32_f16 v[110:113], v[152:155], v[210:213], v[110:113]
	v_mfma_f32_16x16x32_f16 v[106:109], v[182:185], v[210:213], v[106:109]
	v_mfma_f32_16x16x32_f16 v[94:97], v[152:155], v[218:221], v[94:97]
	v_mfma_f32_16x16x32_f16 v[90:93], v[182:185], v[218:221], v[90:93]
	v_mfma_f32_16x16x32_f16 v[78:81], v[152:155], v[226:229], v[78:81]
	v_mfma_f32_16x16x32_f16 v[74:77], v[182:185], v[226:229], v[74:77]
	v_mfma_f32_16x16x32_f16 v[126:129], v[178:181], v[206:209], v[126:129]
	v_mfma_f32_16x16x32_f16 v[122:125], v[186:189], v[206:209], v[122:125]
	v_mfma_f32_16x16x32_f16 v[110:113], v[178:181], v[214:217], v[110:113]
	v_mfma_f32_16x16x32_f16 v[106:109], v[186:189], v[214:217], v[106:109]
	v_mfma_f32_16x16x32_f16 v[94:97], v[178:181], v[222:225], v[94:97]
	v_mfma_f32_16x16x32_f16 v[90:93], v[186:189], v[222:225], v[90:93]
	v_mfma_f32_16x16x32_f16 v[78:81], v[178:181], v[230:233], v[78:81]
	v_mfma_f32_16x16x32_f16 v[74:77], v[186:189], v[230:233], v[74:77]
	s_barrier
	s_mov_b32 m0, s36
	v_lshl_add_u64 v[140:141], s[12:13], 0, v[132:133]
	ds_read_b128 v[234:237], v165
	ds_read_b128 v[238:241], v166
	ds_read_b128 v[242:245], v167
	ds_read_b128 v[246:249], v168
	global_load_lds_dwordx4 v[140:141], off
	s_mov_b32 m0, s37
	v_lshl_add_u64 v[156:157], s[12:13], 0, v[130:131]
	global_load_lds_dwordx4 v[156:157], off
	s_barrier
	s_waitcnt lgkmcnt(0)
	v_mfma_f32_16x16x32_f16 v[118:121], v[234:237], v[202:205], v[118:121]
	v_mfma_f32_16x16x32_f16 v[114:117], v[242:245], v[202:205], v[114:117]
	v_mfma_f32_16x16x32_f16 v[102:105], v[234:237], v[210:213], v[102:105]
	v_mfma_f32_16x16x32_f16 v[98:101], v[242:245], v[210:213], v[98:101]
	v_mfma_f32_16x16x32_f16 v[86:89], v[234:237], v[218:221], v[86:89]
	v_mfma_f32_16x16x32_f16 v[82:85], v[242:245], v[218:221], v[82:85]
	v_mfma_f32_16x16x32_f16 v[70:73], v[234:237], v[226:229], v[70:73]
	v_mfma_f32_16x16x32_f16 v[66:69], v[242:245], v[226:229], v[66:69]
	v_mfma_f32_16x16x32_f16 v[118:121], v[238:241], v[206:209], v[118:121]
	v_mfma_f32_16x16x32_f16 v[114:117], v[246:249], v[206:209], v[114:117]
	v_mfma_f32_16x16x32_f16 v[102:105], v[238:241], v[214:217], v[102:105]
	v_mfma_f32_16x16x32_f16 v[98:101], v[246:249], v[214:217], v[98:101]
	v_mfma_f32_16x16x32_f16 v[86:89], v[238:241], v[222:225], v[86:89]
	v_mfma_f32_16x16x32_f16 v[82:85], v[246:249], v[222:225], v[82:85]
	v_mfma_f32_16x16x32_f16 v[70:73], v[238:241], v[230:233], v[70:73]
	v_mfma_f32_16x16x32_f16 v[66:69], v[246:249], v[230:233], v[66:69]
	s_mov_b32 m0, s35
	v_lshl_add_u64 v[250:251], s[14:15], 0, v[132:133]
	s_barrier
	ds_read_b128 v[202:205], v159 offset:16384
	ds_read_b128 v[206:209], v159 offset:17408
	ds_read_b128 v[210:213], v159 offset:18432
	ds_read_b128 v[214:217], v159 offset:19456
	ds_read_b128 v[218:221], v159 offset:20480
	ds_read_b128 v[222:225], v159 offset:21504
	ds_read_b128 v[226:229], v159 offset:22528
	ds_read_b128 v[230:233], v159 offset:23552
	global_load_lds_dwordx4 v[250:251], off
	s_mov_b32 m0, s38
	v_lshl_add_u64 v[252:253], s[14:15], 0, v[130:131]
	global_load_lds_dwordx4 v[252:253], off
	s_waitcnt vmcnt(10)
	s_barrier
	s_waitcnt lgkmcnt(0)
	v_mfma_f32_16x16x32_f16 v[62:65], v[152:155], v[202:205], v[62:65]
	v_mfma_f32_16x16x32_f16 v[58:61], v[182:185], v[202:205], v[58:61]
	v_mfma_f32_16x16x32_f16 v[46:49], v[152:155], v[210:213], v[46:49]
	v_mfma_f32_16x16x32_f16 v[42:45], v[182:185], v[210:213], v[42:45]
	v_mfma_f32_16x16x32_f16 v[30:33], v[152:155], v[218:221], v[30:33]
	v_mfma_f32_16x16x32_f16 v[26:29], v[182:185], v[218:221], v[26:29]
	v_mfma_f32_16x16x32_f16 v[14:17], v[152:155], v[226:229], v[14:17]
	v_mfma_f32_16x16x32_f16 v[10:13], v[182:185], v[226:229], v[10:13]
	v_mfma_f32_16x16x32_f16 v[62:65], v[178:181], v[206:209], v[62:65]
	v_mfma_f32_16x16x32_f16 v[58:61], v[186:189], v[206:209], v[58:61]
	v_mfma_f32_16x16x32_f16 v[46:49], v[178:181], v[214:217], v[46:49]
	v_mfma_f32_16x16x32_f16 v[42:45], v[186:189], v[214:217], v[42:45]
	v_mfma_f32_16x16x32_f16 v[30:33], v[178:181], v[222:225], v[30:33]
	v_mfma_f32_16x16x32_f16 v[26:29], v[186:189], v[222:225], v[26:29]
	v_mfma_f32_16x16x32_f16 v[14:17], v[178:181], v[230:233], v[14:17]
	v_mfma_f32_16x16x32_f16 v[10:13], v[186:189], v[230:233], v[10:13]
	s_barrier
	s_add_u32 s56, s12, 0x40000
	s_addc_u32 s57, s13, 0
	s_mov_b32 m0, s39
	v_lshl_add_u64 v[152:153], s[56:57], 0, v[132:133]
	global_load_lds_dwordx4 v[152:153], off
	s_mov_b32 m0, s40
	v_lshl_add_u64 v[152:153], s[56:57], 0, v[130:131]
	global_load_lds_dwordx4 v[152:153], off
	ds_read_b128 v[152:155], v169
	ds_read_b128 v[178:181], v170
	ds_read_b128 v[182:185], v171
	ds_read_b128 v[186:189], v172
	s_waitcnt vmcnt(6)
	s_barrier
; #define G8_STAGE(bufoff, gbase) do { _Pragma("unroll") for (int _i = 0; _i < 2; ++_i) \
;     __builtin_amdgcn_global_load_lds((const unsigned*)((const char*)(gbase) + voffA[_i]), (LAS unsigned*)(lds + (bufoff) + ldsw + _i * 8192), 16, 0, 0); } while (0)
; #define G8_LDA(dst, b, h) do { _Pragma("unroll") for (int m = 0; m < 4; ++m) _Pragma("unroll") for (int k = 0; k < 2; ++k) dst[m][k] = *(const LAS h16x8*)(lds + G8_SA(b, h) + aoff + m * 2048 + k * 1024); } while (0)
; #define G8_LDB(dst, b, h) do { _Pragma("unroll") for (int n = 0; n < 2; ++n) _Pragma("unroll") for (int k = 0; k < 2; ++k) dst[n][k] = *(const LAS h16x8*)(lds + G8_SB(b, h) + boff + n * 2048 + k * 1024); } while (0)
; #define G8_MMA(ai, bj, At, Bt_) do { __builtin_amdgcn_s_setprio(1); _Pragma("unroll") for (int m = 0; m < 4; ++m) _Pragma("unroll") for (int n = 0; n < 2; ++n) _Pragma("unroll") for (int k = 0; k < 2; ++k) \
;     acc[ai][bj][m][n] = __builtin_amdgcn_mfma_f32_16x16x32_f16(Bt_[n][k], At[m][k], acc[ai][bj][m][n], 0, 0, 0); __builtin_amdgcn_s_setprio(0); } while (0)
; #define G8_WAIT_V(n) asm volatile("s_waitcnt vmcnt(" #n ")" ::: "memory")
; #define G8_WAIT_L(n) asm volatile("s_waitcnt lgkmcnt(" #n ")" ::: "memory")
; #define G8_BAR __builtin_amdgcn_s_barrier()
; #define G8_SCHED __builtin_amdgcn_sched_barrier(0)
; template <class Epi>
; __device__ __forceinline__ void gemm_phase(LAS unsigned char* lds, const h16* A, const h16* Bt, int K, const Order& S, const Epi& E) {
;     ...
;       G8_LDA(At, 0, 1); G8_STAGE(G8_SA(0, 0), a2);
;       G8_BAR; G8_WAIT_L(0); G8_MMA(1, 0, At, B0); G8_BAR; G8_SCHED;
;       G8_STAGE(G8_SB(0, 1), b2 + hstep);
;       G8_WAIT_V(6); G8_BAR; G8_MMA(1, 1, At, B1); G8_BAR;
;       G8_LDB(B0, 1, 0); G8_SCHED; G8_LDA(At, 1, 0); G8_STAGE(G8_SA(0, 1), a2 + hstep);
;       G8_WAIT_L(8); G8_BAR; G8_WAIT_L(0); G8_MMA(0, 0, At, B0); G8_BAR; G8_SCHED;
;       G8_LDB(B1, 1, 1); G8_STAGE(G8_SB(1, 0), b3);
;       G8_BAR; G8_WAIT_L(0); G8_MMA(0, 1, At, B1); G8_BAR;
;       G8_LDA(At, 1, 1); G8_STAGE(G8_SA(1, 0), a3);
;       G8_BAR; G8_WAIT_L(0); G8_MMA(1, 0, At, B0); G8_BAR; G8_SCHED;
	v_mfma_f32_16x16x32_f16 v[54:57], v[234:237], v[202:205], v[54:57]
	v_mfma_f32_16x16x32_f16 v[50:53], v[242:245], v[202:205], v[50:53]
	v_mfma_f32_16x16x32_f16 v[38:41], v[234:237], v[210:213], v[38:41]
	v_mfma_f32_16x16x32_f16 v[34:37], v[242:245], v[210:213], v[34:37]
	v_mfma_f32_16x16x32_f16 v[22:25], v[234:237], v[218:221], v[22:25]
	v_mfma_f32_16x16x32_f16 v[18:21], v[242:245], v[218:221], v[18:21]
	v_mfma_f32_16x16x32_f16 v[6:9], v[234:237], v[226:229], v[6:9]
	v_mfma_f32_16x16x32_f16 v[2:5], v[242:245], v[226:229], v[2:5]
	v_mfma_f32_16x16x32_f16 v[54:57], v[238:241], v[206:209], v[54:57]
	v_mfma_f32_16x16x32_f16 v[50:53], v[246:249], v[206:209], v[50:53]
	v_mfma_f32_16x16x32_f16 v[38:41], v[238:241], v[214:217], v[38:41]
	v_mfma_f32_16x16x32_f16 v[34:37], v[246:249], v[214:217], v[34:37]
	v_mfma_f32_16x16x32_f16 v[22:25], v[238:241], v[222:225], v[22:25]
	v_mfma_f32_16x16x32_f16 v[18:21], v[246:249], v[222:225], v[18:21]
	v_mfma_f32_16x16x32_f16 v[6:9], v[238:241], v[230:233], v[6:9]
	v_mfma_f32_16x16x32_f16 v[2:5], v[246:249], v[230:233], v[2:5]
	s_barrier
	s_add_u32 s14, s14, 0x40000
	s_addc_u32 s15, s15, 0
	s_mov_b32 m0, s41
	v_lshl_add_u64 v[234:235], s[14:15], 0, v[132:133]
	ds_read_b128 v[202:205], v159 offset:32768
	ds_read_b128 v[206:209], v159 offset:33792
	ds_read_b128 v[210:213], v159 offset:34816
	ds_read_b128 v[214:217], v159 offset:35840
	ds_read_b128 v[218:221], v159 offset:36864
	ds_read_b128 v[222:225], v159 offset:37888
	ds_read_b128 v[226:229], v159 offset:38912
	ds_read_b128 v[230:233], v159 offset:39936
	global_load_lds_dwordx4 v[234:235], off
	s_mov_b32 m0, s42
	v_lshl_add_u64 v[234:235], s[14:15], 0, v[130:131]
	global_load_lds_dwordx4 v[234:235], off
	s_waitcnt lgkmcnt(8)
	s_barrier
	s_waitcnt lgkmcnt(0)
	v_mfma_f32_16x16x32_f16 v[126:129], v[152:155], v[202:205], v[126:129]
	v_mfma_f32_16x16x32_f16 v[122:125], v[182:185], v[202:205], v[122:125]
	v_mfma_f32_16x16x32_f16 v[110:113], v[152:155], v[210:213], v[110:113]
	v_mfma_f32_16x16x32_f16 v[106:109], v[182:185], v[210:213], v[106:109]
	v_mfma_f32_16x16x32_f16 v[94:97], v[152:155], v[218:221], v[94:97]
	v_mfma_f32_16x16x32_f16 v[90:93], v[182:185], v[218:221], v[90:93]
	v_mfma_f32_16x16x32_f16 v[78:81], v[152:155], v[226:229], v[78:81]
	v_mfma_f32_16x16x32_f16 v[74:77], v[182:185], v[226:229], v[74:77]
	v_mfma_f32_16x16x32_f16 v[126:129], v[178:181], v[206:209], v[126:129]
	v_mfma_f32_16x16x32_f16 v[122:125], v[186:189], v[206:209], v[122:125]
	v_mfma_f32_16x16x32_f16 v[110:113], v[178:181], v[214:217], v[110:113]
	v_mfma_f32_16x16x32_f16 v[106:109], v[186:189], v[214:217], v[106:109]
	v_mfma_f32_16x16x32_f16 v[94:97], v[178:181], v[222:225], v[94:97]
	v_mfma_f32_16x16x32_f16 v[90:93], v[186:189], v[222:225], v[90:93]
	v_mfma_f32_16x16x32_f16 v[78:81], v[178:181], v[230:233], v[78:81]
	v_mfma_f32_16x16x32_f16 v[74:77], v[186:189], v[230:233], v[74:77]
	s_barrier
	s_mov_b32 m0, s44
	v_lshl_add_u64 v[140:141], v[140:141], 0, s[94:95]
	ds_read_b128 v[234:237], v173
	ds_read_b128 v[238:241], v174
	ds_read_b128 v[242:245], v175
	ds_read_b128 v[246:249], v176
	global_load_lds_dwordx4 v[140:141], off
	s_mov_b32 m0, s45
	v_lshl_add_u64 v[140:141], v[156:157], 0, s[94:95]
	global_load_lds_dwordx4 v[140:141], off
	s_barrier
	s_waitcnt lgkmcnt(0)
	v_mfma_f32_16x16x32_f16 v[118:121], v[234:237], v[202:205], v[118:121]
	v_mfma_f32_16x16x32_f16 v[114:117], v[242:245], v[202:205], v[114:117]
	v_mfma_f32_16x16x32_f16 v[102:105], v[234:237], v[210:213], v[102:105]
	v_mfma_f32_16x16x32_f16 v[98:101], v[242:245], v[210:213], v[98:101]
	v_mfma_f32_16x16x32_f16 v[86:89], v[234:237], v[218:221], v[86:89]
	v_mfma_f32_16x16x32_f16 v[82:85], v[242:245], v[218:221], v[82:85]
	v_mfma_f32_16x16x32_f16 v[70:73], v[234:237], v[226:229], v[70:73]
	v_mfma_f32_16x16x32_f16 v[66:69], v[242:245], v[226:229], v[66:69]
	v_mfma_f32_16x16x32_f16 v[118:121], v[238:241], v[206:209], v[118:121]
	v_mfma_f32_16x16x32_f16 v[114:117], v[246:249], v[206:209], v[114:117]
	v_mfma_f32_16x16x32_f16 v[102:105], v[238:241], v[214:217], v[102:105]
	v_mfma_f32_16x16x32_f16 v[98:101], v[246:249], v[214:217], v[98:101]
	v_mfma_f32_16x16x32_f16 v[86:89], v[238:241], v[222:225], v[86:89]
	v_mfma_f32_16x16x32_f16 v[82:85], v[246:249], v[222:225], v[82:85]
	v_mfma_f32_16x16x32_f16 v[70:73], v[238:241], v[230:233], v[70:73]
	v_mfma_f32_16x16x32_f16 v[66:69], v[246:249], v[230:233], v[66:69]
	s_mov_b32 m0, s46
	v_lshl_add_u64 v[140:141], v[250:251], 0, s[94:95]
	s_barrier
; #define G8_STAGE(bufoff, gbase) do { _Pragma("unroll") for (int _i = 0; _i < 2; ++_i) \
;     __builtin_amdgcn_global_load_lds((const unsigned*)((const char*)(gbase) + voffA[_i]), (LAS unsigned*)(lds + (bufoff) + ldsw + _i * 8192), 16, 0, 0); } while (0)
; #define G8_LDA(dst, b, h) do { _Pragma("unroll") for (int m = 0; m < 4; ++m) _Pragma("unroll") for (int k = 0; k < 2; ++k) dst[m][k] = *(const LAS h16x8*)(lds + G8_SA(b, h) + aoff + m * 2048 + k * 1024); } while (0)
; #define G8_LDB(dst, b, h) do { _Pragma("unroll") for (int n = 0; n < 2; ++n) _Pragma("unroll") for (int k = 0; k < 2; ++k) dst[n][k] = *(const LAS h16x8*)(lds + G8_SB(b, h) + boff + n * 2048 + k * 1024); } while (0)
; #define G8_MMA(ai, bj, At, Bt_) do { __builtin_amdgcn_s_setprio(1); _Pragma("unroll") for (int m = 0; m < 4; ++m) _Pragma("unroll") for (int n = 0; n < 2; ++n) _Pragma("unroll") for (int k = 0; k < 2; ++k) \
;     acc[ai][bj][m][n] = __builtin_amdgcn_mfma_f32_16x16x32_f16(Bt_[n][k], At[m][k], acc[ai][bj][m][n], 0, 0, 0); __builtin_amdgcn_s_setprio(0); } while (0)
; #define G8_WAIT_V(n) asm volatile("s_waitcnt vmcnt(" #n ")" ::: "memory")
; #define G8_WAIT_L(n) asm volatile("s_waitcnt lgkmcnt(" #n ")" ::: "memory")
; #define G8_BAR __builtin_amdgcn_s_barrier()
; #define G8_SCHED __builtin_amdgcn_sched_barrier(0)
; template <class Epi>
; __device__ __forceinline__ void gemm_phase(LAS unsigned char* lds, const h16* A, const h16* Bt, int K, const Order& S, const Epi& E) {
;     ...
;       G8_LDB(B0, 1, 0); G8_SCHED; G8_LDA(At, 1, 0); G8_STAGE(G8_SA(0, 1), a2 + hstep);
;       G8_WAIT_L(8); G8_BAR; G8_WAIT_L(0); G8_MMA(0, 0, At, B0); G8_BAR; G8_SCHED;
;       G8_LDB(B1, 1, 1); G8_STAGE(G8_SB(1, 0), b3);
;       G8_BAR; G8_WAIT_L(0); G8_MMA(0, 1, At, B1); G8_BAR;
;       G8_LDA(At, 1, 1); G8_STAGE(G8_SA(1, 0), a3);
;       G8_BAR; G8_WAIT_L(0); G8_MMA(1, 0, At, B0); G8_BAR; G8_SCHED;
;       G8_STAGE(G8_SB(1, 1), b3 + hstep);
;       G8_WAIT_V(6); G8_BAR; G8_MMA(1, 1, At, B1); G8_BAR;
;     }
;   __device__ __forceinline__ void operator()(const f32x4 (&acc)[2][2][4][2], const g8::Unit& u, int ui, int wr, int wc, int fr, int fq) const {
;     const int hs = u.pn * 4 + wc;
;     int gi = -1;
;     if (hs < 4) gi = 0; else if (hs < 6) gi = 1; else if (hs >= 16 && hs < 20) gi = 2; else if (hs == 22) gi = 4; else if (hs == 24) gi = 5;
;     const bool gate = (hs == 26);
	ds_read_b128 v[202:205], v159 offset:49152
	ds_read_b128 v[206:209], v159 offset:50176
	ds_read_b128 v[210:213], v159 offset:51200
	ds_read_b128 v[214:217], v159 offset:52224
	ds_read_b128 v[218:221], v159 offset:53248
	ds_read_b128 v[222:225], v159 offset:54272
	ds_read_b128 v[226:229], v159 offset:55296
	ds_read_b128 v[230:233], v159 offset:56320
	global_load_lds_dwordx4 v[140:141], off
	s_mov_b32 m0, s47
	v_lshl_add_u64 v[140:141], v[252:253], 0, s[94:95]
	global_load_lds_dwordx4 v[140:141], off
	s_waitcnt vmcnt(10)
	s_barrier
	s_waitcnt lgkmcnt(0)
	v_mfma_f32_16x16x32_f16 v[62:65], v[152:155], v[202:205], v[62:65]
	v_mfma_f32_16x16x32_f16 v[58:61], v[182:185], v[202:205], v[58:61]
	v_mfma_f32_16x16x32_f16 v[46:49], v[152:155], v[210:213], v[46:49]
	v_mfma_f32_16x16x32_f16 v[42:45], v[182:185], v[210:213], v[42:45]
	v_mfma_f32_16x16x32_f16 v[30:33], v[152:155], v[218:221], v[30:33]
	v_mfma_f32_16x16x32_f16 v[26:29], v[182:185], v[218:221], v[26:29]
	v_mfma_f32_16x16x32_f16 v[14:17], v[152:155], v[226:229], v[14:17]
	v_mfma_f32_16x16x32_f16 v[10:13], v[182:185], v[226:229], v[10:13]
	v_mfma_f32_16x16x32_f16 v[62:65], v[178:181], v[206:209], v[62:65]
	v_mfma_f32_16x16x32_f16 v[58:61], v[186:189], v[206:209], v[58:61]
	v_mfma_f32_16x16x32_f16 v[46:49], v[178:181], v[214:217], v[46:49]
	v_mfma_f32_16x16x32_f16 v[42:45], v[186:189], v[214:217], v[42:45]
	v_mfma_f32_16x16x32_f16 v[30:33], v[178:181], v[222:225], v[30:33]
	v_mfma_f32_16x16x32_f16 v[26:29], v[186:189], v[222:225], v[26:29]
	v_mfma_f32_16x16x32_f16 v[14:17], v[178:181], v[230:233], v[14:17]
	v_mfma_f32_16x16x32_f16 v[10:13], v[186:189], v[230:233], v[10:13]
	s_barrier
	s_add_u32 s12, s12, 0x40080
	s_addc_u32 s13, s13, 0
	s_mov_b32 m0, s48
	v_lshl_add_u64 v[140:141], s[12:13], 0, v[132:133]
	global_load_lds_dwordx4 v[140:141], off
	s_mov_b32 m0, s49
	v_lshl_add_u64 v[140:141], s[12:13], 0, v[130:131]
	global_load_lds_dwordx4 v[140:141], off
	ds_read_b128 v[152:155], v161
	ds_read_b128 v[178:181], v162
	ds_read_b128 v[182:185], v163
	ds_read_b128 v[186:189], v164
	s_waitcnt vmcnt(6)
	s_barrier
	v_mfma_f32_16x16x32_f16 v[54:57], v[234:237], v[202:205], v[54:57]
	v_mfma_f32_16x16x32_f16 v[50:53], v[242:245], v[202:205], v[50:53]
	v_mfma_f32_16x16x32_f16 v[38:41], v[234:237], v[210:213], v[38:41]
	v_mfma_f32_16x16x32_f16 v[34:37], v[242:245], v[210:213], v[34:37]
	v_mfma_f32_16x16x32_f16 v[22:25], v[234:237], v[218:221], v[22:25]
	v_mfma_f32_16x16x32_f16 v[18:21], v[242:245], v[218:221], v[18:21]
	v_mfma_f32_16x16x32_f16 v[6:9], v[234:237], v[226:229], v[6:9]
	v_mfma_f32_16x16x32_f16 v[2:5], v[242:245], v[226:229], v[2:5]
	v_mfma_f32_16x16x32_f16 v[54:57], v[238:241], v[206:209], v[54:57]
	v_mfma_f32_16x16x32_f16 v[50:53], v[246:249], v[206:209], v[50:53]
	v_mfma_f32_16x16x32_f16 v[38:41], v[238:241], v[214:217], v[38:41]
	v_mfma_f32_16x16x32_f16 v[34:37], v[246:249], v[214:217], v[34:37]
	v_mfma_f32_16x16x32_f16 v[22:25], v[238:241], v[222:225], v[22:25]
	v_mfma_f32_16x16x32_f16 v[18:21], v[246:249], v[222:225], v[18:21]
	v_mfma_f32_16x16x32_f16 v[6:9], v[238:241], v[230:233], v[6:9]
	v_mfma_f32_16x16x32_f16 v[2:5], v[246:249], v[230:233], v[2:5]
	s_add_i32 s54, s54, 2
	s_add_u32 s10, s10, 0x100
	s_addc_u32 s11, s11, 0
	s_add_u32 s27, s27, 0x100
	s_addc_u32 s53, s53, 0
	s_cmp_gt_u32 s54, 13
	s_barrier
	s_cbranch_scc0 .LBB0_195
	s_waitcnt lgkmcnt(0)
	s_lshl_b32 s10, s24, 2
	s_or_b32 s19, s10, s43
	s_cmp_lt_i32 s19, 4
	s_cbranch_scc1 .LBB0_203
	s_cmp_lt_u32 s19, 6
	s_cbranch_scc1 .LBB0_204
	s_cmp_eq_u32 s24, 4
	s_cbranch_scc1 .LBB0_205
	s_cmp_lt_i32 s19, 24
	s_cbranch_scc1 .LBB0_206
	s_cmp_eq_u32 s19, 24
	s_mov_b64 s[10:11], -1
	s_cbranch_scc0 .LBB0_202
	s_mov_b64 s[10:11], 0

; #define G8_STAGE(bufoff, gbase) do { _Pragma("unroll") for (int _i = 0; _i < 2; ++_i) \
;     __builtin_amdgcn_global_load_lds((const unsigned*)((const char*)(gbase) + voffA[_i]), (LAS unsigned*)(lds + (bufoff) + ldsw + _i * 8192), 16, 0, 0); } while (0)
; #define G8_LDA(dst, b, h) do { _Pragma("unroll") for (int m = 0; m < 4; ++m) _Pragma("unroll") for (int k = 0; k < 2; ++k) dst[m][k] = *(const LAS h16x8*)(lds + G8_SA(b, h) + aoff + m * 2048 + k * 1024); } while (0)
; #define G8_LDB(dst, b, h) do { _Pragma("unroll") for (int n = 0; n < 2; ++n) _Pragma("unroll") for (int k = 0; k < 2; ++k) dst[n][k] = *(const LAS h16x8*)(lds + G8_SB(b, h) + boff + n * 2048 + k * 1024); } while (0)
; #define G8_MMA(ai, bj, At, Bt_) do { __builtin_amdgcn_s_setprio(1); _Pragma("unroll") for (int m = 0; m < 4; ++m) _Pragma("unroll") for (int n = 0; n < 2; ++n) _Pragma("unroll") for (int k = 0; k < 2; ++k) \
;     acc[ai][bj][m][n] = __builtin_amdgcn_mfma_f32_16x16x32_f16(Bt_[n][k], At[m][k], acc[ai][bj][m][n], 0, 0, 0); __builtin_amdgcn_s_setprio(0); } while (0)
; #define G8_WAIT_V(n) asm volatile("s_waitcnt vmcnt(" #n ")" ::: "memory")
; #define G8_WAIT_L(n) asm volatile("s_waitcnt lgkmcnt(" #n ")" ::: "memory")
; #define G8_BAR __builtin_amdgcn_s_barrier()
; template <class Epi>
; __device__ __forceinline__ void gemm_phase(LAS unsigned char* lds, const h16* A, const h16* Bt, int K, const Order& S, const Epi& E) {
;     ...
;     for (int t = 0; t < nt; t += 2) {
;       const bool last = (t == nt - 2);
;       const char* a1 = cA + (size_t)(t + 1) * kstep;
;       const char* a2 = last ? nA : cA + (size_t)(t + 2) * kstep;
;       const char* b2 = last ? nB : cB + (size_t)(t + 2) * kstep;
;       const char* a3 = a2 + kstep;
;       const char* b3 = b2 + kstep;
;       if (Epi::MID_T >= 0 && t == Epi::MID_T) E.mid(acc, ui, wr, fr);
;       G8_LDB(B0, 0, 0); G8_SCHED; G8_LDA(At, 0, 0); G8_STAGE(G8_SA(1, 1), a1 + hstep);
;       G8_WAIT_L(8); G8_BAR; G8_WAIT_L(0); G8_MMA(0, 0, At, B0); G8_BAR; G8_SCHED;
;       G8_LDB(B1, 0, 1); G8_STAGE(G8_SB(0, 0), b2);
;       G8_BAR; G8_WAIT_L(0); G8_MMA(0, 1, At, B1); G8_BAR;
;       G8_LDA(At, 0, 1); G8_STAGE(G8_SA(0, 0), a2);
;       G8_BAR; G8_WAIT_L(0); G8_MMA(1, 0, At, B0); G8_BAR; G8_SCHED;
;       G8_STAGE(G8_SB(0, 1), b2 + hstep);
;       G8_WAIT_V(6); G8_BAR; G8_MMA(1, 1, At, B1); G8_BAR;
.LBB0_2284:
	v_or_b32_e32 v34, 0x10000, v171
	v_add_u32_e32 v46, 0x10400, v171
	v_add_u32_e32 v50, 0x10800, v171
	v_add_u32_e32 v160, 0x10c00, v171
	ds_read_b128 v[34:37], v34
	ds_read_b128 v[46:49], v46
	ds_read_b128 v[50:53], v50
	ds_read_b128 v[160:163], v160
	s_add_u32 s26, s24, 0xfffe0080
	s_addc_u32 s27, s25, -1
	s_cmp_eq_u32 s55, 4
	s_cselect_b32 s29, s3, s27
	s_cselect_b32 s28, s17, s26
	s_cselect_b32 s27, s15, s54
	s_cselect_b32 s26, s23, s53
	v_lshl_add_u64 v[168:169], s[24:25], 0, v[156:157]
	s_add_i32 m0, s37, 0xc000
	ds_read_b128 v[164:167], v170
	ds_read_b128 v[174:177], v170 offset:1024
	ds_read_b128 v[178:181], v170 offset:2048
	ds_read_b128 v[182:185], v170 offset:3072
	ds_read_b128 v[186:189], v170 offset:4096
	ds_read_b128 v[202:205], v170 offset:5120
	ds_read_b128 v[206:209], v170 offset:6144
	ds_read_b128 v[210:213], v170 offset:7168
	global_load_lds_dwordx4 v[168:169], off
	s_add_i32 m0, s37, 0xe000
	v_lshl_add_u64 v[168:169], s[24:25], 0, v[158:159]
	global_load_lds_dwordx4 v[168:169], off
	s_waitcnt lgkmcnt(8)
	s_barrier
	s_waitcnt lgkmcnt(0)
	v_mfma_f32_16x16x32_f16 v[62:65], v[34:37], v[164:167], v[62:65]
	v_mfma_f32_16x16x32_f16 v[138:141], v[50:53], v[164:167], v[138:141]
	v_mfma_f32_16x16x32_f16 v[122:125], v[34:37], v[178:181], v[122:125]
	v_mfma_f32_16x16x32_f16 v[126:129], v[50:53], v[178:181], v[126:129]
	v_mfma_f32_16x16x32_f16 v[106:109], v[34:37], v[186:189], v[106:109]
	v_mfma_f32_16x16x32_f16 v[110:113], v[50:53], v[186:189], v[110:113]
	v_mfma_f32_16x16x32_f16 v[90:93], v[34:37], v[206:209], v[90:93]
	v_mfma_f32_16x16x32_f16 v[94:97], v[50:53], v[206:209], v[94:97]
	v_mfma_f32_16x16x32_f16 v[62:65], v[46:49], v[174:177], v[62:65]
	v_mfma_f32_16x16x32_f16 v[138:141], v[160:163], v[174:177], v[138:141]
	v_mfma_f32_16x16x32_f16 v[122:125], v[46:49], v[182:185], v[122:125]
	v_mfma_f32_16x16x32_f16 v[126:129], v[160:163], v[182:185], v[126:129]
	v_mfma_f32_16x16x32_f16 v[106:109], v[46:49], v[202:205], v[106:109]
	v_mfma_f32_16x16x32_f16 v[110:113], v[160:163], v[202:205], v[110:113]
	v_mfma_f32_16x16x32_f16 v[90:93], v[46:49], v[210:213], v[90:93]
	v_mfma_f32_16x16x32_f16 v[94:97], v[160:163], v[210:213], v[94:97]
	s_barrier
	v_or_b32_e32 v168, 0x14000, v171
	v_add_u32_e32 v169, 0x14400, v171
	ds_read_b128 v[214:217], v168
	ds_read_b128 v[218:221], v169
	v_add_u32_e32 v168, 0x14800, v171
	v_add_u32_e32 v169, 0x14c00, v171
	s_mov_b32 m0, s38
	ds_read_b128 v[222:225], v168
	ds_read_b128 v[226:229], v169
	v_lshl_add_u64 v[168:169], s[26:27], 0, v[0:1]
	global_load_lds_dwordx4 v[168:169], off
	s_mov_b32 m0, s39
	v_lshl_add_u64 v[230:231], s[26:27], 0, v[152:153]
	global_load_lds_dwordx4 v[230:231], off
	s_barrier
	s_waitcnt lgkmcnt(0)
	v_mfma_f32_16x16x32_f16 v[130:133], v[214:217], v[164:167], v[130:133]
	v_mfma_f32_16x16x32_f16 v[134:137], v[222:225], v[164:167], v[134:137]
	v_mfma_f32_16x16x32_f16 v[114:117], v[214:217], v[178:181], v[114:117]
	v_mfma_f32_16x16x32_f16 v[118:121], v[222:225], v[178:181], v[118:121]
	v_mfma_f32_16x16x32_f16 v[98:101], v[214:217], v[186:189], v[98:101]
	v_mfma_f32_16x16x32_f16 v[102:105], v[222:225], v[186:189], v[102:105]
	v_mfma_f32_16x16x32_f16 v[82:85], v[214:217], v[206:209], v[82:85]
	v_mfma_f32_16x16x32_f16 v[86:89], v[222:225], v[206:209], v[86:89]
	v_mfma_f32_16x16x32_f16 v[130:133], v[218:221], v[174:177], v[130:133]
	v_mfma_f32_16x16x32_f16 v[134:137], v[226:229], v[174:177], v[134:137]
	v_mfma_f32_16x16x32_f16 v[114:117], v[218:221], v[182:185], v[114:117]
	v_mfma_f32_16x16x32_f16 v[118:121], v[226:229], v[182:185], v[118:121]
	v_mfma_f32_16x16x32_f16 v[98:101], v[218:221], v[202:205], v[98:101]
	v_mfma_f32_16x16x32_f16 v[102:105], v[226:229], v[202:205], v[102:105]
	v_mfma_f32_16x16x32_f16 v[82:85], v[218:221], v[210:213], v[82:85]
	v_mfma_f32_16x16x32_f16 v[86:89], v[226:229], v[210:213], v[86:89]
	s_mov_b32 m0, s37
	v_lshl_add_u64 v[232:233], s[28:29], 0, v[0:1]
	s_barrier
	ds_read_b128 v[164:167], v170 offset:16384
	ds_read_b128 v[174:177], v170 offset:17408
	ds_read_b128 v[178:181], v170 offset:18432
	ds_read_b128 v[182:185], v170 offset:19456
	ds_read_b128 v[186:189], v170 offset:20480
	ds_read_b128 v[202:205], v170 offset:21504
	ds_read_b128 v[206:209], v170 offset:22528
	ds_read_b128 v[210:213], v170 offset:23552
	global_load_lds_dwordx4 v[232:233], off
	s_mov_b32 m0, s40
	v_lshl_add_u64 v[234:235], s[28:29], 0, v[152:153]
	global_load_lds_dwordx4 v[234:235], off
	s_barrier
	s_waitcnt lgkmcnt(0)
	v_mfma_f32_16x16x32_f16 v[74:77], v[34:37], v[164:167], v[74:77]
	v_mfma_f32_16x16x32_f16 v[78:81], v[50:53], v[164:167], v[78:81]
	v_mfma_f32_16x16x32_f16 v[54:57], v[34:37], v[178:181], v[54:57]
	v_mfma_f32_16x16x32_f16 v[58:61], v[50:53], v[178:181], v[58:61]
	v_mfma_f32_16x16x32_f16 v[26:29], v[34:37], v[186:189], v[26:29]
	v_mfma_f32_16x16x32_f16 v[30:33], v[50:53], v[186:189], v[30:33]
	v_mfma_f32_16x16x32_f16 v[10:13], v[34:37], v[206:209], v[10:13]
	v_mfma_f32_16x16x32_f16 v[14:17], v[50:53], v[206:209], v[14:17]
	v_mfma_f32_16x16x32_f16 v[74:77], v[46:49], v[174:177], v[74:77]
	v_mfma_f32_16x16x32_f16 v[78:81], v[160:163], v[174:177], v[78:81]
	v_mfma_f32_16x16x32_f16 v[54:57], v[46:49], v[182:185], v[54:57]
	v_mfma_f32_16x16x32_f16 v[58:61], v[160:163], v[182:185], v[58:61]
	v_mfma_f32_16x16x32_f16 v[26:29], v[46:49], v[202:205], v[26:29]
	v_mfma_f32_16x16x32_f16 v[30:33], v[160:163], v[202:205], v[30:33]
	v_mfma_f32_16x16x32_f16 v[10:13], v[46:49], v[210:213], v[10:13]
	v_mfma_f32_16x16x32_f16 v[14:17], v[160:163], v[210:213], v[14:17]
	s_barrier
; #define G8_STAGE(bufoff, gbase) do { _Pragma("unroll") for (int _i = 0; _i < 2; ++_i) \
;     __builtin_amdgcn_global_load_lds((const unsigned*)((const char*)(gbase) + voffA[_i]), (LAS unsigned*)(lds + (bufoff) + ldsw + _i * 8192), 16, 0, 0); } while (0)
; #define G8_LDA(dst, b, h) do { _Pragma("unroll") for (int m = 0; m < 4; ++m) _Pragma("unroll") for (int k = 0; k < 2; ++k) dst[m][k] = *(const LAS h16x8*)(lds + G8_SA(b, h) + aoff + m * 2048 + k * 1024); } while (0)
; #define G8_LDB(dst, b, h) do { _Pragma("unroll") for (int n = 0; n < 2; ++n) _Pragma("unroll") for (int k = 0; k < 2; ++k) dst[n][k] = *(const LAS h16x8*)(lds + G8_SB(b, h) + boff + n * 2048 + k * 1024); } while (0)
; #define G8_MMA(ai, bj, At, Bt_) do { __builtin_amdgcn_s_setprio(1); _Pragma("unroll") for (int m = 0; m < 4; ++m) _Pragma("unroll") for (int n = 0; n < 2; ++n) _Pragma("unroll") for (int k = 0; k < 2; ++k) \
;     acc[ai][bj][m][n] = __builtin_amdgcn_mfma_f32_16x16x32_f16(Bt_[n][k], At[m][k], acc[ai][bj][m][n], 0, 0, 0); __builtin_amdgcn_s_setprio(0); } while (0)
; #define G8_WAIT_V(n) asm volatile("s_waitcnt vmcnt(" #n ")" ::: "memory")
; #define G8_WAIT_L(n) asm volatile("s_waitcnt lgkmcnt(" #n ")" ::: "memory")
; #define G8_BAR __builtin_amdgcn_s_barrier()
; #define G8_SCHED __builtin_amdgcn_sched_barrier(0)
; template <class Epi>
; __device__ __forceinline__ void gemm_phase(LAS unsigned char* lds, const h16* A, const h16* Bt, int K, const Order& S, const Epi& E) {
;     ...
;       G8_LDA(At, 0, 1); G8_STAGE(G8_SA(0, 0), a2);
;       G8_BAR; G8_WAIT_L(0); G8_MMA(1, 0, At, B0); G8_BAR; G8_SCHED;
;       G8_STAGE(G8_SB(0, 1), b2 + hstep);
;       G8_WAIT_V(6); G8_BAR; G8_MMA(1, 1, At, B1); G8_BAR;
;       G8_LDB(B0, 1, 0); G8_SCHED; G8_LDA(At, 1, 0); G8_STAGE(G8_SA(0, 1), a2 + hstep);
;       G8_WAIT_L(8); G8_BAR; G8_WAIT_L(0); G8_MMA(0, 0, At, B0); G8_BAR; G8_SCHED;
;       G8_LDB(B1, 1, 1); G8_STAGE(G8_SB(1, 0), b3);
;       G8_BAR; G8_WAIT_L(0); G8_MMA(0, 1, At, B1); G8_BAR;
;       G8_LDA(At, 1, 1); G8_STAGE(G8_SA(1, 0), a3);
;       G8_BAR; G8_WAIT_L(0); G8_MMA(1, 0, At, B0); G8_BAR; G8_SCHED;
;       G8_STAGE(G8_SB(1, 1), b3 + hstep);
;       G8_WAIT_V(6); G8_BAR; G8_MMA(1, 1, At, B1); G8_BAR;
	s_add_u32 s56, s26, 0x20000
	s_addc_u32 s57, s27, 0
	s_mov_b32 m0, s41
	v_lshl_add_u64 v[34:35], s[56:57], 0, v[0:1]
	global_load_lds_dwordx4 v[34:35], off
	s_mov_b32 m0, s42
	v_lshl_add_u64 v[34:35], s[56:57], 0, v[152:153]
	global_load_lds_dwordx4 v[34:35], off
	s_waitcnt vmcnt(6)
	s_barrier
	v_mfma_f32_16x16x32_f16 v[38:41], v[214:217], v[178:181], v[38:41]
	v_mfma_f32_16x16x32_f16 v[42:45], v[222:225], v[178:181], v[42:45]
	v_mfma_f32_16x16x32_f16 v[18:21], v[214:217], v[186:189], v[18:21]
	v_mfma_f32_16x16x32_f16 v[22:25], v[222:225], v[186:189], v[22:25]
	v_mfma_f32_16x16x32_f16 v[2:5], v[214:217], v[206:209], v[2:5]
	v_mfma_f32_16x16x32_f16 v[6:9], v[222:225], v[206:209], v[6:9]
	v_mfma_f32_16x16x32_f16 v[34:37], v[214:217], v[164:167], v[66:69]
	v_mfma_f32_16x16x32_f16 v[46:49], v[222:225], v[164:167], v[70:73]
	v_mfma_f32_16x16x32_f16 v[38:41], v[218:221], v[182:185], v[38:41]
	v_mfma_f32_16x16x32_f16 v[42:45], v[226:229], v[182:185], v[42:45]
	v_mfma_f32_16x16x32_f16 v[18:21], v[218:221], v[202:205], v[18:21]
	v_mfma_f32_16x16x32_f16 v[22:25], v[226:229], v[202:205], v[22:25]
	v_mfma_f32_16x16x32_f16 v[2:5], v[218:221], v[210:213], v[2:5]
	v_mfma_f32_16x16x32_f16 v[6:9], v[226:229], v[210:213], v[6:9]
	v_mfma_f32_16x16x32_f16 v[34:37], v[218:221], v[174:177], v[34:37]
	v_mfma_f32_16x16x32_f16 v[46:49], v[226:229], v[174:177], v[46:49]
	v_or_b32_e32 v50, 0x18000, v171
	v_add_u32_e32 v66, 0x18400, v171
	v_add_u32_e32 v70, 0x18800, v171
	v_add_u32_e32 v160, 0x18c00, v171
	s_barrier
	ds_read_b128 v[50:53], v50
	ds_read_b128 v[66:69], v66
	ds_read_b128 v[70:73], v70
	ds_read_b128 v[160:163], v160
	s_add_u32 s28, s28, 0x20000
	s_addc_u32 s29, s29, 0
	s_mov_b32 m0, s43
	v_lshl_add_u64 v[214:215], s[28:29], 0, v[0:1]
	ds_read_b128 v[164:167], v170 offset:32768
	ds_read_b128 v[174:177], v170 offset:33792
	ds_read_b128 v[178:181], v170 offset:34816
	ds_read_b128 v[182:185], v170 offset:35840
	ds_read_b128 v[186:189], v170 offset:36864
	ds_read_b128 v[202:205], v170 offset:37888
	ds_read_b128 v[206:209], v170 offset:38912
	ds_read_b128 v[210:213], v170 offset:39936
	global_load_lds_dwordx4 v[214:215], off
	s_mov_b32 m0, s44
	v_lshl_add_u64 v[214:215], s[28:29], 0, v[152:153]
	global_load_lds_dwordx4 v[214:215], off
	s_waitcnt lgkmcnt(8)
	s_barrier
	s_waitcnt lgkmcnt(0)
	v_mfma_f32_16x16x32_f16 v[62:65], v[50:53], v[164:167], v[62:65]
	v_mfma_f32_16x16x32_f16 v[138:141], v[70:73], v[164:167], v[138:141]
	v_mfma_f32_16x16x32_f16 v[122:125], v[50:53], v[178:181], v[122:125]
	v_mfma_f32_16x16x32_f16 v[126:129], v[70:73], v[178:181], v[126:129]
	v_mfma_f32_16x16x32_f16 v[106:109], v[50:53], v[186:189], v[106:109]
	v_mfma_f32_16x16x32_f16 v[110:113], v[70:73], v[186:189], v[110:113]
	v_mfma_f32_16x16x32_f16 v[90:93], v[50:53], v[206:209], v[90:93]
	v_mfma_f32_16x16x32_f16 v[94:97], v[70:73], v[206:209], v[94:97]
	v_mfma_f32_16x16x32_f16 v[62:65], v[66:69], v[174:177], v[62:65]
	v_mfma_f32_16x16x32_f16 v[138:141], v[160:163], v[174:177], v[138:141]
	v_mfma_f32_16x16x32_f16 v[122:125], v[66:69], v[182:185], v[122:125]
	v_mfma_f32_16x16x32_f16 v[126:129], v[160:163], v[182:185], v[126:129]
	v_mfma_f32_16x16x32_f16 v[106:109], v[66:69], v[202:205], v[106:109]
	v_mfma_f32_16x16x32_f16 v[110:113], v[160:163], v[202:205], v[110:113]
	v_mfma_f32_16x16x32_f16 v[90:93], v[66:69], v[210:213], v[90:93]
	v_mfma_f32_16x16x32_f16 v[94:97], v[160:163], v[210:213], v[94:97]
	s_barrier
	v_or_b32_e32 v173, 0x1c000, v171
	s_mov_b32 m0, s46
	v_add_u32_e32 v195, 0x1c400, v171
	ds_read_b128 v[214:217], v173
	ds_read_b128 v[218:221], v195
	v_add_u32_e32 v173, 0x1c800, v171
	v_lshl_add_u64 v[168:169], v[168:169], 0, s[94:95]
	v_add_u32_e32 v195, 0x1cc00, v171
	ds_read_b128 v[222:225], v173
	ds_read_b128 v[226:229], v195
	global_load_lds_dwordx4 v[168:169], off
	s_mov_b32 m0, s47
	v_lshl_add_u64 v[168:169], v[230:231], 0, s[94:95]
	global_load_lds_dwordx4 v[168:169], off
	s_barrier
	s_waitcnt lgkmcnt(0)
	v_mfma_f32_16x16x32_f16 v[130:133], v[214:217], v[164:167], v[130:133]
	v_mfma_f32_16x16x32_f16 v[134:137], v[222:225], v[164:167], v[134:137]
	v_mfma_f32_16x16x32_f16 v[114:117], v[214:217], v[178:181], v[114:117]
	v_mfma_f32_16x16x32_f16 v[118:121], v[222:225], v[178:181], v[118:121]
	v_mfma_f32_16x16x32_f16 v[98:101], v[214:217], v[186:189], v[98:101]
	v_mfma_f32_16x16x32_f16 v[102:105], v[222:225], v[186:189], v[102:105]
	v_mfma_f32_16x16x32_f16 v[82:85], v[214:217], v[206:209], v[82:85]
	v_mfma_f32_16x16x32_f16 v[86:89], v[222:225], v[206:209], v[86:89]
	v_mfma_f32_16x16x32_f16 v[130:133], v[218:221], v[174:177], v[130:133]
	v_mfma_f32_16x16x32_f16 v[134:137], v[226:229], v[174:177], v[134:137]
	v_mfma_f32_16x16x32_f16 v[114:117], v[218:221], v[182:185], v[114:117]
	v_mfma_f32_16x16x32_f16 v[118:121], v[226:229], v[182:185], v[118:121]
	v_mfma_f32_16x16x32_f16 v[98:101], v[218:221], v[202:205], v[98:101]
	v_mfma_f32_16x16x32_f16 v[102:105], v[226:229], v[202:205], v[102:105]
	v_mfma_f32_16x16x32_f16 v[82:85], v[218:221], v[210:213], v[82:85]
	v_mfma_f32_16x16x32_f16 v[86:89], v[226:229], v[210:213], v[86:89]
	s_mov_b32 m0, s48
	v_lshl_add_u64 v[168:169], v[232:233], 0, s[94:95]
	s_barrier
	ds_read_b128 v[164:167], v170 offset:49152
	ds_read_b128 v[174:177], v170 offset:50176
	ds_read_b128 v[178:181], v170 offset:51200
	ds_read_b128 v[182:185], v170 offset:52224
	ds_read_b128 v[186:189], v170 offset:53248
	ds_read_b128 v[202:205], v170 offset:54272
	ds_read_b128 v[206:209], v170 offset:55296
	ds_read_b128 v[210:213], v170 offset:56320
	global_load_lds_dwordx4 v[168:169], off
	s_mov_b32 m0, s49
	v_lshl_add_u64 v[168:169], v[234:235], 0, s[94:95]
	global_load_lds_dwordx4 v[168:169], off
	s_barrier
; #define G8_STAGE(bufoff, gbase) do { _Pragma("unroll") for (int _i = 0; _i < 2; ++_i) \
;     __builtin_amdgcn_global_load_lds((const unsigned*)((const char*)(gbase) + voffA[_i]), (LAS unsigned*)(lds + (bufoff) + ldsw + _i * 8192), 16, 0, 0); } while (0)
; #define G8_LDA(dst, b, h) do { _Pragma("unroll") for (int m = 0; m < 4; ++m) _Pragma("unroll") for (int k = 0; k < 2; ++k) dst[m][k] = *(const LAS h16x8*)(lds + G8_SA(b, h) + aoff + m * 2048 + k * 1024); } while (0)
; #define G8_MMA(ai, bj, At, Bt_) do { __builtin_amdgcn_s_setprio(1); _Pragma("unroll") for (int m = 0; m < 4; ++m) _Pragma("unroll") for (int n = 0; n < 2; ++n) _Pragma("unroll") for (int k = 0; k < 2; ++k) \
;     acc[ai][bj][m][n] = __builtin_amdgcn_mfma_f32_16x16x32_f16(Bt_[n][k], At[m][k], acc[ai][bj][m][n], 0, 0, 0); __builtin_amdgcn_s_setprio(0); } while (0)
; #define G8_WAIT_V(n) asm volatile("s_waitcnt vmcnt(" #n ")" ::: "memory")
; #define G8_WAIT_L(n) asm volatile("s_waitcnt lgkmcnt(" #n ")" ::: "memory")
; #define G8_BAR __builtin_amdgcn_s_barrier()
; #define G8_SCHED __builtin_amdgcn_sched_barrier(0)
; template <class Epi>
; __device__ __forceinline__ void gemm_phase(LAS unsigned char* lds, const h16* A, const h16* Bt, int K, const Order& S, const Epi& E) {
;     ...
;       G8_LDA(At, 1, 1); G8_STAGE(G8_SA(1, 0), a3);
;       G8_BAR; G8_WAIT_L(0); G8_MMA(1, 0, At, B0); G8_BAR; G8_SCHED;
;       G8_STAGE(G8_SB(1, 1), b3 + hstep);
;       G8_WAIT_V(6); G8_BAR; G8_MMA(1, 1, At, B1); G8_BAR;
	s_waitcnt lgkmcnt(0)
	v_mfma_f32_16x16x32_f16 v[74:77], v[50:53], v[164:167], v[74:77]
	v_mfma_f32_16x16x32_f16 v[78:81], v[70:73], v[164:167], v[78:81]
	v_mfma_f32_16x16x32_f16 v[54:57], v[50:53], v[178:181], v[54:57]
	v_mfma_f32_16x16x32_f16 v[58:61], v[70:73], v[178:181], v[58:61]
	v_mfma_f32_16x16x32_f16 v[26:29], v[50:53], v[186:189], v[26:29]
	v_mfma_f32_16x16x32_f16 v[30:33], v[70:73], v[186:189], v[30:33]
	v_mfma_f32_16x16x32_f16 v[10:13], v[50:53], v[206:209], v[10:13]
	v_mfma_f32_16x16x32_f16 v[14:17], v[70:73], v[206:209], v[14:17]
	v_mfma_f32_16x16x32_f16 v[74:77], v[66:69], v[174:177], v[74:77]
	v_mfma_f32_16x16x32_f16 v[78:81], v[160:163], v[174:177], v[78:81]
	v_mfma_f32_16x16x32_f16 v[54:57], v[66:69], v[182:185], v[54:57]
	v_mfma_f32_16x16x32_f16 v[58:61], v[160:163], v[182:185], v[58:61]
	v_mfma_f32_16x16x32_f16 v[26:29], v[66:69], v[202:205], v[26:29]
	v_mfma_f32_16x16x32_f16 v[30:33], v[160:163], v[202:205], v[30:33]
	v_mfma_f32_16x16x32_f16 v[10:13], v[66:69], v[210:213], v[10:13]
	v_mfma_f32_16x16x32_f16 v[14:17], v[160:163], v[210:213], v[14:17]
	s_barrier
	s_add_u32 s26, s26, 0x20080
	s_addc_u32 s27, s27, 0
	s_mov_b32 m0, s50
	v_lshl_add_u64 v[50:51], s[26:27], 0, v[0:1]
	global_load_lds_dwordx4 v[50:51], off
	s_mov_b32 m0, s51
	v_lshl_add_u64 v[50:51], s[26:27], 0, v[152:153]
	global_load_lds_dwordx4 v[50:51], off
	s_waitcnt vmcnt(6)
	s_barrier
	v_mfma_f32_16x16x32_f16 v[34:37], v[214:217], v[164:167], v[34:37]
	v_mfma_f32_16x16x32_f16 v[66:69], v[218:221], v[174:177], v[34:37]
	v_mfma_f32_16x16x32_f16 v[34:37], v[222:225], v[164:167], v[46:49]
	v_mfma_f32_16x16x32_f16 v[70:73], v[226:229], v[174:177], v[34:37]
	v_mfma_f32_16x16x32_f16 v[34:37], v[214:217], v[178:181], v[38:41]
	v_mfma_f32_16x16x32_f16 v[38:41], v[218:221], v[182:185], v[34:37]
	v_mfma_f32_16x16x32_f16 v[34:37], v[222:225], v[178:181], v[42:45]
	v_mfma_f32_16x16x32_f16 v[18:21], v[214:217], v[186:189], v[18:21]
	v_mfma_f32_16x16x32_f16 v[22:25], v[222:225], v[186:189], v[22:25]
	v_mfma_f32_16x16x32_f16 v[2:5], v[214:217], v[206:209], v[2:5]
	v_mfma_f32_16x16x32_f16 v[6:9], v[222:225], v[206:209], v[6:9]
	v_mfma_f32_16x16x32_f16 v[42:45], v[226:229], v[182:185], v[34:37]
	v_mfma_f32_16x16x32_f16 v[18:21], v[218:221], v[202:205], v[18:21]
	v_mfma_f32_16x16x32_f16 v[22:25], v[226:229], v[202:205], v[22:25]
	v_mfma_f32_16x16x32_f16 v[2:5], v[218:221], v[210:213], v[2:5]
	v_mfma_f32_16x16x32_f16 v[6:9], v[226:229], v[210:213], v[6:9]
	s_add_i32 s55, s55, 2
	s_add_u32 s24, s24, 0x100
	s_addc_u32 s25, s25, 0
	s_add_u32 s53, s53, 0x100
	s_addc_u32 s54, s54, 0
	s_cmp_gt_u32 s55, 5
	s_barrier
	s_cbranch_scc0 .LBB0_2284
; __device__ __forceinline__ float xor16(float v) { return __int_as_float(__builtin_amdgcn_ds_swizzle(__float_as_int(v), 0x401F)); }
; __device__ __forceinline__ float sigmoidf(float x) { return 1.f / (1.f + __expf(-x)); }
;   __device__ __forceinline__ void operator()(const f32x4 (&acc)[2][2][4][2], const g8::Unit& u, int ui, int wr, int wc, int fr, int fq) const {
;     const int ocb = 128 * u.pn + 16 * wc + 4 * fq;
;     float4 ba[2], bb[2];
; #pragma unroll
;     for (int bj = 0; bj < 2; ++bj) { ba[bj] = *(const float4*)(gb + ocb + 64 * bj); bb[bj] = *(const float4*)(gb + 512 + ocb + 64 * bj); }
; #pragma unroll
;     for (int ai = 0; ai < 2; ++ai)
; #pragma unroll
;       for (int m = 0; m < 4; ++m) {
;         const size_t row = (size_t)u.pm * 256 + 128 * ai + 64 * wr + 16 * m + fr;
;         float ss = 0.f;
; #pragma unroll
;         for (int bj = 0; bj < 2; ++bj) {
;           const f32x4 a = acc[ai][bj][m][0], b = acc[ai][bj][m][1];
;           float o0 = (a[0] + ba[bj].x) * sigmoidf(b[0] + bb[bj].x);
;           float o1 = (a[1] + ba[bj].y) * sigmoidf(b[1] + bb[bj].y);
;           float o2 = (a[2] + ba[bj].z) * sigmoidf(b[2] + bb[bj].z);
;           float o3 = (a[3] + ba[bj].w) * sigmoidf(b[3] + bb[bj].w);
;           *(h16x4*)(OB + row * 1024 + ocb + 64 * bj) = pack4(o0, o1, o2, o3);
;           ss += o0 * o0 + o1 * o1 + o2 * o2 + o3 * o3;
;         }
;         ss += xor16(ss);
;         ss += __shfl_xor(ss, 32);
;         if (fq == 0) ssqb[row * 16 + u.pn * 4 + wc] = ss;
;       }
	v_lshl_or_b32 v160, s2, 7, v172
	v_ashrrev_i32_e32 v161, 31, v160
	v_lshl_add_u64 v[166:167], v[160:161], 2, s[12:13]
	global_load_dwordx4 v[46:49], v[166:167], off offset:2048
	global_load_dwordx4 v[34:37], v[166:167], off offset:2304
	v_and_b32_e32 v51, 64, v199
	v_xor_b32_e32 v50, 32, v199
	v_add_u32_e32 v51, 64, v51
	v_cmp_lt_i32_e32 vcc, v50, v51
	s_ashr_i32 s23, s22, 31
	s_lshl_b64 s[22:23], s[22:23], 8
	v_cndmask_b32_e32 v50, v199, v50, vcc
	v_lshlrev_b32_e32 v173, 2, v50
	v_lshl_add_u64 v[162:163], s[22:23], 0, v[154:155]
	s_lshl_b32 s22, s2, 2
	v_lshlrev_b64 v[164:165], 11, v[162:163]
	s_ashr_i32 s23, s22, 31
	s_waitcnt vmcnt(0)
	v_add_f32_e32 v50, v138, v46
	v_mul_f32_e32 v50, 0xbfb8aa3b, v50
	v_exp_f32_e32 v138, v50
	global_load_dwordx4 v[50:53], v[166:167], off
	v_add_f32_e32 v139, v139, v47
	v_mul_f32_e32 v139, 0xbfb8aa3b, v139
	v_exp_f32_e32 v139, v139
	v_add_f32_e32 v140, v140, v48
	v_add_f32_e32 v141, v141, v49
	v_mul_f32_e32 v140, 0xbfb8aa3b, v140
	v_pk_add_f32 v[138:139], v[138:139], 1.0 op_sel_hi:[1,0]
	v_mul_f32_e32 v141, 0xbfb8aa3b, v141
	v_div_scale_f32 v168, s[2:3], v139, v139, 1.0
	v_rcp_f32_e32 v169, v168
	v_exp_f32_e32 v140, v140
	v_exp_f32_e32 v141, v141
	v_add_f32_e32 v135, v135, v35
	v_fma_f32 v174, -v168, v169, 1.0
	v_fmac_f32_e32 v169, v174, v169
	v_div_scale_f32 v174, vcc, 1.0, v139, 1.0
	v_mul_f32_e32 v175, v174, v169
	v_fma_f32 v176, -v168, v175, v174
	v_fmac_f32_e32 v175, v176, v169
	v_fma_f32 v168, -v168, v175, v174
	v_div_fmas_f32 v168, v168, v169, v175
	v_div_fixup_f32 v139, v168, v139, 1.0
	v_div_scale_f32 v168, s[2:3], v138, v138, 1.0
	v_rcp_f32_e32 v169, v168
	v_mul_f32_e32 v135, 0xbfb8aa3b, v135
	v_exp_f32_e32 v135, v135
	v_add_f32_e32 v136, v136, v36
	v_fma_f32 v174, -v168, v169, 1.0
	v_fmac_f32_e32 v169, v174, v169
	v_div_scale_f32 v174, vcc, 1.0, v138, 1.0
	v_mul_f32_e32 v175, v174, v169
	v_fma_f32 v176, -v168, v175, v174
	v_fmac_f32_e32 v175, v176, v169
	v_fma_f32 v168, -v168, v175, v174
	v_div_fmas_f32 v168, v168, v169, v175
	v_div_fixup_f32 v138, v168, v138, 1.0
	v_add_f32_e32 v137, v137, v37
	v_mul_f32_e32 v136, 0xbfb8aa3b, v136
	v_mul_f32_e32 v137, 0xbfb8aa3b, v137
	v_exp_f32_e32 v136, v136
	v_exp_f32_e32 v137, v137
	s_waitcnt vmcnt(0)
	v_pk_add_f32 v[62:63], v[62:63], v[50:51]
	s_nop 0
	v_pk_mul_f32 v[62:63], v[62:63], v[138:139]
	v_pk_add_f32 v[138:139], v[140:141], 1.0 op_sel_hi:[1,0]
	v_cvt_pk_f16_f32 v168, v62, v63
	v_div_scale_f32 v140, s[2:3], v139, v139, 1.0
	v_rcp_f32_e32 v141, v140
	v_pk_add_f32 v[64:65], v[64:65], v[52:53]
	v_pk_add_f32 v[136:137], v[136:137], 1.0 op_sel_hi:[1,0]
	v_fma_f32 v169, -v140, v141, 1.0
	v_fmac_f32_e32 v141, v169, v141
	v_div_scale_f32 v169, vcc, 1.0, v139, 1.0
	v_mul_f32_e32 v174, v169, v141
	v_fma_f32 v175, -v140, v174, v169
	v_fmac_f32_e32 v174, v175, v141
	v_fma_f32 v140, -v140, v174, v169
	v_div_fmas_f32 v140, v140, v141, v174
	v_div_fixup_f32 v139, v140, v139, 1.0
	v_div_scale_f32 v140, s[2:3], v138, v138, 1.0
	v_rcp_f32_e32 v141, v140
	s_nop 0
	v_fma_f32 v169, -v140, v141, 1.0
	v_fmac_f32_e32 v141, v169, v141
	v_div_scale_f32 v169, vcc, 1.0, v138, 1.0
	v_mul_f32_e32 v174, v169, v141
	v_fma_f32 v175, -v140, v174, v169
	v_fmac_f32_e32 v174, v175, v141
	v_fma_f32 v140, -v140, v174, v169
	v_div_fmas_f32 v140, v140, v141, v174
	v_div_fixup_f32 v138, v140, v138, 1.0
	v_pk_mul_f32 v[140:141], v[62:63], v[62:63]
	v_add_f32_e32 v62, v134, v34
	v_pk_mul_f32 v[64:65], v[64:65], v[138:139]
	v_lshl_add_u64 v[138:139], s[0:1], 0, v[164:165]
	v_mul_f32_e32 v62, 0xbfb8aa3b, v62
	v_cvt_pk_f16_f32 v169, v64, v65
	v_lshl_add_u64 v[164:165], v[160:161], 1, v[138:139]
	v_pk_mul_f32 v[138:139], v[64:65], v[64:65]
	v_exp_f32_e32 v134, v62
	global_load_dwordx4 v[62:65], v[166:167], off offset:256
	v_pk_add_f32 v[134:135], v[134:135], 1.0 op_sel_hi:[1,0]
	s_nop 0
	v_div_scale_f32 v166, s[2:3], v135, v135, 1.0
	v_rcp_f32_e32 v167, v166
	global_store_dwordx2 v[164:165], v[168:169], off
	v_fma_f32 v168, -v166, v167, 1.0
	v_fmac_f32_e32 v167, v168, v167
	v_div_scale_f32 v168, vcc, 1.0, v135, 1.0
	v_mul_f32_e32 v169, v168, v167
	v_fma_f32 v174, -v166, v169, v168
	v_fmac_f32_e32 v169, v174, v167
	v_fma_f32 v166, -v166, v169, v168
	v_div_fmas_f32 v166, v166, v167, v169
	v_div_fixup_f32 v135, v166, v135, 1.0
	v_div_scale_f32 v166, s[2:3], v134, v134, 1.0
	v_rcp_f32_e32 v167, v166
	s_waitcnt vmcnt(0)
	v_pk_add_f32 v[130:131], v[130:131], v[62:63]
	v_fma_f32 v168, -v166, v167, 1.0
	v_fmac_f32_e32 v167, v168, v167
	v_div_scale_f32 v168, vcc, 1.0, v134, 1.0
	v_mul_f32_e32 v169, v168, v167
	v_fma_f32 v174, -v166, v169, v168
	v_fmac_f32_e32 v169, v174, v167
	v_fma_f32 v166, -v166, v169, v168
	v_div_fmas_f32 v166, v166, v167, v169
	v_div_fixup_f32 v134, v166, v134, 1.0
	v_pk_mul_f32 v[130:131], v[130:131], v[134:135]
	v_div_scale_f32 v135, s[2:3], v137, v137, 1.0
	v_rcp_f32_e32 v166, v135
	v_pk_add_f32 v[132:133], v[132:133], v[64:65]
	v_cvt_pk_f16_f32 v134, v130, v131
	v_pk_mul_f32 v[130:131], v[130:131], v[130:131]
	v_fma_f32 v167, -v135, v166, 1.0
	v_fmac_f32_e32 v166, v167, v166
	v_div_scale_f32 v167, vcc, 1.0, v137, 1.0
	v_mul_f32_e32 v168, v167, v166
	v_fma_f32 v169, -v135, v168, v167
	v_fmac_f32_e32 v168, v169, v166
	v_fma_f32 v135, -v135, v168, v167
	v_div_fmas_f32 v135, v135, v166, v168
	v_div_fixup_f32 v137, v135, v137, 1.0
	v_div_scale_f32 v135, s[2:3], v136, v136, 1.0
	v_rcp_f32_e32 v166, v135
	v_add_f32_e32 v130, v130, v131
	v_add_f32_e32 v131, v140, v141
	v_add_f32_e32 v131, v138, v131
	v_fma_f32 v167, -v135, v166, 1.0
	v_fmac_f32_e32 v166, v167, v166
	v_div_scale_f32 v167, vcc, 1.0, v136, 1.0
	v_mul_f32_e32 v168, v167, v166
	v_fma_f32 v169, -v135, v168, v167
	v_fmac_f32_e32 v168, v169, v166
	v_fma_f32 v135, -v135, v168, v167
	v_div_fmas_f32 v135, v135, v166, v168
	v_div_fixup_f32 v136, v135, v136, 1.0
	v_pk_mul_f32 v[132:133], v[132:133], v[136:137]
	v_add_f32_e32 v131, v139, v131
	v_cvt_pk_f16_f32 v135, v132, v133
	v_pk_mul_f32 v[132:133], v[132:133], v[132:133]
	global_store_dwordx2 v[164:165], v[134:135], off offset:128
	v_add_f32_e32 v130, v132, v130
	v_add_f32_e32 v130, v133, v130
	v_add_f32_e32 v130, v131, v130
	v_mov_b32_e32 v131, v130
	s_nop 1
	v_permlane16_swap_b32_e32 v131, v130
	s_waitcnt lgkmcnt(0)
	v_add_f32_e32 v130, v130, v131
	v_mov_b32_e32 v131, v130
	s_nop 1
	v_permlane32_swap_b32_e32 v131, v130
	s_and_saveexec_b64 s[24:25], s[6:7]
	s_cbranch_execz .LBB0_2287
	s_waitcnt lgkmcnt(0)
	v_add_f32_e32 v132, v130, v131
	v_lshlrev_b64 v[130:131], 6, v[162:163]
	v_lshl_add_u64 v[130:131], s[10:11], 0, v[130:131]
	v_lshl_add_u64 v[130:131], s[22:23], 2, v[130:131]
	s_lshl_b32 s92, s45, 2
	v_lshl_add_u64 v[130:131], v[130:131], 0, s[92:93]
	global_store_dword v[130:131], v132, off

; #define G8_STAGE(bufoff, gbase) do { _Pragma("unroll") for (int _i = 0; _i < 2; ++_i) \
;     __builtin_amdgcn_global_load_lds((const unsigned*)((const char*)(gbase) + voffA[_i]), (LAS unsigned*)(lds + (bufoff) + ldsw + _i * 8192), 16, 0, 0); } while (0)
; #define G8_LDA(dst, b, h) do { _Pragma("unroll") for (int m = 0; m < 4; ++m) _Pragma("unroll") for (int k = 0; k < 2; ++k) dst[m][k] = *(const LAS h16x8*)(lds + G8_SA(b, h) + aoff + m * 2048 + k * 1024); } while (0)
; #define G8_LDB(dst, b, h) do { _Pragma("unroll") for (int n = 0; n < 2; ++n) _Pragma("unroll") for (int k = 0; k < 2; ++k) dst[n][k] = *(const LAS h16x8*)(lds + G8_SB(b, h) + boff + n * 2048 + k * 1024); } while (0)
; #define G8_MMA(ai, bj, At, Bt_) do { __builtin_amdgcn_s_setprio(1); _Pragma("unroll") for (int m = 0; m < 4; ++m) _Pragma("unroll") for (int n = 0; n < 2; ++n) _Pragma("unroll") for (int k = 0; k < 2; ++k) \
;     acc[ai][bj][m][n] = __builtin_amdgcn_mfma_f32_16x16x32_f16(Bt_[n][k], At[m][k], acc[ai][bj][m][n], 0, 0, 0); __builtin_amdgcn_s_setprio(0); } while (0)
; #define G8_WAIT_L(n) asm volatile("s_waitcnt lgkmcnt(" #n ")" ::: "memory")
; #define G8_BAR __builtin_amdgcn_s_barrier()
; #define G8_SCHED __builtin_amdgcn_sched_barrier(0)
; template <class Epi>
; __device__ __forceinline__ void gemm_phase(LAS unsigned char* lds, const h16* A, const h16* Bt, int K, const Order& S, const Epi& E) {
;     ...
;     for (int t = 0; t < nt; t += 2) {
;       const bool last = (t == nt - 2);
;       const char* a1 = cA + (size_t)(t + 1) * kstep;
;       const char* a2 = last ? nA : cA + (size_t)(t + 2) * kstep;
;       const char* b2 = last ? nB : cB + (size_t)(t + 2) * kstep;
;       const char* a3 = a2 + kstep;
;       const char* b3 = b2 + kstep;
;       if (Epi::MID_T >= 0 && t == Epi::MID_T) E.mid(acc, ui, wr, fr);
;       G8_LDB(B0, 0, 0); G8_SCHED; G8_LDA(At, 0, 0); G8_STAGE(G8_SA(1, 1), a1 + hstep);
;       G8_WAIT_L(8); G8_BAR; G8_WAIT_L(0); G8_MMA(0, 0, At, B0); G8_BAR; G8_SCHED;
;       G8_LDB(B1, 0, 1); G8_STAGE(G8_SB(0, 0), b2);
;       G8_BAR; G8_WAIT_L(0); G8_MMA(0, 1, At, B1); G8_BAR;
;       G8_LDA(At, 0, 1); G8_STAGE(G8_SA(0, 0), a2);
;       G8_BAR; G8_WAIT_L(0); G8_MMA(1, 0, At, B0); G8_BAR; G8_SCHED;
.LBB0_2378:
	s_add_u32 s26, s20, s24
	v_or_b32_e32 v0, 0x10000, v158
	s_addc_u32 s27, s21, s25
	v_add_u32_e32 v2, 0x10400, v158
	ds_read_b128 v[162:165], v0
	ds_read_b128 v[166:169], v2
	v_add_u32_e32 v0, 0x10800, v158
	s_add_u32 s26, s26, 0x100
	v_add_u32_e32 v2, 0x10c00, v158
	ds_read_b128 v[170:173], v0
	ds_read_b128 v[174:177], v2
	s_addc_u32 s27, s27, 0
	s_add_u32 s56, s53, s24
	s_addc_u32 s57, s54, s25
	s_cmpk_eq_i32 s24, 0x700
	s_cselect_b32 s29, s3, s27
	s_cselect_b32 s28, s15, s26
	s_cselect_b32 s27, s13, s57
	s_cselect_b32 s26, s23, s56
	v_lshl_add_u64 v[2:3], v[154:155], 0, s[24:25]
	s_add_i32 m0, s37, 0xc000
	ds_read_b128 v[178:181], v139
	ds_read_b128 v[182:185], v139 offset:1024
	ds_read_b128 v[186:189], v139 offset:2048
	ds_read_b128 v[202:205], v139 offset:3072
	ds_read_b128 v[206:209], v139 offset:4096
	ds_read_b128 v[210:213], v139 offset:5120
	ds_read_b128 v[214:217], v139 offset:6144
	ds_read_b128 v[218:221], v139 offset:7168
	global_load_lds_dwordx4 v[2:3], off
	s_add_i32 m0, s37, 0xe000
	v_lshl_add_u64 v[2:3], v[156:157], 0, s[24:25]
	global_load_lds_dwordx4 v[2:3], off
	s_waitcnt lgkmcnt(8)
	s_barrier
	s_waitcnt lgkmcnt(0)
	v_mfma_f32_16x16x32_f16 v[128:131], v[162:165], v[178:181], v[128:131]
	v_mfma_f32_16x16x32_f16 v[124:127], v[170:173], v[178:181], v[124:127]
	v_mfma_f32_16x16x32_f16 v[112:115], v[162:165], v[186:189], v[112:115]
	v_mfma_f32_16x16x32_f16 v[108:111], v[170:173], v[186:189], v[108:111]
	v_mfma_f32_16x16x32_f16 v[96:99], v[162:165], v[206:209], v[96:99]
	v_mfma_f32_16x16x32_f16 v[92:95], v[170:173], v[206:209], v[92:95]
	v_mfma_f32_16x16x32_f16 v[80:83], v[162:165], v[214:217], v[80:83]
	v_mfma_f32_16x16x32_f16 v[76:79], v[170:173], v[214:217], v[76:79]
	v_mfma_f32_16x16x32_f16 v[128:131], v[166:169], v[182:185], v[128:131]
	v_mfma_f32_16x16x32_f16 v[124:127], v[174:177], v[182:185], v[124:127]
	v_mfma_f32_16x16x32_f16 v[112:115], v[166:169], v[202:205], v[112:115]
	v_mfma_f32_16x16x32_f16 v[108:111], v[174:177], v[202:205], v[108:111]
	v_mfma_f32_16x16x32_f16 v[96:99], v[166:169], v[210:213], v[96:99]
	v_mfma_f32_16x16x32_f16 v[92:95], v[174:177], v[210:213], v[92:95]
	v_mfma_f32_16x16x32_f16 v[80:83], v[166:169], v[218:221], v[80:83]
	v_mfma_f32_16x16x32_f16 v[76:79], v[174:177], v[218:221], v[76:79]
	s_barrier
	v_or_b32_e32 v0, 0x14000, v158
	s_mov_b32 m0, s38
	v_add_u32_e32 v2, 0x14400, v158
	ds_read_b128 v[222:225], v0
	ds_read_b128 v[226:229], v2
	v_add_u32_e32 v0, 0x14800, v158
	v_lshl_add_u64 v[238:239], s[26:27], 0, v[134:135]
	v_add_u32_e32 v2, 0x14c00, v158
	ds_read_b128 v[230:233], v0
	ds_read_b128 v[234:237], v2
	global_load_lds_dwordx4 v[238:239], off
	s_mov_b32 m0, s39
	v_lshl_add_u64 v[240:241], s[26:27], 0, v[132:133]
	global_load_lds_dwordx4 v[240:241], off
	s_barrier
	s_waitcnt lgkmcnt(0)
	v_mfma_f32_16x16x32_f16 v[120:123], v[222:225], v[178:181], v[120:123]
	v_mfma_f32_16x16x32_f16 v[116:119], v[230:233], v[178:181], v[116:119]
	v_mfma_f32_16x16x32_f16 v[104:107], v[222:225], v[186:189], v[104:107]
	v_mfma_f32_16x16x32_f16 v[100:103], v[230:233], v[186:189], v[100:103]
	v_mfma_f32_16x16x32_f16 v[88:91], v[222:225], v[206:209], v[88:91]
	v_mfma_f32_16x16x32_f16 v[84:87], v[230:233], v[206:209], v[84:87]
	v_mfma_f32_16x16x32_f16 v[72:75], v[222:225], v[214:217], v[72:75]
	v_mfma_f32_16x16x32_f16 v[68:71], v[230:233], v[214:217], v[68:71]
	v_mfma_f32_16x16x32_f16 v[120:123], v[226:229], v[182:185], v[120:123]
	v_mfma_f32_16x16x32_f16 v[116:119], v[234:237], v[182:185], v[116:119]
	v_mfma_f32_16x16x32_f16 v[104:107], v[226:229], v[202:205], v[104:107]
	v_mfma_f32_16x16x32_f16 v[100:103], v[234:237], v[202:205], v[100:103]
	v_mfma_f32_16x16x32_f16 v[88:91], v[226:229], v[210:213], v[88:91]
	v_mfma_f32_16x16x32_f16 v[84:87], v[234:237], v[210:213], v[84:87]
	v_mfma_f32_16x16x32_f16 v[72:75], v[226:229], v[218:221], v[72:75]
	v_mfma_f32_16x16x32_f16 v[68:71], v[234:237], v[218:221], v[68:71]
	s_mov_b32 m0, s37
	v_lshl_add_u64 v[242:243], s[28:29], 0, v[134:135]
	s_barrier
	ds_read_b128 v[178:181], v139 offset:16384
	ds_read_b128 v[182:185], v139 offset:17408
	ds_read_b128 v[186:189], v139 offset:18432
	ds_read_b128 v[202:205], v139 offset:19456
	ds_read_b128 v[206:209], v139 offset:20480
	ds_read_b128 v[210:213], v139 offset:21504
	ds_read_b128 v[214:217], v139 offset:22528
	ds_read_b128 v[218:221], v139 offset:23552
	global_load_lds_dwordx4 v[242:243], off
	s_mov_b32 m0, s40
	v_lshl_add_u64 v[244:245], s[28:29], 0, v[132:133]
	global_load_lds_dwordx4 v[244:245], off
	s_barrier
	s_waitcnt lgkmcnt(0)
	v_mfma_f32_16x16x32_f16 v[64:67], v[162:165], v[178:181], v[64:67]
	v_mfma_f32_16x16x32_f16 v[60:63], v[170:173], v[178:181], v[60:63]
	v_mfma_f32_16x16x32_f16 v[48:51], v[162:165], v[186:189], v[48:51]
	v_mfma_f32_16x16x32_f16 v[44:47], v[170:173], v[186:189], v[44:47]
	v_mfma_f32_16x16x32_f16 v[32:35], v[162:165], v[206:209], v[32:35]
	v_mfma_f32_16x16x32_f16 v[28:31], v[170:173], v[206:209], v[28:31]
	v_mfma_f32_16x16x32_f16 v[16:19], v[162:165], v[214:217], v[16:19]
	v_mfma_f32_16x16x32_f16 v[12:15], v[170:173], v[214:217], v[12:15]
	v_mfma_f32_16x16x32_f16 v[64:67], v[166:169], v[182:185], v[64:67]
	v_mfma_f32_16x16x32_f16 v[60:63], v[174:177], v[182:185], v[60:63]
	v_mfma_f32_16x16x32_f16 v[48:51], v[166:169], v[202:205], v[48:51]
	v_mfma_f32_16x16x32_f16 v[44:47], v[174:177], v[202:205], v[44:47]
	v_mfma_f32_16x16x32_f16 v[32:35], v[166:169], v[210:213], v[32:35]
	v_mfma_f32_16x16x32_f16 v[28:31], v[174:177], v[210:213], v[28:31]
	v_mfma_f32_16x16x32_f16 v[16:19], v[166:169], v[218:221], v[16:19]
	v_mfma_f32_16x16x32_f16 v[12:15], v[174:177], v[218:221], v[12:15]
	s_barrier
; #define G8_STAGE(bufoff, gbase) do { _Pragma("unroll") for (int _i = 0; _i < 2; ++_i) \
;     __builtin_amdgcn_global_load_lds((const unsigned*)((const char*)(gbase) + voffA[_i]), (LAS unsigned*)(lds + (bufoff) + ldsw + _i * 8192), 16, 0, 0); } while (0)
; #define G8_LDA(dst, b, h) do { _Pragma("unroll") for (int m = 0; m < 4; ++m) _Pragma("unroll") for (int k = 0; k < 2; ++k) dst[m][k] = *(const LAS h16x8*)(lds + G8_SA(b, h) + aoff + m * 2048 + k * 1024); } while (0)
; #define G8_LDB(dst, b, h) do { _Pragma("unroll") for (int n = 0; n < 2; ++n) _Pragma("unroll") for (int k = 0; k < 2; ++k) dst[n][k] = *(const LAS h16x8*)(lds + G8_SB(b, h) + boff + n * 2048 + k * 1024); } while (0)
; #define G8_MMA(ai, bj, At, Bt_) do { __builtin_amdgcn_s_setprio(1); _Pragma("unroll") for (int m = 0; m < 4; ++m) _Pragma("unroll") for (int n = 0; n < 2; ++n) _Pragma("unroll") for (int k = 0; k < 2; ++k) \
;     acc[ai][bj][m][n] = __builtin_amdgcn_mfma_f32_16x16x32_f16(Bt_[n][k], At[m][k], acc[ai][bj][m][n], 0, 0, 0); __builtin_amdgcn_s_setprio(0); } while (0)
; #define G8_WAIT_V(n) asm volatile("s_waitcnt vmcnt(" #n ")" ::: "memory")
; #define G8_WAIT_L(n) asm volatile("s_waitcnt lgkmcnt(" #n ")" ::: "memory")
; #define G8_BAR __builtin_amdgcn_s_barrier()
; #define G8_SCHED __builtin_amdgcn_sched_barrier(0)
; template <class Epi>
; __device__ __forceinline__ void gemm_phase(LAS unsigned char* lds, const h16* A, const h16* Bt, int K, const Order& S, const Epi& E) {
;     ...
;       G8_STAGE(G8_SB(0, 1), b2 + hstep);
;       G8_WAIT_V(6); G8_BAR; G8_MMA(1, 1, At, B1); G8_BAR;
;       G8_LDB(B0, 1, 0); G8_SCHED; G8_LDA(At, 1, 0); G8_STAGE(G8_SA(0, 1), a2 + hstep);
;       G8_WAIT_L(8); G8_BAR; G8_WAIT_L(0); G8_MMA(0, 0, At, B0); G8_BAR; G8_SCHED;
;       G8_LDB(B1, 1, 1); G8_STAGE(G8_SB(1, 0), b3);
	s_add_u32 s56, s26, 0x40000
	s_addc_u32 s57, s27, 0
	s_mov_b32 m0, s41
	v_lshl_add_u64 v[2:3], s[56:57], 0, v[134:135]
	global_load_lds_dwordx4 v[2:3], off
	s_mov_b32 m0, s42
	v_lshl_add_u64 v[2:3], s[56:57], 0, v[132:133]
	global_load_lds_dwordx4 v[2:3], off
	s_waitcnt vmcnt(6)
	s_barrier
	v_mfma_f32_16x16x32_f16 v[56:59], v[222:225], v[178:181], v[56:59]
	v_mfma_f32_16x16x32_f16 v[52:55], v[230:233], v[178:181], v[52:55]
	v_mfma_f32_16x16x32_f16 v[40:43], v[222:225], v[186:189], v[40:43]
	v_mfma_f32_16x16x32_f16 v[36:39], v[230:233], v[186:189], v[36:39]
	v_mfma_f32_16x16x32_f16 v[24:27], v[222:225], v[206:209], v[24:27]
	v_mfma_f32_16x16x32_f16 v[20:23], v[230:233], v[206:209], v[20:23]
	v_mfma_f32_16x16x32_f16 v[8:11], v[222:225], v[214:217], v[8:11]
	v_mfma_f32_16x16x32_f16 v[2:5], v[230:233], v[214:217], v[4:7]
	v_mfma_f32_16x16x32_f16 v[56:59], v[226:229], v[182:185], v[56:59]
	v_mfma_f32_16x16x32_f16 v[52:55], v[234:237], v[182:185], v[52:55]
	v_mfma_f32_16x16x32_f16 v[40:43], v[226:229], v[202:205], v[40:43]
	v_mfma_f32_16x16x32_f16 v[36:39], v[234:237], v[202:205], v[36:39]
	v_mfma_f32_16x16x32_f16 v[24:27], v[226:229], v[210:213], v[24:27]
	v_mfma_f32_16x16x32_f16 v[20:23], v[234:237], v[210:213], v[20:23]
	v_mfma_f32_16x16x32_f16 v[8:11], v[226:229], v[218:221], v[8:11]
	v_mfma_f32_16x16x32_f16 v[2:5], v[234:237], v[218:221], v[2:5]
	v_or_b32_e32 v0, 0x18000, v158
	s_barrier
	v_add_u32_e32 v6, 0x18400, v158
	ds_read_b128 v[162:165], v0
	ds_read_b128 v[166:169], v6
	v_add_u32_e32 v0, 0x18800, v158
	v_add_u32_e32 v6, 0x18c00, v158
	ds_read_b128 v[170:173], v0
	ds_read_b128 v[174:177], v6
	s_add_u32 s28, s28, 0x40000
	s_addc_u32 s29, s29, 0
	s_mov_b32 m0, s43
	v_lshl_add_u64 v[6:7], s[28:29], 0, v[134:135]
	ds_read_b128 v[178:181], v139 offset:32768
	ds_read_b128 v[182:185], v139 offset:33792
	ds_read_b128 v[186:189], v139 offset:34816
	ds_read_b128 v[202:205], v139 offset:35840
	ds_read_b128 v[206:209], v139 offset:36864
	ds_read_b128 v[210:213], v139 offset:37888
	ds_read_b128 v[214:217], v139 offset:38912
	ds_read_b128 v[218:221], v139 offset:39936
	global_load_lds_dwordx4 v[6:7], off
	s_mov_b32 m0, s44
	v_lshl_add_u64 v[6:7], s[28:29], 0, v[132:133]
	global_load_lds_dwordx4 v[6:7], off
	s_waitcnt lgkmcnt(8)
	s_barrier
	s_waitcnt lgkmcnt(0)
	v_mfma_f32_16x16x32_f16 v[128:131], v[162:165], v[178:181], v[128:131]
	v_mfma_f32_16x16x32_f16 v[124:127], v[170:173], v[178:181], v[124:127]
	v_mfma_f32_16x16x32_f16 v[112:115], v[162:165], v[186:189], v[112:115]
	v_mfma_f32_16x16x32_f16 v[108:111], v[170:173], v[186:189], v[108:111]
	v_mfma_f32_16x16x32_f16 v[96:99], v[162:165], v[206:209], v[96:99]
	v_mfma_f32_16x16x32_f16 v[92:95], v[170:173], v[206:209], v[92:95]
	v_mfma_f32_16x16x32_f16 v[80:83], v[162:165], v[214:217], v[80:83]
	v_mfma_f32_16x16x32_f16 v[76:79], v[170:173], v[214:217], v[76:79]
	v_mfma_f32_16x16x32_f16 v[128:131], v[166:169], v[182:185], v[128:131]
	v_mfma_f32_16x16x32_f16 v[124:127], v[174:177], v[182:185], v[124:127]
	v_mfma_f32_16x16x32_f16 v[112:115], v[166:169], v[202:205], v[112:115]
	v_mfma_f32_16x16x32_f16 v[108:111], v[174:177], v[202:205], v[108:111]
	v_mfma_f32_16x16x32_f16 v[96:99], v[166:169], v[210:213], v[96:99]
	v_mfma_f32_16x16x32_f16 v[92:95], v[174:177], v[210:213], v[92:95]
	v_mfma_f32_16x16x32_f16 v[80:83], v[166:169], v[218:221], v[80:83]
	v_mfma_f32_16x16x32_f16 v[76:79], v[174:177], v[218:221], v[76:79]
	s_barrier
	v_or_b32_e32 v0, 0x1c000, v158
	v_add_u32_e32 v6, 0x1c400, v158
	ds_read_b128 v[222:225], v0
	ds_read_b128 v[226:229], v6
	v_add_u32_e32 v0, 0x1c800, v158
	v_add_u32_e32 v6, 0x1cc00, v158
	s_mov_b32 m0, s46
	ds_read_b128 v[230:233], v0
	ds_read_b128 v[234:237], v6
	v_lshl_add_u64 v[6:7], v[238:239], 0, s[94:95]
	global_load_lds_dwordx4 v[6:7], off
	s_mov_b32 m0, s47
	v_lshl_add_u64 v[6:7], v[240:241], 0, s[94:95]
	global_load_lds_dwordx4 v[6:7], off
	s_barrier
; #define G8_STAGE(bufoff, gbase) do { _Pragma("unroll") for (int _i = 0; _i < 2; ++_i) \
;     __builtin_amdgcn_global_load_lds((const unsigned*)((const char*)(gbase) + voffA[_i]), (LAS unsigned*)(lds + (bufoff) + ldsw + _i * 8192), 16, 0, 0); } while (0)
; #define G8_LDA(dst, b, h) do { _Pragma("unroll") for (int m = 0; m < 4; ++m) _Pragma("unroll") for (int k = 0; k < 2; ++k) dst[m][k] = *(const LAS h16x8*)(lds + G8_SA(b, h) + aoff + m * 2048 + k * 1024); } while (0)
; #define G8_MMA(ai, bj, At, Bt_) do { __builtin_amdgcn_s_setprio(1); _Pragma("unroll") for (int m = 0; m < 4; ++m) _Pragma("unroll") for (int n = 0; n < 2; ++n) _Pragma("unroll") for (int k = 0; k < 2; ++k) \
;     acc[ai][bj][m][n] = __builtin_amdgcn_mfma_f32_16x16x32_f16(Bt_[n][k], At[m][k], acc[ai][bj][m][n], 0, 0, 0); __builtin_amdgcn_s_setprio(0); } while (0)
; #define G8_WAIT_V(n) asm volatile("s_waitcnt vmcnt(" #n ")" ::: "memory")
; #define G8_WAIT_L(n) asm volatile("s_waitcnt lgkmcnt(" #n ")" ::: "memory")
; #define G8_BAR __builtin_amdgcn_s_barrier()
; #define G8_SCHED __builtin_amdgcn_sched_barrier(0)
; template <class Epi>
; __device__ __forceinline__ void gemm_phase(LAS unsigned char* lds, const h16* A, const h16* Bt, int K, const Order& S, const Epi& E) {
;     ...
;       G8_BAR; G8_WAIT_L(0); G8_MMA(0, 1, At, B1); G8_BAR;
;       G8_LDA(At, 1, 1); G8_STAGE(G8_SA(1, 0), a3);
;       G8_BAR; G8_WAIT_L(0); G8_MMA(1, 0, At, B0); G8_BAR; G8_SCHED;
;       G8_STAGE(G8_SB(1, 1), b3 + hstep);
;       G8_WAIT_V(6); G8_BAR; G8_MMA(1, 1, At, B1); G8_BAR;
	s_waitcnt lgkmcnt(0)
	v_mfma_f32_16x16x32_f16 v[120:123], v[222:225], v[178:181], v[120:123]
	v_mfma_f32_16x16x32_f16 v[116:119], v[230:233], v[178:181], v[116:119]
	v_mfma_f32_16x16x32_f16 v[104:107], v[222:225], v[186:189], v[104:107]
	v_mfma_f32_16x16x32_f16 v[100:103], v[230:233], v[186:189], v[100:103]
	v_mfma_f32_16x16x32_f16 v[88:91], v[222:225], v[206:209], v[88:91]
	v_mfma_f32_16x16x32_f16 v[84:87], v[230:233], v[206:209], v[84:87]
	v_mfma_f32_16x16x32_f16 v[72:75], v[222:225], v[214:217], v[72:75]
	v_mfma_f32_16x16x32_f16 v[68:71], v[230:233], v[214:217], v[68:71]
	v_mfma_f32_16x16x32_f16 v[120:123], v[226:229], v[182:185], v[120:123]
	v_mfma_f32_16x16x32_f16 v[116:119], v[234:237], v[182:185], v[116:119]
	v_mfma_f32_16x16x32_f16 v[104:107], v[226:229], v[202:205], v[104:107]
	v_mfma_f32_16x16x32_f16 v[100:103], v[234:237], v[202:205], v[100:103]
	v_mfma_f32_16x16x32_f16 v[88:91], v[226:229], v[210:213], v[88:91]
	v_mfma_f32_16x16x32_f16 v[84:87], v[234:237], v[210:213], v[84:87]
	v_mfma_f32_16x16x32_f16 v[72:75], v[226:229], v[218:221], v[72:75]
	v_mfma_f32_16x16x32_f16 v[68:71], v[234:237], v[218:221], v[68:71]
	s_mov_b32 m0, s48
	v_lshl_add_u64 v[6:7], v[242:243], 0, s[94:95]
	s_barrier
	ds_read_b128 v[178:181], v139 offset:49152
	ds_read_b128 v[182:185], v139 offset:50176
	ds_read_b128 v[186:189], v139 offset:51200
	ds_read_b128 v[202:205], v139 offset:52224
	ds_read_b128 v[206:209], v139 offset:53248
	ds_read_b128 v[210:213], v139 offset:54272
	ds_read_b128 v[214:217], v139 offset:55296
	ds_read_b128 v[218:221], v139 offset:56320
	global_load_lds_dwordx4 v[6:7], off
	s_mov_b32 m0, s49
	v_lshl_add_u64 v[6:7], v[244:245], 0, s[94:95]
	global_load_lds_dwordx4 v[6:7], off
	s_barrier
	s_waitcnt lgkmcnt(0)
	v_mfma_f32_16x16x32_f16 v[64:67], v[162:165], v[178:181], v[64:67]
	v_mfma_f32_16x16x32_f16 v[60:63], v[170:173], v[178:181], v[60:63]
	v_mfma_f32_16x16x32_f16 v[48:51], v[162:165], v[186:189], v[48:51]
	v_mfma_f32_16x16x32_f16 v[44:47], v[170:173], v[186:189], v[44:47]
	v_mfma_f32_16x16x32_f16 v[32:35], v[162:165], v[206:209], v[32:35]
	v_mfma_f32_16x16x32_f16 v[28:31], v[170:173], v[206:209], v[28:31]
	v_mfma_f32_16x16x32_f16 v[16:19], v[162:165], v[214:217], v[16:19]
	v_mfma_f32_16x16x32_f16 v[12:15], v[170:173], v[214:217], v[12:15]
	v_mfma_f32_16x16x32_f16 v[64:67], v[166:169], v[182:185], v[64:67]
	v_mfma_f32_16x16x32_f16 v[60:63], v[174:177], v[182:185], v[60:63]
	v_mfma_f32_16x16x32_f16 v[48:51], v[166:169], v[202:205], v[48:51]
	v_mfma_f32_16x16x32_f16 v[44:47], v[174:177], v[202:205], v[44:47]
	v_mfma_f32_16x16x32_f16 v[32:35], v[166:169], v[210:213], v[32:35]
	v_mfma_f32_16x16x32_f16 v[28:31], v[174:177], v[210:213], v[28:31]
	v_mfma_f32_16x16x32_f16 v[16:19], v[166:169], v[218:221], v[16:19]
	v_mfma_f32_16x16x32_f16 v[12:15], v[174:177], v[218:221], v[12:15]
	s_barrier
	s_add_u32 s26, s26, 0x40080
	s_addc_u32 s27, s27, 0
	s_mov_b32 m0, s50
	v_lshl_add_u64 v[6:7], s[26:27], 0, v[134:135]
	global_load_lds_dwordx4 v[6:7], off
	s_mov_b32 m0, s51
	v_lshl_add_u64 v[6:7], s[26:27], 0, v[132:133]
	global_load_lds_dwordx4 v[6:7], off
	s_waitcnt vmcnt(6)
	s_barrier
	v_mfma_f32_16x16x32_f16 v[56:59], v[222:225], v[178:181], v[56:59]
	v_mfma_f32_16x16x32_f16 v[52:55], v[230:233], v[178:181], v[52:55]
	v_mfma_f32_16x16x32_f16 v[40:43], v[222:225], v[186:189], v[40:43]
	v_mfma_f32_16x16x32_f16 v[36:39], v[230:233], v[186:189], v[36:39]
	v_mfma_f32_16x16x32_f16 v[24:27], v[222:225], v[206:209], v[24:27]
	v_mfma_f32_16x16x32_f16 v[20:23], v[230:233], v[206:209], v[20:23]
	v_mfma_f32_16x16x32_f16 v[6:9], v[222:225], v[214:217], v[8:11]
	v_mfma_f32_16x16x32_f16 v[2:5], v[230:233], v[214:217], v[2:5]
	v_mfma_f32_16x16x32_f16 v[56:59], v[226:229], v[182:185], v[56:59]
	v_mfma_f32_16x16x32_f16 v[52:55], v[234:237], v[182:185], v[52:55]
	v_mfma_f32_16x16x32_f16 v[40:43], v[226:229], v[202:205], v[40:43]
	v_mfma_f32_16x16x32_f16 v[36:39], v[234:237], v[202:205], v[36:39]
	v_mfma_f32_16x16x32_f16 v[24:27], v[226:229], v[210:213], v[24:27]
	v_mfma_f32_16x16x32_f16 v[20:23], v[234:237], v[210:213], v[20:23]
	v_mfma_f32_16x16x32_f16 v[8:11], v[226:229], v[218:221], v[6:9]
	v_mfma_f32_16x16x32_f16 v[4:7], v[234:237], v[218:221], v[2:5]
	s_add_i32 s55, s55, 2
	s_add_u32 s24, s24, 0x100
	s_addc_u32 s25, s25, 0
	s_cmp_gt_u32 s55, 13
	s_barrier
	s_cbranch_scc1 .LBB0_2381

; #define G8_STAGE(bufoff, gbase) do { _Pragma("unroll") for (int _i = 0; _i < 2; ++_i) \
;     __builtin_amdgcn_global_load_lds((const unsigned*)((const char*)(gbase) + voffA[_i]), (LAS unsigned*)(lds + (bufoff) + ldsw + _i * 8192), 16, 0, 0); } while (0)
; #define G8_LDA(dst, b, h) do { _Pragma("unroll") for (int m = 0; m < 4; ++m) _Pragma("unroll") for (int k = 0; k < 2; ++k) dst[m][k] = *(const LAS h16x8*)(lds + G8_SA(b, h) + aoff + m * 2048 + k * 1024); } while (0)
; #define G8_LDB(dst, b, h) do { _Pragma("unroll") for (int n = 0; n < 2; ++n) _Pragma("unroll") for (int k = 0; k < 2; ++k) dst[n][k] = *(const LAS h16x8*)(lds + G8_SB(b, h) + boff + n * 2048 + k * 1024); } while (0)
; #define G8_MMA(ai, bj, At, Bt_) do { __builtin_amdgcn_s_setprio(1); _Pragma("unroll") for (int m = 0; m < 4; ++m) _Pragma("unroll") for (int n = 0; n < 2; ++n) _Pragma("unroll") for (int k = 0; k < 2; ++k) \
;     acc[ai][bj][m][n] = __builtin_amdgcn_mfma_f32_16x16x32_f16(Bt_[n][k], At[m][k], acc[ai][bj][m][n], 0, 0, 0); __builtin_amdgcn_s_setprio(0); } while (0)
; #define G8_WAIT_V(n) asm volatile("s_waitcnt vmcnt(" #n ")" ::: "memory")
; #define G8_WAIT_L(n) asm volatile("s_waitcnt lgkmcnt(" #n ")" ::: "memory")
; #define G8_BAR __builtin_amdgcn_s_barrier()
; template <class Epi>
; __device__ __forceinline__ void gemm_phase(LAS unsigned char* lds, const h16* A, const h16* Bt, int K, const Order& S, const Epi& E) {
;     ...
;     for (int t = 0; t < nt; t += 2) {
;       const bool last = (t == nt - 2);
;       const char* a1 = cA + (size_t)(t + 1) * kstep;
;       const char* a2 = last ? nA : cA + (size_t)(t + 2) * kstep;
;       const char* b2 = last ? nB : cB + (size_t)(t + 2) * kstep;
;       const char* a3 = a2 + kstep;
;       const char* b3 = b2 + kstep;
;       if (Epi::MID_T >= 0 && t == Epi::MID_T) E.mid(acc, ui, wr, fr);
;       G8_LDB(B0, 0, 0); G8_SCHED; G8_LDA(At, 0, 0); G8_STAGE(G8_SA(1, 1), a1 + hstep);
;       G8_WAIT_L(8); G8_BAR; G8_WAIT_L(0); G8_MMA(0, 0, At, B0); G8_BAR; G8_SCHED;
;       G8_LDB(B1, 0, 1); G8_STAGE(G8_SB(0, 0), b2);
;       G8_BAR; G8_WAIT_L(0); G8_MMA(0, 1, At, B1); G8_BAR;
;       G8_LDA(At, 0, 1); G8_STAGE(G8_SA(0, 0), a2);
;       G8_BAR; G8_WAIT_L(0); G8_MMA(1, 0, At, B0); G8_BAR; G8_SCHED;
;       G8_STAGE(G8_SB(0, 1), b2 + hstep);
;       G8_WAIT_V(6); G8_BAR; G8_MMA(1, 1, At, B1); G8_BAR;
.LBB0_2473:
	s_add_u32 s20, s18, 0xfffc0080
	s_addc_u32 s21, s19, -1
	s_cmp_eq_u32 s51, 12
	s_cselect_b32 s23, s13, s21
	s_cselect_b32 s22, s47, s20
	s_cselect_b32 s21, s11, s50
	s_cselect_b32 s20, s48, s49
	v_lshl_add_u64 v[188:189], s[18:19], 0, v[134:135]
	s_add_i32 m0, s27, 0xc000
	ds_read_b128 v[176:179], v139
	ds_read_b128 v[180:183], v139 offset:1024
	ds_read_b128 v[184:187], v139 offset:2048
	ds_read_b128 v[202:205], v139 offset:3072
	ds_read_b128 v[206:209], v139 offset:4096
	ds_read_b128 v[210:213], v139 offset:5120
	ds_read_b128 v[214:217], v139 offset:6144
	ds_read_b128 v[218:221], v139 offset:7168
	global_load_lds_dwordx4 v[188:189], off
	s_add_i32 m0, s27, 0xe000
	v_lshl_add_u64 v[188:189], s[18:19], 0, v[136:137]
	global_load_lds_dwordx4 v[188:189], off
	s_waitcnt lgkmcnt(8)
	s_barrier
	s_waitcnt lgkmcnt(0)
	v_mfma_f32_16x16x32_f16 v[126:129], v[160:163], v[176:179], v[126:129]
	v_mfma_f32_16x16x32_f16 v[122:125], v[168:171], v[176:179], v[122:125]
	v_mfma_f32_16x16x32_f16 v[110:113], v[160:163], v[184:187], v[110:113]
	v_mfma_f32_16x16x32_f16 v[106:109], v[168:171], v[184:187], v[106:109]
	v_mfma_f32_16x16x32_f16 v[94:97], v[160:163], v[206:209], v[94:97]
	v_mfma_f32_16x16x32_f16 v[90:93], v[168:171], v[206:209], v[90:93]
	v_mfma_f32_16x16x32_f16 v[78:81], v[160:163], v[214:217], v[78:81]
	v_mfma_f32_16x16x32_f16 v[74:77], v[168:171], v[214:217], v[74:77]
	v_mfma_f32_16x16x32_f16 v[126:129], v[164:167], v[180:183], v[126:129]
	v_mfma_f32_16x16x32_f16 v[122:125], v[172:175], v[180:183], v[122:125]
	v_mfma_f32_16x16x32_f16 v[110:113], v[164:167], v[202:205], v[110:113]
	v_mfma_f32_16x16x32_f16 v[106:109], v[172:175], v[202:205], v[106:109]
	v_mfma_f32_16x16x32_f16 v[94:97], v[164:167], v[210:213], v[94:97]
	v_mfma_f32_16x16x32_f16 v[90:93], v[172:175], v[210:213], v[90:93]
	v_mfma_f32_16x16x32_f16 v[78:81], v[164:167], v[218:221], v[78:81]
	v_mfma_f32_16x16x32_f16 v[74:77], v[172:175], v[218:221], v[74:77]
	s_barrier
	v_or_b32_e32 v159, 0x14000, v140
	v_add_u32_e32 v188, 0x14400, v140
	ds_read_b128 v[222:225], v159
	ds_read_b128 v[226:229], v188
	v_add_u32_e32 v159, 0x14800, v140
	v_add_u32_e32 v188, 0x14c00, v140
	s_mov_b32 m0, s28
	ds_read_b128 v[230:233], v159
	ds_read_b128 v[234:237], v188
	v_lshl_add_u64 v[188:189], s[20:21], 0, v[132:133]
	global_load_lds_dwordx4 v[188:189], off
	s_mov_b32 m0, s29
	v_lshl_add_u64 v[238:239], s[20:21], 0, v[130:131]
	global_load_lds_dwordx4 v[238:239], off
	s_barrier
	s_waitcnt lgkmcnt(0)
	v_mfma_f32_16x16x32_f16 v[118:121], v[222:225], v[176:179], v[118:121]
	v_mfma_f32_16x16x32_f16 v[114:117], v[230:233], v[176:179], v[114:117]
	v_mfma_f32_16x16x32_f16 v[102:105], v[222:225], v[184:187], v[102:105]
	v_mfma_f32_16x16x32_f16 v[98:101], v[230:233], v[184:187], v[98:101]
	v_mfma_f32_16x16x32_f16 v[86:89], v[222:225], v[206:209], v[86:89]
	v_mfma_f32_16x16x32_f16 v[82:85], v[230:233], v[206:209], v[82:85]
	v_mfma_f32_16x16x32_f16 v[70:73], v[222:225], v[214:217], v[70:73]
	v_mfma_f32_16x16x32_f16 v[66:69], v[230:233], v[214:217], v[66:69]
	v_mfma_f32_16x16x32_f16 v[118:121], v[226:229], v[180:183], v[118:121]
	v_mfma_f32_16x16x32_f16 v[114:117], v[234:237], v[180:183], v[114:117]
	v_mfma_f32_16x16x32_f16 v[102:105], v[226:229], v[202:205], v[102:105]
	v_mfma_f32_16x16x32_f16 v[98:101], v[234:237], v[202:205], v[98:101]
	v_mfma_f32_16x16x32_f16 v[86:89], v[226:229], v[210:213], v[86:89]
	v_mfma_f32_16x16x32_f16 v[82:85], v[234:237], v[210:213], v[82:85]
	v_mfma_f32_16x16x32_f16 v[70:73], v[226:229], v[218:221], v[70:73]
	v_mfma_f32_16x16x32_f16 v[66:69], v[234:237], v[218:221], v[66:69]
	s_mov_b32 m0, s27
	v_lshl_add_u64 v[240:241], s[22:23], 0, v[132:133]
	s_barrier
	ds_read_b128 v[176:179], v139 offset:16384
	ds_read_b128 v[180:183], v139 offset:17408
	ds_read_b128 v[184:187], v139 offset:18432
	ds_read_b128 v[202:205], v139 offset:19456
	ds_read_b128 v[206:209], v139 offset:20480
	ds_read_b128 v[210:213], v139 offset:21504
	ds_read_b128 v[214:217], v139 offset:22528
	ds_read_b128 v[218:221], v139 offset:23552
	global_load_lds_dwordx4 v[240:241], off
	s_mov_b32 m0, s30
	v_lshl_add_u64 v[242:243], s[22:23], 0, v[130:131]
	global_load_lds_dwordx4 v[242:243], off
	s_waitcnt vmcnt(10)
	s_barrier
	s_waitcnt lgkmcnt(0)
	v_mfma_f32_16x16x32_f16 v[62:65], v[160:163], v[176:179], v[62:65]
	v_mfma_f32_16x16x32_f16 v[58:61], v[168:171], v[176:179], v[58:61]
	v_mfma_f32_16x16x32_f16 v[46:49], v[160:163], v[184:187], v[46:49]
	v_mfma_f32_16x16x32_f16 v[42:45], v[168:171], v[184:187], v[42:45]
	v_mfma_f32_16x16x32_f16 v[30:33], v[160:163], v[206:209], v[30:33]
	v_mfma_f32_16x16x32_f16 v[26:29], v[168:171], v[206:209], v[26:29]
	v_mfma_f32_16x16x32_f16 v[14:17], v[160:163], v[214:217], v[14:17]
	v_mfma_f32_16x16x32_f16 v[10:13], v[168:171], v[214:217], v[10:13]
	v_mfma_f32_16x16x32_f16 v[62:65], v[164:167], v[180:183], v[62:65]
	v_mfma_f32_16x16x32_f16 v[58:61], v[172:175], v[180:183], v[58:61]
	v_mfma_f32_16x16x32_f16 v[46:49], v[164:167], v[202:205], v[46:49]
	v_mfma_f32_16x16x32_f16 v[42:45], v[172:175], v[202:205], v[42:45]
	v_mfma_f32_16x16x32_f16 v[30:33], v[164:167], v[210:213], v[30:33]
	v_mfma_f32_16x16x32_f16 v[26:29], v[172:175], v[210:213], v[26:29]
	v_mfma_f32_16x16x32_f16 v[14:17], v[164:167], v[218:221], v[14:17]
	v_mfma_f32_16x16x32_f16 v[10:13], v[172:175], v[218:221], v[10:13]
	s_barrier
	s_add_u32 s52, s20, 0x40000
	s_addc_u32 s53, s21, 0
	s_mov_b32 m0, s31
	v_lshl_add_u64 v[160:161], s[52:53], 0, v[132:133]
	global_load_lds_dwordx4 v[160:161], off
	s_mov_b32 m0, s34
	v_lshl_add_u64 v[160:161], s[52:53], 0, v[130:131]
	global_load_lds_dwordx4 v[160:161], off
	v_or_b32_e32 v159, 0x18000, v140
	v_add_u32_e32 v164, 0x18400, v140
	ds_read_b128 v[160:163], v159
	ds_read_b128 v[164:167], v164
	v_add_u32_e32 v159, 0x18800, v140
	v_add_u32_e32 v172, 0x18c00, v140
	ds_read_b128 v[168:171], v159
	ds_read_b128 v[172:175], v172
	s_waitcnt vmcnt(6)
	s_barrier
; #define G8_STAGE(bufoff, gbase) do { _Pragma("unroll") for (int _i = 0; _i < 2; ++_i) \
;     __builtin_amdgcn_global_load_lds((const unsigned*)((const char*)(gbase) + voffA[_i]), (LAS unsigned*)(lds + (bufoff) + ldsw + _i * 8192), 16, 0, 0); } while (0)
; #define G8_LDA(dst, b, h) do { _Pragma("unroll") for (int m = 0; m < 4; ++m) _Pragma("unroll") for (int k = 0; k < 2; ++k) dst[m][k] = *(const LAS h16x8*)(lds + G8_SA(b, h) + aoff + m * 2048 + k * 1024); } while (0)
; #define G8_LDB(dst, b, h) do { _Pragma("unroll") for (int n = 0; n < 2; ++n) _Pragma("unroll") for (int k = 0; k < 2; ++k) dst[n][k] = *(const LAS h16x8*)(lds + G8_SB(b, h) + boff + n * 2048 + k * 1024); } while (0)
; #define G8_MMA(ai, bj, At, Bt_) do { __builtin_amdgcn_s_setprio(1); _Pragma("unroll") for (int m = 0; m < 4; ++m) _Pragma("unroll") for (int n = 0; n < 2; ++n) _Pragma("unroll") for (int k = 0; k < 2; ++k) \
;     acc[ai][bj][m][n] = __builtin_amdgcn_mfma_f32_16x16x32_f16(Bt_[n][k], At[m][k], acc[ai][bj][m][n], 0, 0, 0); __builtin_amdgcn_s_setprio(0); } while (0)
; #define G8_WAIT_V(n) asm volatile("s_waitcnt vmcnt(" #n ")" ::: "memory")
; #define G8_WAIT_L(n) asm volatile("s_waitcnt lgkmcnt(" #n ")" ::: "memory")
; #define G8_BAR __builtin_amdgcn_s_barrier()
; #define G8_SCHED __builtin_amdgcn_sched_barrier(0)
; template <class Epi>
; __device__ __forceinline__ void gemm_phase(LAS unsigned char* lds, const h16* A, const h16* Bt, int K, const Order& S, const Epi& E) {
;     ...
;       G8_WAIT_V(6); G8_BAR; G8_MMA(1, 1, At, B1); G8_BAR;
;       G8_LDB(B0, 1, 0); G8_SCHED; G8_LDA(At, 1, 0); G8_STAGE(G8_SA(0, 1), a2 + hstep);
;       G8_WAIT_L(8); G8_BAR; G8_WAIT_L(0); G8_MMA(0, 0, At, B0); G8_BAR; G8_SCHED;
;       G8_LDB(B1, 1, 1); G8_STAGE(G8_SB(1, 0), b3);
;       G8_BAR; G8_WAIT_L(0); G8_MMA(0, 1, At, B1); G8_BAR;
;       G8_LDA(At, 1, 1); G8_STAGE(G8_SA(1, 0), a3);
	v_mfma_f32_16x16x32_f16 v[54:57], v[222:225], v[176:179], v[54:57]
	v_mfma_f32_16x16x32_f16 v[50:53], v[230:233], v[176:179], v[50:53]
	v_mfma_f32_16x16x32_f16 v[38:41], v[222:225], v[184:187], v[38:41]
	v_mfma_f32_16x16x32_f16 v[34:37], v[230:233], v[184:187], v[34:37]
	v_mfma_f32_16x16x32_f16 v[22:25], v[222:225], v[206:209], v[22:25]
	v_mfma_f32_16x16x32_f16 v[18:21], v[230:233], v[206:209], v[18:21]
	v_mfma_f32_16x16x32_f16 v[6:9], v[222:225], v[214:217], v[6:9]
	v_mfma_f32_16x16x32_f16 v[2:5], v[230:233], v[214:217], v[2:5]
	v_mfma_f32_16x16x32_f16 v[54:57], v[226:229], v[180:183], v[54:57]
	v_mfma_f32_16x16x32_f16 v[50:53], v[234:237], v[180:183], v[50:53]
	v_mfma_f32_16x16x32_f16 v[38:41], v[226:229], v[202:205], v[38:41]
	v_mfma_f32_16x16x32_f16 v[34:37], v[234:237], v[202:205], v[34:37]
	v_mfma_f32_16x16x32_f16 v[22:25], v[226:229], v[210:213], v[22:25]
	v_mfma_f32_16x16x32_f16 v[18:21], v[234:237], v[210:213], v[18:21]
	v_mfma_f32_16x16x32_f16 v[6:9], v[226:229], v[218:221], v[6:9]
	v_mfma_f32_16x16x32_f16 v[2:5], v[234:237], v[218:221], v[2:5]
	s_barrier
	s_add_u32 s22, s22, 0x40000
	s_addc_u32 s23, s23, 0
	s_mov_b32 m0, s35
	v_lshl_add_u64 v[222:223], s[22:23], 0, v[132:133]
	ds_read_b128 v[176:179], v139 offset:32768
	ds_read_b128 v[180:183], v139 offset:33792
	ds_read_b128 v[184:187], v139 offset:34816
	ds_read_b128 v[202:205], v139 offset:35840
	ds_read_b128 v[206:209], v139 offset:36864
	ds_read_b128 v[210:213], v139 offset:37888
	ds_read_b128 v[214:217], v139 offset:38912
	ds_read_b128 v[218:221], v139 offset:39936
	global_load_lds_dwordx4 v[222:223], off
	s_mov_b32 m0, s36
	v_lshl_add_u64 v[222:223], s[22:23], 0, v[130:131]
	global_load_lds_dwordx4 v[222:223], off
	s_waitcnt lgkmcnt(8)
	s_barrier
	s_waitcnt lgkmcnt(0)
	v_mfma_f32_16x16x32_f16 v[126:129], v[160:163], v[176:179], v[126:129]
	v_mfma_f32_16x16x32_f16 v[122:125], v[168:171], v[176:179], v[122:125]
	v_mfma_f32_16x16x32_f16 v[110:113], v[160:163], v[184:187], v[110:113]
	v_mfma_f32_16x16x32_f16 v[106:109], v[168:171], v[184:187], v[106:109]
	v_mfma_f32_16x16x32_f16 v[94:97], v[160:163], v[206:209], v[94:97]
	v_mfma_f32_16x16x32_f16 v[90:93], v[168:171], v[206:209], v[90:93]
	v_mfma_f32_16x16x32_f16 v[78:81], v[160:163], v[214:217], v[78:81]
	v_mfma_f32_16x16x32_f16 v[74:77], v[168:171], v[214:217], v[74:77]
	v_mfma_f32_16x16x32_f16 v[126:129], v[164:167], v[180:183], v[126:129]
	v_mfma_f32_16x16x32_f16 v[122:125], v[172:175], v[180:183], v[122:125]
	v_mfma_f32_16x16x32_f16 v[110:113], v[164:167], v[202:205], v[110:113]
	v_mfma_f32_16x16x32_f16 v[106:109], v[172:175], v[202:205], v[106:109]
	v_mfma_f32_16x16x32_f16 v[94:97], v[164:167], v[210:213], v[94:97]
	v_mfma_f32_16x16x32_f16 v[90:93], v[172:175], v[210:213], v[90:93]
	v_mfma_f32_16x16x32_f16 v[78:81], v[164:167], v[218:221], v[78:81]
	v_mfma_f32_16x16x32_f16 v[74:77], v[172:175], v[218:221], v[74:77]
	s_barrier
	v_or_b32_e32 v159, 0x1c000, v140
	s_mov_b32 m0, s37
	v_add_u32_e32 v195, 0x1c400, v140
	ds_read_b128 v[222:225], v159
	ds_read_b128 v[226:229], v195
	v_add_u32_e32 v159, 0x1c800, v140
	v_lshl_add_u64 v[188:189], v[188:189], 0, s[94:95]
	v_add_u32_e32 v195, 0x1cc00, v140
	ds_read_b128 v[230:233], v159
	ds_read_b128 v[234:237], v195
	global_load_lds_dwordx4 v[188:189], off
	s_mov_b32 m0, s38
	v_lshl_add_u64 v[188:189], v[238:239], 0, s[94:95]
	global_load_lds_dwordx4 v[188:189], off
	s_barrier
	s_waitcnt lgkmcnt(0)
	v_mfma_f32_16x16x32_f16 v[118:121], v[222:225], v[176:179], v[118:121]
	v_mfma_f32_16x16x32_f16 v[114:117], v[230:233], v[176:179], v[114:117]
	v_mfma_f32_16x16x32_f16 v[102:105], v[222:225], v[184:187], v[102:105]
	v_mfma_f32_16x16x32_f16 v[98:101], v[230:233], v[184:187], v[98:101]
	v_mfma_f32_16x16x32_f16 v[86:89], v[222:225], v[206:209], v[86:89]
	v_mfma_f32_16x16x32_f16 v[82:85], v[230:233], v[206:209], v[82:85]
	v_mfma_f32_16x16x32_f16 v[70:73], v[222:225], v[214:217], v[70:73]
	v_mfma_f32_16x16x32_f16 v[66:69], v[230:233], v[214:217], v[66:69]
	v_mfma_f32_16x16x32_f16 v[118:121], v[226:229], v[180:183], v[118:121]
	v_mfma_f32_16x16x32_f16 v[114:117], v[234:237], v[180:183], v[114:117]
	v_mfma_f32_16x16x32_f16 v[102:105], v[226:229], v[202:205], v[102:105]
	v_mfma_f32_16x16x32_f16 v[98:101], v[234:237], v[202:205], v[98:101]
	v_mfma_f32_16x16x32_f16 v[86:89], v[226:229], v[210:213], v[86:89]
	v_mfma_f32_16x16x32_f16 v[82:85], v[234:237], v[210:213], v[82:85]
	v_mfma_f32_16x16x32_f16 v[70:73], v[226:229], v[218:221], v[70:73]
	v_mfma_f32_16x16x32_f16 v[66:69], v[234:237], v[218:221], v[66:69]
	s_mov_b32 m0, s39
	v_lshl_add_u64 v[188:189], v[240:241], 0, s[94:95]
	s_barrier
	ds_read_b128 v[176:179], v139 offset:49152
	ds_read_b128 v[180:183], v139 offset:50176
	ds_read_b128 v[184:187], v139 offset:51200
	ds_read_b128 v[202:205], v139 offset:52224
	ds_read_b128 v[206:209], v139 offset:53248
	ds_read_b128 v[210:213], v139 offset:54272
	ds_read_b128 v[214:217], v139 offset:55296
	ds_read_b128 v[218:221], v139 offset:56320
	global_load_lds_dwordx4 v[188:189], off
	s_mov_b32 m0, s40
	v_lshl_add_u64 v[188:189], v[242:243], 0, s[94:95]
	global_load_lds_dwordx4 v[188:189], off
	s_waitcnt vmcnt(10)
	s_barrier
; #define G8_STAGE(bufoff, gbase) do { _Pragma("unroll") for (int _i = 0; _i < 2; ++_i) \
;     __builtin_amdgcn_global_load_lds((const unsigned*)((const char*)(gbase) + voffA[_i]), (LAS unsigned*)(lds + (bufoff) + ldsw + _i * 8192), 16, 0, 0); } while (0)
; #define G8_MMA(ai, bj, At, Bt_) do { __builtin_amdgcn_s_setprio(1); _Pragma("unroll") for (int m = 0; m < 4; ++m) _Pragma("unroll") for (int n = 0; n < 2; ++n) _Pragma("unroll") for (int k = 0; k < 2; ++k) \
;     acc[ai][bj][m][n] = __builtin_amdgcn_mfma_f32_16x16x32_f16(Bt_[n][k], At[m][k], acc[ai][bj][m][n], 0, 0, 0); __builtin_amdgcn_s_setprio(0); } while (0)
; #define G8_WAIT_V(n) asm volatile("s_waitcnt vmcnt(" #n ")" ::: "memory")
; #define G8_WAIT_L(n) asm volatile("s_waitcnt lgkmcnt(" #n ")" ::: "memory")
; #define G8_BAR __builtin_amdgcn_s_barrier()
; #define G8_SCHED __builtin_amdgcn_sched_barrier(0)
; template <class Epi>
; __device__ __forceinline__ void gemm_phase(LAS unsigned char* lds, const h16* A, const h16* Bt, int K, const Order& S, const Epi& E) {
;     ...
;       G8_BAR; G8_WAIT_L(0); G8_MMA(1, 0, At, B0); G8_BAR; G8_SCHED;
;       G8_STAGE(G8_SB(1, 1), b3 + hstep);
;       G8_WAIT_V(6); G8_BAR; G8_MMA(1, 1, At, B1); G8_BAR;
;   __device__ __forceinline__ void operator()(const f32x4 (&acc)[2][2][4][2], const g8::Unit& u, int ui, int wr, int wc, int fr, int fq) const {
; #pragma unroll
;     for (int ai = 0; ai < 2; ++ai)
; #pragma unroll
;       for (int m = 0; m < 4; ++m) {
;         const int rl = 128 * ai + 64 * wr + 16 * m + fr;
;         const float r = rsl[ui * 256 + rl];
;         h16* rowp = hid + (size_t)(u.pm * 256 + rl) * DFF + 256 * u.pn + 32 * wc + 8 * fq;
; #pragma unroll
;         for (int bj = 0; bj < 2; ++bj) {
;           f32x4 v[2];
; #pragma unroll
;           for (int n = 0; n < 2; ++n) {
;             v[n] = acc[ai][bj][m][n] * r;
; #pragma unroll
;             for (int j = 0; j < 4; ++j) { const float t = fmaxf(v[n][j], 0.f); v[n][j] = t * t; }
;           }
;           __builtin_nontemporal_store(pack8(v[0], v[1]), (h16x8*)(rowp + 128 * bj));
	s_waitcnt lgkmcnt(0)
	v_mfma_f32_16x16x32_f16 v[62:65], v[160:163], v[176:179], v[62:65]
	v_mfma_f32_16x16x32_f16 v[58:61], v[168:171], v[176:179], v[58:61]
	v_mfma_f32_16x16x32_f16 v[46:49], v[160:163], v[184:187], v[46:49]
	v_mfma_f32_16x16x32_f16 v[42:45], v[168:171], v[184:187], v[42:45]
	v_mfma_f32_16x16x32_f16 v[30:33], v[160:163], v[206:209], v[30:33]
	v_mfma_f32_16x16x32_f16 v[26:29], v[168:171], v[206:209], v[26:29]
	v_mfma_f32_16x16x32_f16 v[14:17], v[160:163], v[214:217], v[14:17]
	v_mfma_f32_16x16x32_f16 v[10:13], v[168:171], v[214:217], v[10:13]
	v_mfma_f32_16x16x32_f16 v[62:65], v[164:167], v[180:183], v[62:65]
	v_mfma_f32_16x16x32_f16 v[58:61], v[172:175], v[180:183], v[58:61]
	v_mfma_f32_16x16x32_f16 v[46:49], v[164:167], v[202:205], v[46:49]
	v_mfma_f32_16x16x32_f16 v[42:45], v[172:175], v[202:205], v[42:45]
	v_mfma_f32_16x16x32_f16 v[30:33], v[164:167], v[210:213], v[30:33]
	v_mfma_f32_16x16x32_f16 v[26:29], v[172:175], v[210:213], v[26:29]
	v_mfma_f32_16x16x32_f16 v[14:17], v[164:167], v[218:221], v[14:17]
	v_mfma_f32_16x16x32_f16 v[10:13], v[172:175], v[218:221], v[10:13]
	s_barrier
	s_add_u32 s20, s20, 0x40080
	s_addc_u32 s21, s21, 0
	s_mov_b32 m0, s41
	v_lshl_add_u64 v[160:161], s[20:21], 0, v[132:133]
	global_load_lds_dwordx4 v[160:161], off
	s_mov_b32 m0, s42
	v_lshl_add_u64 v[160:161], s[20:21], 0, v[130:131]
	global_load_lds_dwordx4 v[160:161], off
	v_or_b32_e32 v159, 0x10000, v140
	v_add_u32_e32 v164, 0x10400, v140
	ds_read_b128 v[160:163], v159
	ds_read_b128 v[164:167], v164
	v_add_u32_e32 v159, 0x10800, v140
	v_add_u32_e32 v172, 0x10c00, v140
	ds_read_b128 v[168:171], v159
	ds_read_b128 v[172:175], v172
	s_waitcnt vmcnt(6)
	s_barrier
	v_mfma_f32_16x16x32_f16 v[54:57], v[222:225], v[176:179], v[54:57]
	v_mfma_f32_16x16x32_f16 v[50:53], v[230:233], v[176:179], v[50:53]
	v_mfma_f32_16x16x32_f16 v[38:41], v[222:225], v[184:187], v[38:41]
	v_mfma_f32_16x16x32_f16 v[34:37], v[230:233], v[184:187], v[34:37]
	v_mfma_f32_16x16x32_f16 v[22:25], v[222:225], v[206:209], v[22:25]
	v_mfma_f32_16x16x32_f16 v[18:21], v[230:233], v[206:209], v[18:21]
	v_mfma_f32_16x16x32_f16 v[6:9], v[222:225], v[214:217], v[6:9]
	v_mfma_f32_16x16x32_f16 v[2:5], v[230:233], v[214:217], v[2:5]
	v_mfma_f32_16x16x32_f16 v[54:57], v[226:229], v[180:183], v[54:57]
	v_mfma_f32_16x16x32_f16 v[50:53], v[234:237], v[180:183], v[50:53]
	v_mfma_f32_16x16x32_f16 v[38:41], v[226:229], v[202:205], v[38:41]
	v_mfma_f32_16x16x32_f16 v[34:37], v[234:237], v[202:205], v[34:37]
	v_mfma_f32_16x16x32_f16 v[22:25], v[226:229], v[210:213], v[22:25]
	v_mfma_f32_16x16x32_f16 v[18:21], v[234:237], v[210:213], v[18:21]
	v_mfma_f32_16x16x32_f16 v[6:9], v[226:229], v[218:221], v[6:9]
	v_mfma_f32_16x16x32_f16 v[2:5], v[234:237], v[218:221], v[2:5]
	s_add_i32 s51, s51, 2
	s_add_u32 s18, s18, 0x100
	s_addc_u32 s19, s19, 0
	s_add_u32 s49, s49, 0x100
	s_addc_u32 s50, s50, 0
	s_cmp_gt_u32 s51, 13
	s_barrier
	s_cbranch_scc0 .LBB0_2473
	s_waitcnt lgkmcnt(0)
	v_lshl_add_u32 v159, s44, 10, v158
	s_waitcnt vmcnt(0)
	ds_read2_b32 v[160:161], v159 offset1:16
	s_lshl_b32 s11, s46, 8
	v_add_u32_e32 v162, s11, v138
	s_lshl_b32 s18, s45, 8
	v_ashrrev_i32_e32 v163, 31, v162
	s_waitcnt lgkmcnt(0)
	v_pk_mul_f32 v[128:129], v[128:129], v[160:161] op_sel_hi:[1,0]
	v_pk_mul_f32 v[126:127], v[126:127], v[160:161] op_sel_hi:[1,0]
	v_pk_mul_f32 v[122:123], v[122:123], v[160:161] op_sel_hi:[1,0]
	v_max_f32_e32 v166, 0, v126
	v_max_f32_e32 v126, 0, v127
	v_max_f32_e32 v127, 0, v128
	v_max_f32_e32 v128, 0, v129
	v_pk_mul_f32 v[124:125], v[124:125], v[160:161] op_sel_hi:[1,0]
	v_max_f32_e32 v129, 0, v122
	v_max_f32_e32 v164, 0, v123
	v_pk_mul_f32 v[122:123], v[126:127], v[126:127]
	v_max_f32_e32 v165, 0, v124
	v_fma_mixlo_f16 v124, v166, v166, 0
	v_cvt_pk_f16_f32 v123, v122, v123
	s_ashr_i32 s19, s18, 31
	v_lshlrev_b64 v[162:163], 13, v[162:163]
	v_max_f32_e32 v167, 0, v125
	v_pack_b32_f16 v122, v124, v123
	v_pk_mul_f32 v[124:125], v[128:129], v[128:129]
	v_lshl_add_u64 v[162:163], s[0:1], 0, v[162:163]
	s_lshl_b64 s[18:19], s[18:19], 1
	v_cvt_pk_f16_f32 v126, v124, v125
	v_pk_mul_f32 v[124:125], v[164:165], v[164:165]
	v_lshl_add_u64 v[162:163], v[162:163], 0, s[18:19]
	v_cvt_pk_f16_f32 v125, v124, v125
	v_lshl_add_u64 v[162:163], v[162:163], 0, s[92:93]
	v_alignbit_b32 v124, v125, v126, 16
	v_lshrrev_b32_e32 v125, 16, v125
	v_lshl_add_u64 v[162:163], v[162:163], 0, v[0:1]
	v_alignbit_b32 v123, v126, v123, 16
	v_fma_mixhi_f16 v125, v167, v167, 0
	v_pk_mul_f32 v[120:121], v[120:121], v[160:161] op_sel_hi:[1,0]
	v_pk_mul_f32 v[118:119], v[118:119], v[160:161] op_sel_hi:[1,0]
	global_store_dwordx4 v[162:163], v[122:125], off nt
	v_pk_mul_f32 v[114:115], v[114:115], v[160:161] op_sel_hi:[1,0]
	v_pk_mul_f32 v[116:117], v[116:117], v[160:161] op_sel_hi:[1,0]
	v_max_f32_e32 v124, 0, v118
	v_max_f32_e32 v118, 0, v119
	v_max_f32_e32 v119, 0, v120
	v_max_f32_e32 v120, 0, v121
	v_max_f32_e32 v121, 0, v114
	v_max_f32_e32 v122, 0, v115
	v_pk_mul_f32 v[114:115], v[118:119], v[118:119]
	v_max_f32_e32 v123, 0, v116
	v_fma_mixlo_f16 v116, v124, v124, 0
	v_cvt_pk_f16_f32 v115, v114, v115
	v_max_f32_e32 v125, 0, v117
	v_pack_b32_f16 v114, v116, v115
	v_pk_mul_f32 v[116:117], v[120:121], v[120:121]
	s_and_b64 vcc, exec, s[6:7]
	v_cvt_pk_f16_f32 v118, v116, v117
	v_pk_mul_f32 v[116:117], v[122:123], v[122:123]
	v_alignbit_b32 v115, v118, v115, 16
	v_cvt_pk_f16_f32 v117, v116, v117
	v_alignbit_b32 v116, v117, v118, 16
	v_lshrrev_b32_e32 v117, 16, v117
	v_fma_mixhi_f16 v117, v125, v125, 0
	global_store_dwordx4 v[162:163], v[114:117], off offset:256 nt
	s_mov_b32 s45, s10
	s_mov_b32 s46, s12
	v_mov_b32_e32 v116, v161
;   __device__ __forceinline__ void operator()(const f32x4 (&acc)[2][2][4][2], const g8::Unit& u, int ui, int wr, int wc, int fr, int fq) const {
; #pragma unroll
;     for (int ai = 0; ai < 2; ++ai)
; #pragma unroll
;       for (int m = 0; m < 4; ++m) {
;         const int rl = 128 * ai + 64 * wr + 16 * m + fr;
;         const float r = rsl[ui * 256 + rl];
;         h16* rowp = hid + (size_t)(u.pm * 256 + rl) * DFF + 256 * u.pn + 32 * wc + 8 * fq;
; #pragma unroll
;         for (int bj = 0; bj < 2; ++bj) {
;           f32x4 v[2];
; #pragma unroll
;           for (int n = 0; n < 2; ++n) {
;             v[n] = acc[ai][bj][m][n] * r;
; #pragma unroll
;             for (int j = 0; j < 4; ++j) { const float t = fmaxf(v[n][j], 0.f); v[n][j] = t * t; }
;           }
;           __builtin_nontemporal_store(pack8(v[0], v[1]), (h16x8*)(rowp + 128 * bj));
	v_pk_mul_f32 v[110:111], v[110:111], v[116:117] op_sel_hi:[1,0]
	v_pk_mul_f32 v[112:113], v[112:113], v[116:117] op_sel_hi:[1,0]
	v_max_f32_e32 v117, 0, v110
	v_max_f32_e32 v110, 0, v111
	v_max_f32_e32 v111, 0, v112
	v_pk_mul_f32 v[106:107], v[106:107], v[116:117] op_sel_hi:[1,0]
	v_add_u32_e32 v114, s11, v141
	v_max_f32_e32 v112, 0, v113
	v_pk_mul_f32 v[108:109], v[108:109], v[116:117] op_sel_hi:[1,0]
	v_max_f32_e32 v113, 0, v106
	v_max_f32_e32 v118, 0, v107
	v_pk_mul_f32 v[106:107], v[110:111], v[110:111]
	v_ashrrev_i32_e32 v115, 31, v114
	v_max_f32_e32 v119, 0, v108
	v_fma_mixlo_f16 v108, v117, v117, 0
	v_cvt_pk_f16_f32 v107, v106, v107
	v_lshlrev_b64 v[114:115], 13, v[114:115]
	v_max_f32_e32 v120, 0, v109
	v_pack_b32_f16 v106, v108, v107
	v_pk_mul_f32 v[108:109], v[112:113], v[112:113]
	v_lshl_add_u64 v[114:115], s[0:1], 0, v[114:115]
	v_cvt_pk_f16_f32 v110, v108, v109
	v_pk_mul_f32 v[108:109], v[118:119], v[118:119]
	v_lshl_add_u64 v[114:115], v[114:115], 0, s[18:19]
	v_cvt_pk_f16_f32 v109, v108, v109
	v_lshl_add_u64 v[114:115], v[114:115], 0, s[92:93]
	v_alignbit_b32 v108, v109, v110, 16
	v_lshrrev_b32_e32 v109, 16, v109
	v_lshl_add_u64 v[114:115], v[114:115], 0, v[0:1]
	v_alignbit_b32 v107, v110, v107, 16
	v_fma_mixhi_f16 v109, v120, v120, 0
	v_pk_mul_f32 v[104:105], v[104:105], v[116:117] op_sel_hi:[1,0]
	v_pk_mul_f32 v[102:103], v[102:103], v[116:117] op_sel_hi:[1,0]
	global_store_dwordx4 v[114:115], v[106:109], off nt
	v_pk_mul_f32 v[98:99], v[98:99], v[116:117] op_sel_hi:[1,0]
	v_pk_mul_f32 v[100:101], v[100:101], v[116:117] op_sel_hi:[1,0]
	v_max_f32_e32 v108, 0, v102
	v_max_f32_e32 v102, 0, v103
	v_max_f32_e32 v103, 0, v104
	v_max_f32_e32 v104, 0, v105
	v_max_f32_e32 v105, 0, v98
	v_max_f32_e32 v106, 0, v99
	v_pk_mul_f32 v[98:99], v[102:103], v[102:103]
	v_max_f32_e32 v107, 0, v100
	v_fma_mixlo_f16 v100, v108, v108, 0
	v_cvt_pk_f16_f32 v99, v98, v99
	v_max_f32_e32 v109, 0, v101
	v_pack_b32_f16 v98, v100, v99
	v_pk_mul_f32 v[100:101], v[104:105], v[104:105]
	s_mov_b64 s[20:21], s[16:17]
	v_cvt_pk_f16_f32 v102, v100, v101
	v_pk_mul_f32 v[100:101], v[106:107], v[106:107]
	v_alignbit_b32 v99, v102, v99, 16
	v_cvt_pk_f16_f32 v101, v100, v101
	v_alignbit_b32 v100, v101, v102, 16
	v_lshrrev_b32_e32 v101, 16, v101
	v_fma_mixhi_f16 v101, v109, v109, 0
	global_store_dwordx4 v[114:115], v[98:101], off offset:256 nt
	ds_read2_b32 v[98:99], v159 offset0:32 offset1:48
	s_mov_b32 s44, s43
	v_add_u32_e32 v100, s11, v152
	v_ashrrev_i32_e32 v101, 31, v100
	v_lshlrev_b64 v[100:101], 13, v[100:101]
	s_waitcnt lgkmcnt(0)
	v_pk_mul_f32 v[96:97], v[96:97], v[98:99] op_sel_hi:[1,0]
	v_pk_mul_f32 v[94:95], v[94:95], v[98:99] op_sel_hi:[1,0]
	v_pk_mul_f32 v[90:91], v[90:91], v[98:99] op_sel_hi:[1,0]
	v_max_f32_e32 v104, 0, v94
	v_max_f32_e32 v94, 0, v95
	v_max_f32_e32 v95, 0, v96
	v_max_f32_e32 v96, 0, v97
	v_pk_mul_f32 v[92:93], v[92:93], v[98:99] op_sel_hi:[1,0]
	v_max_f32_e32 v97, 0, v90
	v_max_f32_e32 v102, 0, v91
	v_pk_mul_f32 v[90:91], v[94:95], v[94:95]
	v_max_f32_e32 v103, 0, v92
	v_fma_mixlo_f16 v92, v104, v104, 0
	v_cvt_pk_f16_f32 v91, v90, v91
	v_max_f32_e32 v105, 0, v93
	v_pack_b32_f16 v90, v92, v91
	v_pk_mul_f32 v[92:93], v[96:97], v[96:97]
	v_lshl_add_u64 v[100:101], s[0:1], 0, v[100:101]
	v_cvt_pk_f16_f32 v94, v92, v93
	v_pk_mul_f32 v[92:93], v[102:103], v[102:103]
	v_lshl_add_u64 v[100:101], v[100:101], 0, s[18:19]
	v_cvt_pk_f16_f32 v93, v92, v93
	v_lshl_add_u64 v[100:101], v[100:101], 0, s[92:93]
	v_alignbit_b32 v92, v93, v94, 16
	v_lshrrev_b32_e32 v93, 16, v93
	v_lshl_add_u64 v[100:101], v[100:101], 0, v[0:1]
	v_alignbit_b32 v91, v94, v91, 16
	v_fma_mixhi_f16 v93, v105, v105, 0
	v_pk_mul_f32 v[88:89], v[88:89], v[98:99] op_sel_hi:[1,0]
	v_pk_mul_f32 v[86:87], v[86:87], v[98:99] op_sel_hi:[1,0]
	global_store_dwordx4 v[100:101], v[90:93], off nt
	v_pk_mul_f32 v[82:83], v[82:83], v[98:99] op_sel_hi:[1,0]
	v_pk_mul_f32 v[84:85], v[84:85], v[98:99] op_sel_hi:[1,0]
	v_max_f32_e32 v92, 0, v86
	v_max_f32_e32 v86, 0, v87
	v_max_f32_e32 v87, 0, v88
	v_max_f32_e32 v88, 0, v89
	v_max_f32_e32 v89, 0, v82
	v_max_f32_e32 v90, 0, v83
	v_pk_mul_f32 v[82:83], v[86:87], v[86:87]
	v_max_f32_e32 v91, 0, v84
	v_fma_mixlo_f16 v84, v92, v92, 0
	v_cvt_pk_f16_f32 v83, v82, v83
	v_max_f32_e32 v93, 0, v85
	v_pack_b32_f16 v82, v84, v83
	v_pk_mul_f32 v[84:85], v[88:89], v[88:89]
	s_nop 0
	v_cvt_pk_f16_f32 v86, v84, v85
	v_pk_mul_f32 v[84:85], v[90:91], v[90:91]
	v_alignbit_b32 v83, v86, v83, 16
	v_cvt_pk_f16_f32 v85, v84, v85
	v_alignbit_b32 v84, v85, v86, 16
	v_lshrrev_b32_e32 v85, 16, v85
	v_fma_mixhi_f16 v85, v93, v93, 0
	global_store_dwordx4 v[100:101], v[82:85], off offset:256 nt
	s_nop 1
	v_mov_b32_e32 v84, v99
	v_pk_mul_f32 v[78:79], v[78:79], v[84:85] op_sel_hi:[1,0]
	v_pk_mul_f32 v[80:81], v[80:81], v[84:85] op_sel_hi:[1,0]
	v_max_f32_e32 v85, 0, v78
	v_max_f32_e32 v78, 0, v79
	v_max_f32_e32 v79, 0, v80
	v_pk_mul_f32 v[74:75], v[74:75], v[84:85] op_sel_hi:[1,0]
	v_add_u32_e32 v82, s11, v153
	v_max_f32_e32 v80, 0, v81
	v_pk_mul_f32 v[76:77], v[76:77], v[84:85] op_sel_hi:[1,0]
	v_max_f32_e32 v81, 0, v74
	v_max_f32_e32 v86, 0, v75
	v_pk_mul_f32 v[74:75], v[78:79], v[78:79]
	v_ashrrev_i32_e32 v83, 31, v82
	v_max_f32_e32 v87, 0, v76
	v_fma_mixlo_f16 v76, v85, v85, 0
	v_cvt_pk_f16_f32 v75, v74, v75
	v_lshlrev_b64 v[82:83], 13, v[82:83]
	v_max_f32_e32 v88, 0, v77
	v_pack_b32_f16 v74, v76, v75
	v_pk_mul_f32 v[76:77], v[80:81], v[80:81]
	v_lshl_add_u64 v[82:83], s[0:1], 0, v[82:83]
	v_cvt_pk_f16_f32 v78, v76, v77
	v_pk_mul_f32 v[76:77], v[86:87], v[86:87]
	v_lshl_add_u64 v[82:83], v[82:83], 0, s[18:19]
	v_cvt_pk_f16_f32 v77, v76, v77
	v_lshl_add_u64 v[82:83], v[82:83], 0, s[92:93]
	v_alignbit_b32 v76, v77, v78, 16
	v_lshrrev_b32_e32 v77, 16, v77
	v_lshl_add_u64 v[82:83], v[82:83], 0, v[0:1]
	v_alignbit_b32 v75, v78, v75, 16
	v_fma_mixhi_f16 v77, v88, v88, 0
	v_pk_mul_f32 v[72:73], v[72:73], v[84:85] op_sel_hi:[1,0]
	v_pk_mul_f32 v[70:71], v[70:71], v[84:85] op_sel_hi:[1,0]
	global_store_dwordx4 v[82:83], v[74:77], off nt
	v_pk_mul_f32 v[66:67], v[66:67], v[84:85] op_sel_hi:[1,0]
	v_pk_mul_f32 v[68:69], v[68:69], v[84:85] op_sel_hi:[1,0]
	v_max_f32_e32 v76, 0, v70
	v_max_f32_e32 v70, 0, v71
	v_max_f32_e32 v71, 0, v72
	v_max_f32_e32 v72, 0, v73
	v_max_f32_e32 v73, 0, v66
	v_max_f32_e32 v74, 0, v67
	v_pk_mul_f32 v[66:67], v[70:71], v[70:71]
	v_max_f32_e32 v75, 0, v68
	v_fma_mixlo_f16 v68, v76, v76, 0
	v_cvt_pk_f16_f32 v67, v66, v67
	v_max_f32_e32 v77, 0, v69
	v_pack_b32_f16 v66, v68, v67
	v_pk_mul_f32 v[68:69], v[72:73], v[72:73]
	s_nop 0
	v_cvt_pk_f16_f32 v70, v68, v69
	v_pk_mul_f32 v[68:69], v[74:75], v[74:75]
	v_alignbit_b32 v67, v70, v67, 16
	v_cvt_pk_f16_f32 v69, v68, v69
	v_alignbit_b32 v68, v69, v70, 16
	v_lshrrev_b32_e32 v69, 16, v69
	v_fma_mixhi_f16 v69, v77, v77, 0
	global_store_dwordx4 v[82:83], v[66:69], off offset:256 nt
	ds_read2_b32 v[66:67], v159 offset0:128 offset1:144
	s_waitcnt lgkmcnt(0)
;   __device__ __forceinline__ void operator()(const f32x4 (&acc)[2][2][4][2], const g8::Unit& u, int ui, int wr, int wc, int fr, int fq) const {
; #pragma unroll
;     for (int ai = 0; ai < 2; ++ai)
; #pragma unroll
;       for (int m = 0; m < 4; ++m) {
;         const int rl = 128 * ai + 64 * wr + 16 * m + fr;
;         const float r = rsl[ui * 256 + rl];
;         h16* rowp = hid + (size_t)(u.pm * 256 + rl) * DFF + 256 * u.pn + 32 * wc + 8 * fq;
; #pragma unroll
;         for (int bj = 0; bj < 2; ++bj) {
;           f32x4 v[2];
; #pragma unroll
;           for (int n = 0; n < 2; ++n) {
;             v[n] = acc[ai][bj][m][n] * r;
; #pragma unroll
;             for (int j = 0; j < 4; ++j) { const float t = fmaxf(v[n][j], 0.f); v[n][j] = t * t; }
;           }
;           __builtin_nontemporal_store(pack8(v[0], v[1]), (h16x8*)(rowp + 128 * bj));
	v_pk_mul_f32 v[64:65], v[64:65], v[66:67] op_sel_hi:[1,0]
	v_pk_mul_f32 v[62:63], v[62:63], v[66:67] op_sel_hi:[1,0]
	v_pk_mul_f32 v[58:59], v[58:59], v[66:67] op_sel_hi:[1,0]
	v_max_f32_e32 v72, 0, v62
	v_max_f32_e32 v62, 0, v63
	v_max_f32_e32 v63, 0, v64
	v_add_u32_e32 v68, s11, v154
	v_max_f32_e32 v64, 0, v65
	v_pk_mul_f32 v[60:61], v[60:61], v[66:67] op_sel_hi:[1,0]
	v_max_f32_e32 v65, 0, v58
	v_max_f32_e32 v70, 0, v59
	v_pk_mul_f32 v[58:59], v[62:63], v[62:63]
	v_ashrrev_i32_e32 v69, 31, v68
	v_max_f32_e32 v71, 0, v60
	v_fma_mixlo_f16 v60, v72, v72, 0
	v_cvt_pk_f16_f32 v59, v58, v59
	v_lshlrev_b64 v[68:69], 13, v[68:69]
	v_max_f32_e32 v73, 0, v61
	v_pack_b32_f16 v58, v60, v59
	v_pk_mul_f32 v[60:61], v[64:65], v[64:65]
	v_lshl_add_u64 v[68:69], s[0:1], 0, v[68:69]
	v_cvt_pk_f16_f32 v62, v60, v61
	v_pk_mul_f32 v[60:61], v[70:71], v[70:71]
	v_lshl_add_u64 v[68:69], v[68:69], 0, s[18:19]
	v_cvt_pk_f16_f32 v61, v60, v61
	v_lshl_add_u64 v[68:69], v[68:69], 0, s[92:93]
	v_alignbit_b32 v60, v61, v62, 16
	v_lshrrev_b32_e32 v61, 16, v61
	v_lshl_add_u64 v[68:69], v[68:69], 0, v[0:1]
	v_alignbit_b32 v59, v62, v59, 16
	v_fma_mixhi_f16 v61, v73, v73, 0
	v_pk_mul_f32 v[56:57], v[56:57], v[66:67] op_sel_hi:[1,0]
	v_pk_mul_f32 v[54:55], v[54:55], v[66:67] op_sel_hi:[1,0]
	global_store_dwordx4 v[68:69], v[58:61], off nt
	v_pk_mul_f32 v[50:51], v[50:51], v[66:67] op_sel_hi:[1,0]
	v_pk_mul_f32 v[52:53], v[52:53], v[66:67] op_sel_hi:[1,0]
	v_max_f32_e32 v60, 0, v54
	v_max_f32_e32 v54, 0, v55
	v_max_f32_e32 v55, 0, v56
	v_max_f32_e32 v56, 0, v57
	v_max_f32_e32 v57, 0, v50
	v_max_f32_e32 v58, 0, v51
	v_pk_mul_f32 v[50:51], v[54:55], v[54:55]
	v_max_f32_e32 v59, 0, v52
	v_fma_mixlo_f16 v52, v60, v60, 0
	v_cvt_pk_f16_f32 v51, v50, v51
	v_max_f32_e32 v61, 0, v53
	v_pack_b32_f16 v50, v52, v51
	v_pk_mul_f32 v[52:53], v[56:57], v[56:57]
	s_nop 0
	v_cvt_pk_f16_f32 v54, v52, v53
	v_pk_mul_f32 v[52:53], v[58:59], v[58:59]
	v_alignbit_b32 v51, v54, v51, 16
	v_cvt_pk_f16_f32 v53, v52, v53
	v_alignbit_b32 v52, v53, v54, 16
	v_lshrrev_b32_e32 v53, 16, v53
	v_fma_mixhi_f16 v53, v61, v61, 0
	global_store_dwordx4 v[68:69], v[50:53], off offset:256 nt
	s_nop 1
	v_mov_b32_e32 v52, v67
	v_pk_mul_f32 v[46:47], v[46:47], v[52:53] op_sel_hi:[1,0]
	v_pk_mul_f32 v[48:49], v[48:49], v[52:53] op_sel_hi:[1,0]
	v_max_f32_e32 v53, 0, v46
	v_max_f32_e32 v46, 0, v47
	v_max_f32_e32 v47, 0, v48
	v_pk_mul_f32 v[42:43], v[42:43], v[52:53] op_sel_hi:[1,0]
	v_add_u32_e32 v50, s11, v155
	v_max_f32_e32 v48, 0, v49
	v_pk_mul_f32 v[44:45], v[44:45], v[52:53] op_sel_hi:[1,0]
	v_max_f32_e32 v49, 0, v42
	v_max_f32_e32 v54, 0, v43
	v_pk_mul_f32 v[42:43], v[46:47], v[46:47]
	v_ashrrev_i32_e32 v51, 31, v50
	v_max_f32_e32 v55, 0, v44
	v_fma_mixlo_f16 v44, v53, v53, 0
	v_cvt_pk_f16_f32 v43, v42, v43
	v_lshlrev_b64 v[50:51], 13, v[50:51]
	v_max_f32_e32 v56, 0, v45
	v_pack_b32_f16 v42, v44, v43
	v_pk_mul_f32 v[44:45], v[48:49], v[48:49]
	v_lshl_add_u64 v[50:51], s[0:1], 0, v[50:51]
	v_cvt_pk_f16_f32 v46, v44, v45
	v_pk_mul_f32 v[44:45], v[54:55], v[54:55]
	v_lshl_add_u64 v[50:51], v[50:51], 0, s[18:19]
	v_cvt_pk_f16_f32 v45, v44, v45
	v_lshl_add_u64 v[50:51], v[50:51], 0, s[92:93]
	v_alignbit_b32 v44, v45, v46, 16
	v_lshrrev_b32_e32 v45, 16, v45
	v_lshl_add_u64 v[50:51], v[50:51], 0, v[0:1]
	v_alignbit_b32 v43, v46, v43, 16
	v_fma_mixhi_f16 v45, v56, v56, 0
	v_pk_mul_f32 v[40:41], v[40:41], v[52:53] op_sel_hi:[1,0]
	v_pk_mul_f32 v[38:39], v[38:39], v[52:53] op_sel_hi:[1,0]
	global_store_dwordx4 v[50:51], v[42:45], off nt
	v_pk_mul_f32 v[34:35], v[34:35], v[52:53] op_sel_hi:[1,0]
	v_pk_mul_f32 v[36:37], v[36:37], v[52:53] op_sel_hi:[1,0]
	v_max_f32_e32 v44, 0, v38
	v_max_f32_e32 v38, 0, v39
	v_max_f32_e32 v39, 0, v40
	v_max_f32_e32 v40, 0, v41
	v_max_f32_e32 v41, 0, v34
	v_max_f32_e32 v42, 0, v35
	v_pk_mul_f32 v[34:35], v[38:39], v[38:39]
	v_max_f32_e32 v43, 0, v36
	v_fma_mixlo_f16 v36, v44, v44, 0
	v_cvt_pk_f16_f32 v35, v34, v35
	v_max_f32_e32 v45, 0, v37
	v_pack_b32_f16 v34, v36, v35
	v_pk_mul_f32 v[36:37], v[40:41], v[40:41]
	s_nop 0
	v_cvt_pk_f16_f32 v38, v36, v37
	v_pk_mul_f32 v[36:37], v[42:43], v[42:43]
	v_alignbit_b32 v35, v38, v35, 16
	v_cvt_pk_f16_f32 v37, v36, v37
	v_alignbit_b32 v36, v37, v38, 16
	v_lshrrev_b32_e32 v37, 16, v37
	v_fma_mixhi_f16 v37, v45, v45, 0
	global_store_dwordx4 v[50:51], v[34:37], off offset:256 nt
	ds_read2_b32 v[34:35], v159 offset0:160 offset1:176
	s_waitcnt lgkmcnt(0)
; #define G8_WAIT_V(n) asm volatile("s_waitcnt vmcnt(" #n ")" ::: "memory")
; #define G8_BAR __builtin_amdgcn_s_barrier()
; template <class Epi>
; __device__ __forceinline__ void gemm_phase(LAS unsigned char* lds, const h16* A, const h16* Bt, int K, const Order& S, const Epi& E) {
;     ...
;     if (!has_next) break;
; #pragma unroll
;     for (int a = 0; a < 2; ++a)
; #pragma unroll
;       for (int b = 0; b < 2; ++b)
; #pragma unroll
;         for (int m = 0; m < 4; ++m)
; #pragma unroll
;           for (int n = 0; n < 2; ++n) acc[a][b][m][n] = (f32x4){0.f, 0.f, 0.f, 0.f};
;     cur = nxt; cA = nA; cB = nB; ++ui;
;   }
;   G8_WAIT_V(0);
;   if (wr == 0) G8_BAR;
;   __device__ __forceinline__ void operator()(const f32x4 (&acc)[2][2][4][2], const g8::Unit& u, int ui, int wr, int wc, int fr, int fq) const {
; #pragma unroll
;     for (int ai = 0; ai < 2; ++ai)
; #pragma unroll
;       for (int m = 0; m < 4; ++m) {
;         const int rl = 128 * ai + 64 * wr + 16 * m + fr;
;         const float r = rsl[ui * 256 + rl];
;         h16* rowp = hid + (size_t)(u.pm * 256 + rl) * DFF + 256 * u.pn + 32 * wc + 8 * fq;
; #pragma unroll
;         for (int bj = 0; bj < 2; ++bj) {
;           f32x4 v[2];
; #pragma unroll
;           for (int n = 0; n < 2; ++n) {
;             v[n] = acc[ai][bj][m][n] * r;
; #pragma unroll
;             for (int j = 0; j < 4; ++j) { const float t = fmaxf(v[n][j], 0.f); v[n][j] = t * t; }
;           }
;           __builtin_nontemporal_store(pack8(v[0], v[1]), (h16x8*)(rowp + 128 * bj));
;         }
;       }
;   }
	v_pk_mul_f32 v[32:33], v[32:33], v[34:35] op_sel_hi:[1,0]
	v_pk_mul_f32 v[30:31], v[30:31], v[34:35] op_sel_hi:[1,0]
	v_pk_mul_f32 v[26:27], v[26:27], v[34:35] op_sel_hi:[1,0]
	v_max_f32_e32 v40, 0, v30
	v_max_f32_e32 v30, 0, v31
	v_max_f32_e32 v31, 0, v32
	v_add_u32_e32 v36, s11, v156
	v_max_f32_e32 v32, 0, v33
	v_pk_mul_f32 v[28:29], v[28:29], v[34:35] op_sel_hi:[1,0]
	v_max_f32_e32 v33, 0, v26
	v_max_f32_e32 v38, 0, v27
	v_pk_mul_f32 v[26:27], v[30:31], v[30:31]
	v_ashrrev_i32_e32 v37, 31, v36
	v_max_f32_e32 v39, 0, v28
	v_fma_mixlo_f16 v28, v40, v40, 0
	v_cvt_pk_f16_f32 v27, v26, v27
	v_lshlrev_b64 v[36:37], 13, v[36:37]
	v_max_f32_e32 v41, 0, v29
	v_pack_b32_f16 v26, v28, v27
	v_pk_mul_f32 v[28:29], v[32:33], v[32:33]
	v_lshl_add_u64 v[36:37], s[0:1], 0, v[36:37]
	v_cvt_pk_f16_f32 v30, v28, v29
	v_pk_mul_f32 v[28:29], v[38:39], v[38:39]
	v_lshl_add_u64 v[36:37], v[36:37], 0, s[18:19]
	v_cvt_pk_f16_f32 v29, v28, v29
	v_lshl_add_u64 v[36:37], v[36:37], 0, s[92:93]
	v_alignbit_b32 v28, v29, v30, 16
	v_lshrrev_b32_e32 v29, 16, v29
	v_lshl_add_u64 v[36:37], v[36:37], 0, v[0:1]
	v_alignbit_b32 v27, v30, v27, 16
	v_fma_mixhi_f16 v29, v41, v41, 0
	v_pk_mul_f32 v[24:25], v[24:25], v[34:35] op_sel_hi:[1,0]
	v_pk_mul_f32 v[22:23], v[22:23], v[34:35] op_sel_hi:[1,0]
	global_store_dwordx4 v[36:37], v[26:29], off nt
	v_pk_mul_f32 v[18:19], v[18:19], v[34:35] op_sel_hi:[1,0]
	v_pk_mul_f32 v[20:21], v[20:21], v[34:35] op_sel_hi:[1,0]
	v_max_f32_e32 v28, 0, v22
	v_max_f32_e32 v22, 0, v23
	v_max_f32_e32 v23, 0, v24
	v_max_f32_e32 v24, 0, v25
	v_max_f32_e32 v25, 0, v18
	v_max_f32_e32 v26, 0, v19
	v_pk_mul_f32 v[18:19], v[22:23], v[22:23]
	v_max_f32_e32 v27, 0, v20
	v_fma_mixlo_f16 v20, v28, v28, 0
	v_cvt_pk_f16_f32 v19, v18, v19
	v_max_f32_e32 v29, 0, v21
	v_pack_b32_f16 v18, v20, v19
	v_pk_mul_f32 v[20:21], v[24:25], v[24:25]
	s_nop 0
	v_cvt_pk_f16_f32 v22, v20, v21
	v_pk_mul_f32 v[20:21], v[26:27], v[26:27]
	v_alignbit_b32 v19, v22, v19, 16
	v_cvt_pk_f16_f32 v21, v20, v21
	v_alignbit_b32 v20, v21, v22, 16
	v_lshrrev_b32_e32 v21, 16, v21
	v_fma_mixhi_f16 v21, v29, v29, 0
	global_store_dwordx4 v[36:37], v[18:21], off offset:256 nt
	s_nop 1
	v_mov_b32_e32 v20, v35
	v_pk_mul_f32 v[14:15], v[14:15], v[20:21] op_sel_hi:[1,0]
	v_pk_mul_f32 v[16:17], v[16:17], v[20:21] op_sel_hi:[1,0]
	v_max_f32_e32 v21, 0, v14
	v_max_f32_e32 v14, 0, v15
	v_max_f32_e32 v15, 0, v16
	v_pk_mul_f32 v[10:11], v[10:11], v[20:21] op_sel_hi:[1,0]
	v_add_u32_e32 v18, s11, v157
	v_max_f32_e32 v16, 0, v17
	v_pk_mul_f32 v[12:13], v[12:13], v[20:21] op_sel_hi:[1,0]
	v_max_f32_e32 v17, 0, v10
	v_max_f32_e32 v22, 0, v11
	v_pk_mul_f32 v[10:11], v[14:15], v[14:15]
	v_ashrrev_i32_e32 v19, 31, v18
	v_max_f32_e32 v23, 0, v12
	v_fma_mixlo_f16 v12, v21, v21, 0
	v_cvt_pk_f16_f32 v11, v10, v11
	v_lshlrev_b64 v[18:19], 13, v[18:19]
	v_max_f32_e32 v24, 0, v13
	v_pack_b32_f16 v10, v12, v11
	v_pk_mul_f32 v[12:13], v[16:17], v[16:17]
	v_lshl_add_u64 v[18:19], s[0:1], 0, v[18:19]
	v_cvt_pk_f16_f32 v14, v12, v13
	v_pk_mul_f32 v[12:13], v[22:23], v[22:23]
	v_lshl_add_u64 v[18:19], v[18:19], 0, s[18:19]
	v_cvt_pk_f16_f32 v13, v12, v13
	v_lshl_add_u64 v[18:19], v[18:19], 0, s[92:93]
	v_alignbit_b32 v12, v13, v14, 16
	v_lshrrev_b32_e32 v13, 16, v13
	v_lshl_add_u64 v[18:19], v[18:19], 0, v[0:1]
	v_alignbit_b32 v11, v14, v11, 16
	v_fma_mixhi_f16 v13, v24, v24, 0
	v_pk_mul_f32 v[8:9], v[8:9], v[20:21] op_sel_hi:[1,0]
	v_pk_mul_f32 v[6:7], v[6:7], v[20:21] op_sel_hi:[1,0]
	global_store_dwordx4 v[18:19], v[10:13], off nt
	v_pk_mul_f32 v[2:3], v[2:3], v[20:21] op_sel_hi:[1,0]
	v_pk_mul_f32 v[4:5], v[4:5], v[20:21] op_sel_hi:[1,0]
	v_max_f32_e32 v12, 0, v6
	v_max_f32_e32 v6, 0, v7
	v_max_f32_e32 v7, 0, v8
	v_max_f32_e32 v8, 0, v9
	v_max_f32_e32 v9, 0, v2
	v_max_f32_e32 v10, 0, v3
	v_pk_mul_f32 v[2:3], v[6:7], v[6:7]
	v_max_f32_e32 v11, 0, v4
	v_fma_mixlo_f16 v4, v12, v12, 0
	v_cvt_pk_f16_f32 v3, v2, v3
	v_max_f32_e32 v13, 0, v5
	v_pack_b32_f16 v2, v4, v3
	v_pk_mul_f32 v[4:5], v[8:9], v[8:9]
	s_mov_b64 s[18:19], s[14:15]
	v_cvt_pk_f16_f32 v6, v4, v5
	v_pk_mul_f32 v[4:5], v[10:11], v[10:11]
	v_alignbit_b32 v3, v6, v3, 16
	v_cvt_pk_f16_f32 v5, v4, v5
	v_alignbit_b32 v4, v5, v6, 16
	v_lshrrev_b32_e32 v5, 16, v5
	v_fma_mixhi_f16 v5, v13, v13, 0
	global_store_dwordx4 v[18:19], v[2:5], off offset:256 nt
	s_cbranch_vccz .LBB0_2466
	s_waitcnt vmcnt(0)
	s_cmpk_gt_u32 s2, 0xff
	s_cbranch_scc1 .LBB0_2477
	s_barrier

; #define G8_STAGE(bufoff, gbase) do { _Pragma("unroll") for (int _i = 0; _i < 2; ++_i) \
;     __builtin_amdgcn_global_load_lds((const unsigned*)((const char*)(gbase) + voffA[_i]), (LAS unsigned*)(lds + (bufoff) + ldsw + _i * 8192), 16, 0, 0); } while (0)
; #define G8_LDA(dst, b, h) do { _Pragma("unroll") for (int m = 0; m < 4; ++m) _Pragma("unroll") for (int k = 0; k < 2; ++k) dst[m][k] = *(const LAS h16x8*)(lds + G8_SA(b, h) + aoff + m * 2048 + k * 1024); } while (0)
; #define G8_LDB(dst, b, h) do { _Pragma("unroll") for (int n = 0; n < 2; ++n) _Pragma("unroll") for (int k = 0; k < 2; ++k) dst[n][k] = *(const LAS h16x8*)(lds + G8_SB(b, h) + boff + n * 2048 + k * 1024); } while (0)
; #define G8_MMA(ai, bj, At, Bt_) do { __builtin_amdgcn_s_setprio(1); _Pragma("unroll") for (int m = 0; m < 4; ++m) _Pragma("unroll") for (int n = 0; n < 2; ++n) _Pragma("unroll") for (int k = 0; k < 2; ++k) \
;     acc[ai][bj][m][n] = __builtin_amdgcn_mfma_f32_16x16x32_f16(Bt_[n][k], At[m][k], acc[ai][bj][m][n], 0, 0, 0); __builtin_amdgcn_s_setprio(0); } while (0)
; #define G8_WAIT_V(n) asm volatile("s_waitcnt vmcnt(" #n ")" ::: "memory")
; #define G8_WAIT_L(n) asm volatile("s_waitcnt lgkmcnt(" #n ")" ::: "memory")
; #define G8_BAR __builtin_amdgcn_s_barrier()
; template <class Epi>
; __device__ __forceinline__ void gemm_phase(LAS unsigned char* lds, const h16* A, const h16* Bt, int K, const Order& S, const Epi& E) {
;     ...
;     for (int t = 0; t < nt; t += 2) {
;       const bool last = (t == nt - 2);
;       const char* a1 = cA + (size_t)(t + 1) * kstep;
;       const char* a2 = last ? nA : cA + (size_t)(t + 2) * kstep;
;       const char* b2 = last ? nB : cB + (size_t)(t + 2) * kstep;
;       const char* a3 = a2 + kstep;
;       const char* b3 = b2 + kstep;
;       if (Epi::MID_T >= 0 && t == Epi::MID_T) E.mid(acc, ui, wr, fr);
;       G8_LDB(B0, 0, 0); G8_SCHED; G8_LDA(At, 0, 0); G8_STAGE(G8_SA(1, 1), a1 + hstep);
;       G8_WAIT_L(8); G8_BAR; G8_WAIT_L(0); G8_MMA(0, 0, At, B0); G8_BAR; G8_SCHED;
;       G8_LDB(B1, 0, 1); G8_STAGE(G8_SB(0, 0), b2);
;       G8_BAR; G8_WAIT_L(0); G8_MMA(0, 1, At, B1); G8_BAR;
;       G8_LDA(At, 0, 1); G8_STAGE(G8_SA(0, 0), a2);
;       G8_BAR; G8_WAIT_L(0); G8_MMA(1, 0, At, B0); G8_BAR; G8_SCHED;
;       G8_STAGE(G8_SB(0, 1), b2 + hstep);
;       G8_WAIT_V(6); G8_BAR; G8_MMA(1, 1, At, B1); G8_BAR;
.LBB0_2542:
	s_add_u32 s24, s22, 0xfff00080
	s_addc_u32 s25, s23, -1
	s_cmp_eq_u32 s53, 60
	s_cselect_b32 s27, s3, s25
	s_cselect_b32 s26, s9, s24
	s_cselect_b32 s25, s15, s52
	s_cselect_b32 s24, s17, s51
	v_lshl_add_u64 v[140:141], s[22:23], 0, v[136:137]
	s_add_i32 m0, s35, 0xc000
	ds_read_b128 v[172:175], v135
	ds_read_b128 v[176:179], v135 offset:1024
	ds_read_b128 v[180:183], v135 offset:2048
	ds_read_b128 v[184:187], v135 offset:3072
	ds_read_b128 v[202:205], v135 offset:4096
	ds_read_b128 v[206:209], v135 offset:5120
	ds_read_b128 v[210:213], v135 offset:6144
	ds_read_b128 v[214:217], v135 offset:7168
	global_load_lds_dwordx4 v[140:141], off
	s_add_i32 m0, s35, 0xe000
	v_lshl_add_u64 v[140:141], s[22:23], 0, v[138:139]
	global_load_lds_dwordx4 v[140:141], off
	s_waitcnt lgkmcnt(8)
	s_barrier
	s_waitcnt lgkmcnt(0)
	v_mfma_f32_16x16x32_f16 v[126:129], v[152:155], v[172:175], v[126:129]
	v_mfma_f32_16x16x32_f16 v[122:125], v[164:167], v[172:175], v[122:125]
	v_mfma_f32_16x16x32_f16 v[110:113], v[152:155], v[180:183], v[110:113]
	v_mfma_f32_16x16x32_f16 v[106:109], v[164:167], v[180:183], v[106:109]
	v_mfma_f32_16x16x32_f16 v[94:97], v[152:155], v[202:205], v[94:97]
	v_mfma_f32_16x16x32_f16 v[90:93], v[164:167], v[202:205], v[90:93]
	v_mfma_f32_16x16x32_f16 v[78:81], v[152:155], v[210:213], v[78:81]
	v_mfma_f32_16x16x32_f16 v[74:77], v[164:167], v[210:213], v[74:77]
	v_mfma_f32_16x16x32_f16 v[126:129], v[160:163], v[176:179], v[126:129]
	v_mfma_f32_16x16x32_f16 v[122:125], v[168:171], v[176:179], v[122:125]
	v_mfma_f32_16x16x32_f16 v[110:113], v[160:163], v[184:187], v[110:113]
	v_mfma_f32_16x16x32_f16 v[106:109], v[168:171], v[184:187], v[106:109]
	v_mfma_f32_16x16x32_f16 v[94:97], v[160:163], v[206:209], v[94:97]
	v_mfma_f32_16x16x32_f16 v[90:93], v[168:171], v[206:209], v[90:93]
	v_mfma_f32_16x16x32_f16 v[78:81], v[160:163], v[214:217], v[78:81]
	v_mfma_f32_16x16x32_f16 v[74:77], v[168:171], v[214:217], v[74:77]
	s_barrier
	v_or_b32_e32 v140, 0x14000, v158
	v_add_u32_e32 v141, 0x14400, v158
	ds_read_b128 v[218:221], v140
	ds_read_b128 v[222:225], v141
	v_add_u32_e32 v140, 0x14800, v158
	v_add_u32_e32 v141, 0x14c00, v158
	s_mov_b32 m0, s36
	ds_read_b128 v[226:229], v140
	ds_read_b128 v[230:233], v141
	v_lshl_add_u64 v[140:141], s[24:25], 0, v[0:1]
	global_load_lds_dwordx4 v[140:141], off
	s_mov_b32 m0, s37
	v_lshl_add_u64 v[156:157], s[24:25], 0, v[130:131]
	global_load_lds_dwordx4 v[156:157], off
	s_barrier
	s_waitcnt lgkmcnt(0)
	v_mfma_f32_16x16x32_f16 v[118:121], v[218:221], v[172:175], v[118:121]
	v_mfma_f32_16x16x32_f16 v[114:117], v[226:229], v[172:175], v[114:117]
	v_mfma_f32_16x16x32_f16 v[102:105], v[218:221], v[180:183], v[102:105]
	v_mfma_f32_16x16x32_f16 v[98:101], v[226:229], v[180:183], v[98:101]
	v_mfma_f32_16x16x32_f16 v[86:89], v[218:221], v[202:205], v[86:89]
	v_mfma_f32_16x16x32_f16 v[82:85], v[226:229], v[202:205], v[82:85]
	v_mfma_f32_16x16x32_f16 v[70:73], v[218:221], v[210:213], v[70:73]
	v_mfma_f32_16x16x32_f16 v[66:69], v[226:229], v[210:213], v[66:69]
	v_mfma_f32_16x16x32_f16 v[118:121], v[222:225], v[176:179], v[118:121]
	v_mfma_f32_16x16x32_f16 v[114:117], v[230:233], v[176:179], v[114:117]
	v_mfma_f32_16x16x32_f16 v[102:105], v[222:225], v[184:187], v[102:105]
	v_mfma_f32_16x16x32_f16 v[98:101], v[230:233], v[184:187], v[98:101]
	v_mfma_f32_16x16x32_f16 v[86:89], v[222:225], v[206:209], v[86:89]
	v_mfma_f32_16x16x32_f16 v[82:85], v[230:233], v[206:209], v[82:85]
	v_mfma_f32_16x16x32_f16 v[70:73], v[222:225], v[214:217], v[70:73]
	v_mfma_f32_16x16x32_f16 v[66:69], v[230:233], v[214:217], v[66:69]
	s_mov_b32 m0, s35
	v_lshl_add_u64 v[188:189], s[26:27], 0, v[0:1]
	s_barrier
	ds_read_b128 v[172:175], v135 offset:16384
	ds_read_b128 v[176:179], v135 offset:17408
	ds_read_b128 v[180:183], v135 offset:18432
	ds_read_b128 v[184:187], v135 offset:19456
	ds_read_b128 v[202:205], v135 offset:20480
	ds_read_b128 v[206:209], v135 offset:21504
	ds_read_b128 v[210:213], v135 offset:22528
	ds_read_b128 v[214:217], v135 offset:23552
	global_load_lds_dwordx4 v[188:189], off
	s_mov_b32 m0, s38
	v_lshl_add_u64 v[234:235], s[26:27], 0, v[130:131]
	global_load_lds_dwordx4 v[234:235], off
	s_waitcnt vmcnt(10)
	s_barrier
	s_waitcnt lgkmcnt(0)
	v_mfma_f32_16x16x32_f16 v[62:65], v[152:155], v[172:175], v[62:65]
	v_mfma_f32_16x16x32_f16 v[58:61], v[164:167], v[172:175], v[58:61]
	v_mfma_f32_16x16x32_f16 v[46:49], v[152:155], v[180:183], v[46:49]
	v_mfma_f32_16x16x32_f16 v[42:45], v[164:167], v[180:183], v[42:45]
	v_mfma_f32_16x16x32_f16 v[30:33], v[152:155], v[202:205], v[30:33]
	v_mfma_f32_16x16x32_f16 v[26:29], v[164:167], v[202:205], v[26:29]
	v_mfma_f32_16x16x32_f16 v[14:17], v[152:155], v[210:213], v[14:17]
	v_mfma_f32_16x16x32_f16 v[10:13], v[164:167], v[210:213], v[10:13]
	v_mfma_f32_16x16x32_f16 v[62:65], v[160:163], v[176:179], v[62:65]
	v_mfma_f32_16x16x32_f16 v[58:61], v[168:171], v[176:179], v[58:61]
	v_mfma_f32_16x16x32_f16 v[46:49], v[160:163], v[184:187], v[46:49]
	v_mfma_f32_16x16x32_f16 v[42:45], v[168:171], v[184:187], v[42:45]
	v_mfma_f32_16x16x32_f16 v[30:33], v[160:163], v[206:209], v[30:33]
	v_mfma_f32_16x16x32_f16 v[26:29], v[168:171], v[206:209], v[26:29]
	v_mfma_f32_16x16x32_f16 v[14:17], v[160:163], v[214:217], v[14:17]
	v_mfma_f32_16x16x32_f16 v[10:13], v[168:171], v[214:217], v[10:13]
	s_barrier
	s_add_u32 s54, s24, 0x100000
	s_addc_u32 s55, s25, 0
	s_mov_b32 m0, s39
	v_lshl_add_u64 v[152:153], s[54:55], 0, v[0:1]
	global_load_lds_dwordx4 v[152:153], off
	s_mov_b32 m0, s40
	v_lshl_add_u64 v[152:153], s[54:55], 0, v[130:131]
	global_load_lds_dwordx4 v[152:153], off
	v_or_b32_e32 v152, 0x18000, v158
	v_add_u32_e32 v159, 0x18400, v158
	ds_read_b128 v[152:155], v152
	ds_read_b128 v[160:163], v159
	v_add_u32_e32 v159, 0x18800, v158
	v_add_u32_e32 v168, 0x18c00, v158
	ds_read_b128 v[164:167], v159
	ds_read_b128 v[168:171], v168
	s_waitcnt vmcnt(6)
	s_barrier
; #define G8_STAGE(bufoff, gbase) do { _Pragma("unroll") for (int _i = 0; _i < 2; ++_i) \
;     __builtin_amdgcn_global_load_lds((const unsigned*)((const char*)(gbase) + voffA[_i]), (LAS unsigned*)(lds + (bufoff) + ldsw + _i * 8192), 16, 0, 0); } while (0)
; #define G8_LDA(dst, b, h) do { _Pragma("unroll") for (int m = 0; m < 4; ++m) _Pragma("unroll") for (int k = 0; k < 2; ++k) dst[m][k] = *(const LAS h16x8*)(lds + G8_SA(b, h) + aoff + m * 2048 + k * 1024); } while (0)
; #define G8_LDB(dst, b, h) do { _Pragma("unroll") for (int n = 0; n < 2; ++n) _Pragma("unroll") for (int k = 0; k < 2; ++k) dst[n][k] = *(const LAS h16x8*)(lds + G8_SB(b, h) + boff + n * 2048 + k * 1024); } while (0)
; #define G8_MMA(ai, bj, At, Bt_) do { __builtin_amdgcn_s_setprio(1); _Pragma("unroll") for (int m = 0; m < 4; ++m) _Pragma("unroll") for (int n = 0; n < 2; ++n) _Pragma("unroll") for (int k = 0; k < 2; ++k) \
;     acc[ai][bj][m][n] = __builtin_amdgcn_mfma_f32_16x16x32_f16(Bt_[n][k], At[m][k], acc[ai][bj][m][n], 0, 0, 0); __builtin_amdgcn_s_setprio(0); } while (0)
; #define G8_WAIT_V(n) asm volatile("s_waitcnt vmcnt(" #n ")" ::: "memory")
; #define G8_WAIT_L(n) asm volatile("s_waitcnt lgkmcnt(" #n ")" ::: "memory")
; #define G8_BAR __builtin_amdgcn_s_barrier()
; #define G8_SCHED __builtin_amdgcn_sched_barrier(0)
; template <class Epi>
; __device__ __forceinline__ void gemm_phase(LAS unsigned char* lds, const h16* A, const h16* Bt, int K, const Order& S, const Epi& E) {
;     ...
;       G8_WAIT_V(6); G8_BAR; G8_MMA(1, 1, At, B1); G8_BAR;
;       G8_LDB(B0, 1, 0); G8_SCHED; G8_LDA(At, 1, 0); G8_STAGE(G8_SA(0, 1), a2 + hstep);
;       G8_WAIT_L(8); G8_BAR; G8_WAIT_L(0); G8_MMA(0, 0, At, B0); G8_BAR; G8_SCHED;
;       G8_LDB(B1, 1, 1); G8_STAGE(G8_SB(1, 0), b3);
;       G8_BAR; G8_WAIT_L(0); G8_MMA(0, 1, At, B1); G8_BAR;
;       G8_LDA(At, 1, 1); G8_STAGE(G8_SA(1, 0), a3);
	v_mfma_f32_16x16x32_f16 v[54:57], v[218:221], v[172:175], v[54:57]
	v_mfma_f32_16x16x32_f16 v[50:53], v[226:229], v[172:175], v[50:53]
	v_mfma_f32_16x16x32_f16 v[38:41], v[218:221], v[180:183], v[38:41]
	v_mfma_f32_16x16x32_f16 v[34:37], v[226:229], v[180:183], v[34:37]
	v_mfma_f32_16x16x32_f16 v[22:25], v[218:221], v[202:205], v[22:25]
	v_mfma_f32_16x16x32_f16 v[18:21], v[226:229], v[202:205], v[18:21]
	v_mfma_f32_16x16x32_f16 v[6:9], v[218:221], v[210:213], v[6:9]
	v_mfma_f32_16x16x32_f16 v[2:5], v[226:229], v[210:213], v[2:5]
	v_mfma_f32_16x16x32_f16 v[54:57], v[222:225], v[176:179], v[54:57]
	v_mfma_f32_16x16x32_f16 v[50:53], v[230:233], v[176:179], v[50:53]
	v_mfma_f32_16x16x32_f16 v[38:41], v[222:225], v[184:187], v[38:41]
	v_mfma_f32_16x16x32_f16 v[34:37], v[230:233], v[184:187], v[34:37]
	v_mfma_f32_16x16x32_f16 v[22:25], v[222:225], v[206:209], v[22:25]
	v_mfma_f32_16x16x32_f16 v[18:21], v[230:233], v[206:209], v[18:21]
	v_mfma_f32_16x16x32_f16 v[6:9], v[222:225], v[214:217], v[6:9]
	v_mfma_f32_16x16x32_f16 v[2:5], v[230:233], v[214:217], v[2:5]
	s_barrier
	s_add_u32 s26, s26, 0x100000
	s_addc_u32 s27, s27, 0
	s_mov_b32 m0, s41
	v_lshl_add_u64 v[218:219], s[26:27], 0, v[0:1]
	ds_read_b128 v[172:175], v135 offset:32768
	ds_read_b128 v[176:179], v135 offset:33792
	ds_read_b128 v[180:183], v135 offset:34816
	ds_read_b128 v[184:187], v135 offset:35840
	ds_read_b128 v[202:205], v135 offset:36864
	ds_read_b128 v[206:209], v135 offset:37888
	ds_read_b128 v[210:213], v135 offset:38912
	ds_read_b128 v[214:217], v135 offset:39936
	global_load_lds_dwordx4 v[218:219], off
	s_mov_b32 m0, s42
	v_lshl_add_u64 v[218:219], s[26:27], 0, v[130:131]
	global_load_lds_dwordx4 v[218:219], off
	s_waitcnt lgkmcnt(8)
	s_barrier
	s_waitcnt lgkmcnt(0)
	v_mfma_f32_16x16x32_f16 v[126:129], v[152:155], v[172:175], v[126:129]
	v_mfma_f32_16x16x32_f16 v[122:125], v[164:167], v[172:175], v[122:125]
	v_mfma_f32_16x16x32_f16 v[110:113], v[152:155], v[180:183], v[110:113]
	v_mfma_f32_16x16x32_f16 v[106:109], v[164:167], v[180:183], v[106:109]
	v_mfma_f32_16x16x32_f16 v[94:97], v[152:155], v[202:205], v[94:97]
	v_mfma_f32_16x16x32_f16 v[90:93], v[164:167], v[202:205], v[90:93]
	v_mfma_f32_16x16x32_f16 v[78:81], v[152:155], v[210:213], v[78:81]
	v_mfma_f32_16x16x32_f16 v[74:77], v[164:167], v[210:213], v[74:77]
	v_mfma_f32_16x16x32_f16 v[126:129], v[160:163], v[176:179], v[126:129]
	v_mfma_f32_16x16x32_f16 v[122:125], v[168:171], v[176:179], v[122:125]
	v_mfma_f32_16x16x32_f16 v[110:113], v[160:163], v[184:187], v[110:113]
	v_mfma_f32_16x16x32_f16 v[106:109], v[168:171], v[184:187], v[106:109]
	v_mfma_f32_16x16x32_f16 v[94:97], v[160:163], v[206:209], v[94:97]
	v_mfma_f32_16x16x32_f16 v[90:93], v[168:171], v[206:209], v[90:93]
	v_mfma_f32_16x16x32_f16 v[78:81], v[160:163], v[214:217], v[78:81]
	v_mfma_f32_16x16x32_f16 v[74:77], v[168:171], v[214:217], v[74:77]
	s_barrier
	v_or_b32_e32 v159, 0x1c000, v158
	s_mov_b32 m0, s44
	v_add_u32_e32 v195, 0x1c400, v158
	ds_read_b128 v[218:221], v159
	ds_read_b128 v[222:225], v195
	v_add_u32_e32 v159, 0x1c800, v158
	v_lshl_add_u64 v[140:141], v[140:141], 0, s[94:95]
	v_add_u32_e32 v195, 0x1cc00, v158
	ds_read_b128 v[226:229], v159
	ds_read_b128 v[230:233], v195
	global_load_lds_dwordx4 v[140:141], off
	s_mov_b32 m0, s45
	v_lshl_add_u64 v[140:141], v[156:157], 0, s[94:95]
	global_load_lds_dwordx4 v[140:141], off
	s_barrier
	s_waitcnt lgkmcnt(0)
	v_mfma_f32_16x16x32_f16 v[118:121], v[218:221], v[172:175], v[118:121]
	v_mfma_f32_16x16x32_f16 v[114:117], v[226:229], v[172:175], v[114:117]
	v_mfma_f32_16x16x32_f16 v[102:105], v[218:221], v[180:183], v[102:105]
	v_mfma_f32_16x16x32_f16 v[98:101], v[226:229], v[180:183], v[98:101]
	v_mfma_f32_16x16x32_f16 v[86:89], v[218:221], v[202:205], v[86:89]
	v_mfma_f32_16x16x32_f16 v[82:85], v[226:229], v[202:205], v[82:85]
	v_mfma_f32_16x16x32_f16 v[70:73], v[218:221], v[210:213], v[70:73]
	v_mfma_f32_16x16x32_f16 v[66:69], v[226:229], v[210:213], v[66:69]
	v_mfma_f32_16x16x32_f16 v[118:121], v[222:225], v[176:179], v[118:121]
	v_mfma_f32_16x16x32_f16 v[114:117], v[230:233], v[176:179], v[114:117]
	v_mfma_f32_16x16x32_f16 v[102:105], v[222:225], v[184:187], v[102:105]
	v_mfma_f32_16x16x32_f16 v[98:101], v[230:233], v[184:187], v[98:101]
	v_mfma_f32_16x16x32_f16 v[86:89], v[222:225], v[206:209], v[86:89]
	v_mfma_f32_16x16x32_f16 v[82:85], v[230:233], v[206:209], v[82:85]
	v_mfma_f32_16x16x32_f16 v[70:73], v[222:225], v[214:217], v[70:73]
	v_mfma_f32_16x16x32_f16 v[66:69], v[230:233], v[214:217], v[66:69]
	s_mov_b32 m0, s46
	v_lshl_add_u64 v[140:141], v[188:189], 0, s[94:95]
	s_barrier
	ds_read_b128 v[172:175], v135 offset:49152
	ds_read_b128 v[176:179], v135 offset:50176
	ds_read_b128 v[180:183], v135 offset:51200
	ds_read_b128 v[184:187], v135 offset:52224
	ds_read_b128 v[202:205], v135 offset:53248
	ds_read_b128 v[206:209], v135 offset:54272
	ds_read_b128 v[210:213], v135 offset:55296
	ds_read_b128 v[214:217], v135 offset:56320
	global_load_lds_dwordx4 v[140:141], off
	s_mov_b32 m0, s47
	v_lshl_add_u64 v[140:141], v[234:235], 0, s[94:95]
	global_load_lds_dwordx4 v[140:141], off
	s_waitcnt vmcnt(10)
	s_barrier
; #define G8_STAGE(bufoff, gbase) do { _Pragma("unroll") for (int _i = 0; _i < 2; ++_i) \
;     __builtin_amdgcn_global_load_lds((const unsigned*)((const char*)(gbase) + voffA[_i]), (LAS unsigned*)(lds + (bufoff) + ldsw + _i * 8192), 16, 0, 0); } while (0)
; #define G8_MMA(ai, bj, At, Bt_) do { __builtin_amdgcn_s_setprio(1); _Pragma("unroll") for (int m = 0; m < 4; ++m) _Pragma("unroll") for (int n = 0; n < 2; ++n) _Pragma("unroll") for (int k = 0; k < 2; ++k) \
;     acc[ai][bj][m][n] = __builtin_amdgcn_mfma_f32_16x16x32_f16(Bt_[n][k], At[m][k], acc[ai][bj][m][n], 0, 0, 0); __builtin_amdgcn_s_setprio(0); } while (0)
; #define G8_WAIT_V(n) asm volatile("s_waitcnt vmcnt(" #n ")" ::: "memory")
; #define G8_WAIT_L(n) asm volatile("s_waitcnt lgkmcnt(" #n ")" ::: "memory")
; #define G8_BAR __builtin_amdgcn_s_barrier()
; #define G8_SCHED __builtin_amdgcn_sched_barrier(0)
; template <class Epi>
; __device__ __forceinline__ void gemm_phase(LAS unsigned char* lds, const h16* A, const h16* Bt, int K, const Order& S, const Epi& E) {
;     ...
;       G8_BAR; G8_WAIT_L(0); G8_MMA(1, 0, At, B0); G8_BAR; G8_SCHED;
;       G8_STAGE(G8_SB(1, 1), b3 + hstep);
;       G8_WAIT_V(6); G8_BAR; G8_MMA(1, 1, At, B1); G8_BAR;
;   __device__ __forceinline__ void operator()(const f32x4 (&acc)[2][2][4][2], const g8::Unit& u, int ui, int wr, int wc, int fr, int fq) const {
; #pragma unroll
;     for (int ai = 0; ai < 2; ++ai)
; #pragma unroll
;       for (int m = 0; m < 4; ++m) {
;         const size_t row = (size_t)u.pm * 256 + 128 * ai + 64 * wr + 16 * m + fr;
;         const size_t base = row * DM + 256 * u.pn + 32 * wc + 8 * fq;
;         float ss = 0.f;
; #pragma unroll
;         for (int bj = 0; bj < 2; ++bj) {
;           const size_t idx = base + 128 * bj;
;           const h16x8 xv = *(const h16x8*)(xb + idx);
;           f32x4 x0 = acc[ai][bj][m][0], x1 = acc[ai][bj][m][1];
; #pragma unroll
;           for (int j = 0; j < 4; ++j) { x0[j] += (float)xv[j]; x1[j] += (float)xv[4 + j]; ss += x0[j] * x0[j] + x1[j] * x1[j]; }
;           if (final_out) {
;             __builtin_nontemporal_store(x0, (f32x4*)(xo + idx));
;             __builtin_nontemporal_store(x1, (f32x4*)(xo + idx + 4));
;           } else {
;             *(h16x8*)(xb + idx) = pack8(x0, x1);
;           }
	s_waitcnt lgkmcnt(0)
	v_mfma_f32_16x16x32_f16 v[62:65], v[152:155], v[172:175], v[62:65]
	v_mfma_f32_16x16x32_f16 v[58:61], v[164:167], v[172:175], v[58:61]
	v_mfma_f32_16x16x32_f16 v[46:49], v[152:155], v[180:183], v[46:49]
	v_mfma_f32_16x16x32_f16 v[42:45], v[164:167], v[180:183], v[42:45]
	v_mfma_f32_16x16x32_f16 v[30:33], v[152:155], v[202:205], v[30:33]
	v_mfma_f32_16x16x32_f16 v[26:29], v[164:167], v[202:205], v[26:29]
	v_mfma_f32_16x16x32_f16 v[14:17], v[152:155], v[210:213], v[14:17]
	v_mfma_f32_16x16x32_f16 v[10:13], v[164:167], v[210:213], v[10:13]
	v_mfma_f32_16x16x32_f16 v[62:65], v[160:163], v[176:179], v[62:65]
	v_mfma_f32_16x16x32_f16 v[58:61], v[168:171], v[176:179], v[58:61]
	v_mfma_f32_16x16x32_f16 v[46:49], v[160:163], v[184:187], v[46:49]
	v_mfma_f32_16x16x32_f16 v[42:45], v[168:171], v[184:187], v[42:45]
	v_mfma_f32_16x16x32_f16 v[30:33], v[160:163], v[206:209], v[30:33]
	v_mfma_f32_16x16x32_f16 v[26:29], v[168:171], v[206:209], v[26:29]
	v_mfma_f32_16x16x32_f16 v[14:17], v[160:163], v[214:217], v[14:17]
	v_mfma_f32_16x16x32_f16 v[10:13], v[168:171], v[214:217], v[10:13]
	s_barrier
	s_add_u32 s24, s24, 0x100080
	s_addc_u32 s25, s25, 0
	s_mov_b32 m0, s48
	v_lshl_add_u64 v[140:141], s[24:25], 0, v[0:1]
	global_load_lds_dwordx4 v[140:141], off
	s_mov_b32 m0, s49
	v_lshl_add_u64 v[140:141], s[24:25], 0, v[130:131]
	global_load_lds_dwordx4 v[140:141], off
	v_or_b32_e32 v140, 0x10000, v158
	v_add_u32_e32 v141, 0x10400, v158
	ds_read_b128 v[152:155], v140
	ds_read_b128 v[160:163], v141
	v_add_u32_e32 v140, 0x10800, v158
	v_add_u32_e32 v141, 0x10c00, v158
	ds_read_b128 v[164:167], v140
	ds_read_b128 v[168:171], v141
	s_waitcnt vmcnt(6)
	s_barrier
	v_mfma_f32_16x16x32_f16 v[54:57], v[218:221], v[172:175], v[54:57]
	v_mfma_f32_16x16x32_f16 v[50:53], v[226:229], v[172:175], v[50:53]
	v_mfma_f32_16x16x32_f16 v[38:41], v[218:221], v[180:183], v[38:41]
	v_mfma_f32_16x16x32_f16 v[34:37], v[226:229], v[180:183], v[34:37]
	v_mfma_f32_16x16x32_f16 v[22:25], v[218:221], v[202:205], v[22:25]
	v_mfma_f32_16x16x32_f16 v[18:21], v[226:229], v[202:205], v[18:21]
	v_mfma_f32_16x16x32_f16 v[6:9], v[218:221], v[210:213], v[6:9]
	v_mfma_f32_16x16x32_f16 v[2:5], v[226:229], v[210:213], v[2:5]
	v_mfma_f32_16x16x32_f16 v[54:57], v[222:225], v[176:179], v[54:57]
	v_mfma_f32_16x16x32_f16 v[50:53], v[230:233], v[176:179], v[50:53]
	v_mfma_f32_16x16x32_f16 v[38:41], v[222:225], v[184:187], v[38:41]
	v_mfma_f32_16x16x32_f16 v[34:37], v[230:233], v[184:187], v[34:37]
	v_mfma_f32_16x16x32_f16 v[22:25], v[222:225], v[206:209], v[22:25]
	v_mfma_f32_16x16x32_f16 v[18:21], v[230:233], v[206:209], v[18:21]
	v_mfma_f32_16x16x32_f16 v[6:9], v[222:225], v[214:217], v[6:9]
	v_mfma_f32_16x16x32_f16 v[2:5], v[230:233], v[214:217], v[2:5]
	s_add_i32 s53, s53, 2
	s_add_u32 s22, s22, 0x100
	s_addc_u32 s23, s23, 0
	s_add_u32 s51, s51, 0x100
	s_addc_u32 s52, s52, 0
	s_cmp_gt_u32 s53, 61
	s_barrier
	s_cbranch_scc0 .LBB0_2542
	s_waitcnt lgkmcnt(0)
	s_ashr_i32 s9, s8, 31
	s_lshl_b64 s[8:9], s[8:9], 8
	s_lshl_b32 s3, s2, 8
	v_lshl_add_u64 v[140:141], s[8:9], 0, v[132:133]
	s_ashr_i32 s8, s3, 31
	v_mov_b32_e32 v153, s8
	v_or_b32_e32 v152, s3, v134
	v_lshlrev_b64 v[154:155], 10, v[140:141]
	v_lshl_add_u64 v[156:157], v[154:155], 0, v[152:153]
	v_lshl_add_u64 v[154:155], v[156:157], 1, s[10:11]
	global_load_dwordx4 v[166:169], v[154:155], off
	global_load_dwordx4 v[170:173], v[154:155], off offset:256
	s_mov_b32 s9, 0
	s_mov_b32 s8, 0x8000
	v_lshl_add_u64 v[234:235], v[154:155], 0, s[8:9]
	global_load_dwordx4 v[174:177], v[234:235], off
	global_load_dwordx4 v[178:181], v[234:235], off offset:256
	s_mov_b32 s8, 0x10000
	v_lshl_add_u64 v[234:235], v[154:155], 0, s[8:9]
	global_load_dwordx4 v[182:185], v[234:235], off
	global_load_dwordx4 v[186:189], v[234:235], off offset:256
	s_mov_b32 s8, 0x18000
	v_lshl_add_u64 v[234:235], v[154:155], 0, s[8:9]
	global_load_dwordx4 v[202:205], v[234:235], off
	global_load_dwordx4 v[206:209], v[234:235], off offset:256
	s_mov_b32 s8, 0x40000
	v_lshl_add_u64 v[234:235], v[154:155], 0, s[8:9]
	global_load_dwordx4 v[210:213], v[234:235], off
	global_load_dwordx4 v[214:217], v[234:235], off offset:256
	s_mov_b32 s8, 0x48000
	v_lshl_add_u64 v[234:235], v[154:155], 0, s[8:9]
	global_load_dwordx4 v[218:221], v[234:235], off
	global_load_dwordx4 v[222:225], v[234:235], off offset:256
	s_mov_b32 s8, 0x50000
	v_lshl_add_u64 v[234:235], v[154:155], 0, s[8:9]
	global_load_dwordx4 v[226:229], v[234:235], off
	global_load_dwordx4 v[230:233], v[234:235], off offset:256
	s_mov_b64 s[8:9], -1
	s_and_b64 vcc, exec, s[0:1]
	s_waitcnt vmcnt(13)
	v_cvt_f32_f16_e32 v164, v166
	v_cvt_f32_f16_sdwa v165, v166 dst_sel:DWORD dst_unused:UNUSED_PAD src0_sel:WORD_1
	v_cvt_f32_f16_e32 v160, v167
	v_cvt_f32_f16_sdwa v161, v167 dst_sel:DWORD dst_unused:UNUSED_PAD src0_sel:WORD_1
	v_pk_add_f32 v[126:127], v[126:127], v[164:165]
	v_cvt_f32_f16_e32 v164, v168
	v_cvt_f32_f16_sdwa v165, v168 dst_sel:DWORD dst_unused:UNUSED_PAD src0_sel:WORD_1
	v_pk_add_f32 v[128:129], v[128:129], v[160:161]
	v_cvt_f32_f16_e32 v160, v169
	v_cvt_f32_f16_sdwa v161, v169 dst_sel:DWORD dst_unused:UNUSED_PAD src0_sel:WORD_1
	v_pk_add_f32 v[122:123], v[122:123], v[164:165]
	v_pk_add_f32 v[124:125], v[124:125], v[160:161]
	s_cbranch_vccz .LBB0_2545
	v_cvt_pk_f16_f32 v163, v124, v125
	v_cvt_pk_f16_f32 v162, v122, v123
	v_cvt_pk_f16_f32 v161, v128, v129
	v_cvt_pk_f16_f32 v160, v126, v127
	global_store_dwordx4 v[154:155], v[160:163], off
	s_mov_b64 s[8:9], 0
